# rows: nt also on the Y (bf16 GEMM output) loads
# speedup vs baseline: 1.0277x; 1.0000x over previous
_Z10fwd_kernelILi4ELi5EEv4Args:
	s_load_dword s3, s[0:1], 0xe8
	s_load_dwordx4 s[4:7], s[0:1], 0xd0
	s_load_dwordx2 s[8:9], s[0:1], 0xa8
	s_load_dwordx2 s[10:11], s[0:1], 0xb0
	s_load_dwordx4 s[12:15], s[0:1], 0x0
	s_waitcnt lgkmcnt(0)
	s_cmp_lg_u32 s3, 0x100
	s_cbranch_scc1 .Lrows4_orig
	v_readfirstlane_b32 s16, v0
	s_lshr_b32 s16, s16, 6
	s_lshl_b32 s18, s2, 3
	s_add_u32 s16, s16, s18
	s_mov_b32 s17, 0x3a800000
	v_mov_b32_e32 v3, 0x358637bd
	v_and_b32_e32 v10, 63, v0
	v_lshlrev_b32_e32 v1, 4, v10
	v_lshlrev_b32_e32 v2, 3, v10
	v_xor_b32_e32 v4, 1, v10
	v_xor_b32_e32 v5, 2, v10
	v_xor_b32_e32 v6, 4, v10
	v_xor_b32_e32 v7, 8, v10
	v_xor_b32_e32 v8, 16, v10
	v_xor_b32_e32 v9, 32, v10
	v_lshlrev_b32_e32 v4, 2, v4
	v_lshlrev_b32_e32 v5, 2, v5
	v_lshlrev_b32_e32 v6, 2, v6
	v_lshlrev_b32_e32 v7, 2, v7
	v_lshlrev_b32_e32 v8, 2, v8
	v_lshlrev_b32_e32 v9, 2, v9
	global_load_dwordx4 v[20:23], v1, s[8:9] offset:0
	global_load_dwordx4 v[24:27], v1, s[8:9] offset:1024
	global_load_dwordx4 v[28:31], v1, s[8:9] offset:2048
	global_load_dwordx4 v[32:35], v1, s[8:9] offset:3072
	global_load_dwordx4 v[36:39], v1, s[10:11] offset:0
	global_load_dwordx4 v[40:43], v1, s[10:11] offset:1024
	global_load_dwordx4 v[44:47], v1, s[10:11] offset:2048
	global_load_dwordx4 v[48:51], v1, s[10:11] offset:3072
	s_lshr_b32 s54, s16, 2
	s_and_b32 s55, s16, 3
	s_lshl_b32 s55, s55, 10
	s_lshl_b32 s18, s54, 12
	s_add_u32 s18, s18, s55
	s_add_u32 s56, s6, s18
	s_addc_u32 s57, s7, 0
	s_add_u32 s56, s56, 0x7400000
	s_addc_u32 s57, s57, 0
	global_load_dwordx4 v[208:211], v1, s[56:57]
	s_add_u32 s56, s56, 0x200000
	s_addc_u32 s57, s57, 0
	global_load_dwordx4 v[212:215], v1, s[56:57]
	s_add_u32 s56, s14, s18
	s_addc_u32 s57, s15, 0
	global_load_dwordx4 v[240:243], v1, s[56:57]
	s_add_u32 s56, s8, s55
	s_addc_u32 s57, s9, 0
	global_load_dwordx4 v[244:247], v1, s[56:57]
	s_add_u32 s56, s10, s55
	s_addc_u32 s57, s11, 0
	global_load_dwordx4 v[248:251], v1, s[56:57]
	s_add_u32 s53, s16, 0x0
	s_lshl_b32 s18, s53, 12
	s_lshl_b32 s19, s53, 11
	s_add_u32 s20, s12, s18
	s_addc_u32 s21, s13, 0
	s_add_u32 s22, s6, s19
	s_addc_u32 s23, s7, 0
	s_add_u32 s22, s22, 0x5200000
	s_addc_u32 s23, s23, 0
	s_add_u32 s24, s4, s18
	s_addc_u32 s25, s5, 0
	s_add_u32 s26, s6, s19
	s_addc_u32 s27, s7, 0
	s_add_u32 s26, s26, 0x3100000
	s_addc_u32 s27, s27, 0
	global_load_dwordx2 v[66:67], v2, s[22:23] offset:0 nt
	global_load_dwordx2 v[70:71], v2, s[22:23] offset:512 nt
	global_load_dwordx2 v[74:75], v2, s[22:23] offset:1024 nt
	global_load_dwordx2 v[78:79], v2, s[22:23] offset:1536 nt
	global_load_dwordx4 v[80:83], v1, s[20:21] offset:0 nt
	global_load_dwordx4 v[84:87], v1, s[20:21] offset:1024 nt
	global_load_dwordx4 v[88:91], v1, s[20:21] offset:2048 nt
	global_load_dwordx4 v[92:95], v1, s[20:21] offset:3072 nt
	s_add_u32 s53, s16, 0x800
	s_lshl_b32 s18, s53, 12
	s_lshl_b32 s19, s53, 11
	s_add_u32 s28, s12, s18
	s_addc_u32 s29, s13, 0
	s_add_u32 s30, s6, s19
	s_addc_u32 s31, s7, 0
	s_add_u32 s30, s30, 0x5200000
	s_addc_u32 s31, s31, 0
	s_add_u32 s32, s4, s18
	s_addc_u32 s33, s5, 0
	s_add_u32 s34, s6, s19
	s_addc_u32 s35, s7, 0
	s_add_u32 s34, s34, 0x3100000
	s_addc_u32 s35, s35, 0
	global_load_dwordx2 v[98:99], v2, s[30:31] offset:0 nt
	global_load_dwordx2 v[102:103], v2, s[30:31] offset:512 nt
	global_load_dwordx2 v[106:107], v2, s[30:31] offset:1024 nt
	global_load_dwordx2 v[110:111], v2, s[30:31] offset:1536 nt
	global_load_dwordx4 v[112:115], v1, s[28:29] offset:0 nt
	global_load_dwordx4 v[116:119], v1, s[28:29] offset:1024 nt
	global_load_dwordx4 v[120:123], v1, s[28:29] offset:2048 nt
	global_load_dwordx4 v[124:127], v1, s[28:29] offset:3072 nt
	s_add_u32 s53, s16, 0x1000
	s_lshl_b32 s18, s53, 12
	s_lshl_b32 s19, s53, 11
	s_add_u32 s36, s12, s18
	s_addc_u32 s37, s13, 0
	s_add_u32 s38, s6, s19
	s_addc_u32 s39, s7, 0
	s_add_u32 s38, s38, 0x5200000
	s_addc_u32 s39, s39, 0
	s_add_u32 s40, s4, s18
	s_addc_u32 s41, s5, 0
	s_add_u32 s42, s6, s19
	s_addc_u32 s43, s7, 0
	s_add_u32 s42, s42, 0x3100000
	s_addc_u32 s43, s43, 0
	global_load_dwordx2 v[130:131], v2, s[38:39] offset:0 nt
	global_load_dwordx2 v[134:135], v2, s[38:39] offset:512 nt
	global_load_dwordx2 v[138:139], v2, s[38:39] offset:1024 nt
	global_load_dwordx2 v[142:143], v2, s[38:39] offset:1536 nt
	global_load_dwordx4 v[144:147], v1, s[36:37] offset:0 nt
	global_load_dwordx4 v[148:151], v1, s[36:37] offset:1024 nt
	global_load_dwordx4 v[152:155], v1, s[36:37] offset:2048 nt
	global_load_dwordx4 v[156:159], v1, s[36:37] offset:3072 nt
	s_add_u32 s53, s16, 0x1800
	s_lshl_b32 s18, s53, 12
	s_lshl_b32 s19, s53, 11
	s_add_u32 s44, s12, s18
	s_addc_u32 s45, s13, 0
	s_add_u32 s46, s6, s19
	s_addc_u32 s47, s7, 0
	s_add_u32 s46, s46, 0x5200000
	s_addc_u32 s47, s47, 0
	s_add_u32 s48, s4, s18
	s_addc_u32 s49, s5, 0
	s_add_u32 s50, s6, s19
	s_addc_u32 s51, s7, 0
	s_add_u32 s50, s50, 0x3100000
	s_addc_u32 s51, s51, 0
	global_load_dwordx2 v[162:163], v2, s[46:47] offset:0 nt
	global_load_dwordx2 v[166:167], v2, s[46:47] offset:512 nt
	global_load_dwordx2 v[170:171], v2, s[46:47] offset:1024 nt
	global_load_dwordx2 v[174:175], v2, s[46:47] offset:1536 nt
	global_load_dwordx4 v[176:179], v1, s[44:45] offset:0 nt
	global_load_dwordx4 v[180:183], v1, s[44:45] offset:1024 nt
	global_load_dwordx4 v[184:187], v1, s[44:45] offset:2048 nt
	global_load_dwordx4 v[188:191], v1, s[44:45] offset:3072 nt
	s_waitcnt vmcnt(16)
	v_lshlrev_b32_e32 v64, 16, v66
	v_and_b32_e32 v65, 0xffff0000, v66
	v_lshlrev_b32_e32 v66, 16, v67
	v_and_b32_e32 v67, 0xffff0000, v67
	v_lshlrev_b32_e32 v68, 16, v70
	v_and_b32_e32 v69, 0xffff0000, v70
	v_lshlrev_b32_e32 v70, 16, v71
	v_and_b32_e32 v71, 0xffff0000, v71
	v_lshlrev_b32_e32 v72, 16, v74
	v_and_b32_e32 v73, 0xffff0000, v74
	v_lshlrev_b32_e32 v74, 16, v75
	v_and_b32_e32 v75, 0xffff0000, v75
	v_lshlrev_b32_e32 v76, 16, v78
	v_and_b32_e32 v77, 0xffff0000, v78
	v_lshlrev_b32_e32 v78, 16, v79
	v_and_b32_e32 v79, 0xffff0000, v79
	v_lshlrev_b32_e32 v96, 16, v98
	v_and_b32_e32 v97, 0xffff0000, v98
	v_lshlrev_b32_e32 v98, 16, v99
	v_and_b32_e32 v99, 0xffff0000, v99
	v_lshlrev_b32_e32 v100, 16, v102
	v_and_b32_e32 v101, 0xffff0000, v102
	v_lshlrev_b32_e32 v102, 16, v103
	v_and_b32_e32 v103, 0xffff0000, v103
	v_lshlrev_b32_e32 v104, 16, v106
	v_and_b32_e32 v105, 0xffff0000, v106
	v_lshlrev_b32_e32 v106, 16, v107
	v_and_b32_e32 v107, 0xffff0000, v107
	v_lshlrev_b32_e32 v108, 16, v110
	v_and_b32_e32 v109, 0xffff0000, v110
	v_lshlrev_b32_e32 v110, 16, v111
	v_and_b32_e32 v111, 0xffff0000, v111
	v_mul_f32_e32 v10, v64, v64
	v_fmac_f32_e32 v10, v65, v65
	v_fmac_f32_e32 v10, v66, v66
	v_fmac_f32_e32 v10, v67, v67
	v_fmac_f32_e32 v10, v68, v68
	v_fmac_f32_e32 v10, v69, v69
	v_fmac_f32_e32 v10, v70, v70
	v_fmac_f32_e32 v10, v71, v71
	v_fmac_f32_e32 v10, v72, v72
	v_fmac_f32_e32 v10, v73, v73
	v_fmac_f32_e32 v10, v74, v74
	v_fmac_f32_e32 v10, v75, v75
	v_fmac_f32_e32 v10, v76, v76
	v_fmac_f32_e32 v10, v77, v77
	v_fmac_f32_e32 v10, v78, v78
	v_fmac_f32_e32 v10, v79, v79
	v_mul_f32_e32 v11, v96, v96
	v_fmac_f32_e32 v11, v97, v97
	v_fmac_f32_e32 v11, v98, v98
	v_fmac_f32_e32 v11, v99, v99
	v_fmac_f32_e32 v11, v100, v100
	v_fmac_f32_e32 v11, v101, v101
	v_fmac_f32_e32 v11, v102, v102
	v_fmac_f32_e32 v11, v103, v103
	v_fmac_f32_e32 v11, v104, v104
	v_fmac_f32_e32 v11, v105, v105
	v_fmac_f32_e32 v11, v106, v106
	v_fmac_f32_e32 v11, v107, v107
	v_fmac_f32_e32 v11, v108, v108
	v_fmac_f32_e32 v11, v109, v109
	v_fmac_f32_e32 v11, v110, v110
	v_fmac_f32_e32 v11, v111, v111
	ds_bpermute_b32 v12, v4, v10
	ds_bpermute_b32 v13, v4, v11
	s_waitcnt lgkmcnt(0)
	v_add_f32_e32 v10, v10, v12
	v_add_f32_e32 v11, v11, v13
	ds_bpermute_b32 v12, v5, v10
	ds_bpermute_b32 v13, v5, v11
	s_waitcnt lgkmcnt(0)
	v_add_f32_e32 v10, v10, v12
	v_add_f32_e32 v11, v11, v13
	ds_bpermute_b32 v12, v6, v10
	ds_bpermute_b32 v13, v6, v11
	s_waitcnt lgkmcnt(0)
	v_add_f32_e32 v10, v10, v12
	v_add_f32_e32 v11, v11, v13
	ds_bpermute_b32 v12, v7, v10
	ds_bpermute_b32 v13, v7, v11
	s_waitcnt lgkmcnt(0)
	v_add_f32_e32 v10, v10, v12
	v_add_f32_e32 v11, v11, v13
	ds_bpermute_b32 v12, v8, v10
	ds_bpermute_b32 v13, v8, v11
	s_waitcnt lgkmcnt(0)
	v_add_f32_e32 v10, v10, v12
	v_add_f32_e32 v11, v11, v13
	ds_bpermute_b32 v12, v9, v10
	ds_bpermute_b32 v13, v9, v11
	s_waitcnt lgkmcnt(0)
	v_add_f32_e32 v10, v10, v12
	v_add_f32_e32 v11, v11, v13
	v_fma_f32 v14, v10, s17, v3
	v_fma_f32 v15, v11, s17, v3
	v_rsq_f32_e32 v14, v14
	v_rsq_f32_e32 v15, v15
	s_nop 0
	v_mul_f32_e32 v64, v64, v14
	v_mul_f32_e32 v65, v65, v14
	v_mul_f32_e32 v66, v66, v14
	v_mul_f32_e32 v67, v67, v14
	v_mul_f32_e32 v68, v68, v14
	v_mul_f32_e32 v69, v69, v14
	v_mul_f32_e32 v70, v70, v14
	v_mul_f32_e32 v71, v71, v14
	v_mul_f32_e32 v72, v72, v14
	v_mul_f32_e32 v73, v73, v14
	v_mul_f32_e32 v74, v74, v14
	v_mul_f32_e32 v75, v75, v14
	v_mul_f32_e32 v76, v76, v14
	v_mul_f32_e32 v77, v77, v14
	v_mul_f32_e32 v78, v78, v14
	v_mul_f32_e32 v79, v79, v14
	v_fmac_f32_e32 v80, v64, v20
	v_fmac_f32_e32 v81, v65, v21
	v_fmac_f32_e32 v82, v66, v22
	v_fmac_f32_e32 v83, v67, v23
	v_fmac_f32_e32 v84, v68, v24
	v_fmac_f32_e32 v85, v69, v25
	v_fmac_f32_e32 v86, v70, v26
	v_fmac_f32_e32 v87, v71, v27
	v_fmac_f32_e32 v88, v72, v28
	v_fmac_f32_e32 v89, v73, v29
	v_fmac_f32_e32 v90, v74, v30
	v_fmac_f32_e32 v91, v75, v31
	v_fmac_f32_e32 v92, v76, v32
	v_fmac_f32_e32 v93, v77, v33
	v_fmac_f32_e32 v94, v78, v34
	v_fmac_f32_e32 v95, v79, v35
	global_store_dwordx4 v1, v[80:83], s[24:25] offset:0 nt
	global_store_dwordx4 v1, v[84:87], s[24:25] offset:1024 nt
	global_store_dwordx4 v1, v[88:91], s[24:25] offset:2048 nt
	global_store_dwordx4 v1, v[92:95], s[24:25] offset:3072 nt
	v_mul_f32_e32 v96, v96, v15
	v_mul_f32_e32 v97, v97, v15
	v_mul_f32_e32 v98, v98, v15
	v_mul_f32_e32 v99, v99, v15
	v_mul_f32_e32 v100, v100, v15
	v_mul_f32_e32 v101, v101, v15
	v_mul_f32_e32 v102, v102, v15
	v_mul_f32_e32 v103, v103, v15
	v_mul_f32_e32 v104, v104, v15
	v_mul_f32_e32 v105, v105, v15
	v_mul_f32_e32 v106, v106, v15
	v_mul_f32_e32 v107, v107, v15
	v_mul_f32_e32 v108, v108, v15
	v_mul_f32_e32 v109, v109, v15
	v_mul_f32_e32 v110, v110, v15
	v_mul_f32_e32 v111, v111, v15
	v_fmac_f32_e32 v112, v96, v20
	v_fmac_f32_e32 v113, v97, v21
	v_fmac_f32_e32 v114, v98, v22
	v_fmac_f32_e32 v115, v99, v23
	v_fmac_f32_e32 v116, v100, v24
	v_fmac_f32_e32 v117, v101, v25
	v_fmac_f32_e32 v118, v102, v26
	v_fmac_f32_e32 v119, v103, v27
	v_fmac_f32_e32 v120, v104, v28
	v_fmac_f32_e32 v121, v105, v29
	v_fmac_f32_e32 v122, v106, v30
	v_fmac_f32_e32 v123, v107, v31
	v_fmac_f32_e32 v124, v108, v32
	v_fmac_f32_e32 v125, v109, v33
	v_fmac_f32_e32 v126, v110, v34
	v_fmac_f32_e32 v127, v111, v35
	global_store_dwordx4 v1, v[112:115], s[32:33] offset:0 nt
	global_store_dwordx4 v1, v[116:119], s[32:33] offset:1024 nt
	global_store_dwordx4 v1, v[120:123], s[32:33] offset:2048 nt
	global_store_dwordx4 v1, v[124:127], s[32:33] offset:3072 nt
	v_mul_f32_e32 v10, v80, v80
	v_fmac_f32_e32 v10, v81, v81
	v_fmac_f32_e32 v10, v82, v82
	v_fmac_f32_e32 v10, v83, v83
	v_fmac_f32_e32 v10, v84, v84
	v_fmac_f32_e32 v10, v85, v85
	v_fmac_f32_e32 v10, v86, v86
	v_fmac_f32_e32 v10, v87, v87
	v_fmac_f32_e32 v10, v88, v88
	v_fmac_f32_e32 v10, v89, v89
	v_fmac_f32_e32 v10, v90, v90
	v_fmac_f32_e32 v10, v91, v91
	v_fmac_f32_e32 v10, v92, v92
	v_fmac_f32_e32 v10, v93, v93
	v_fmac_f32_e32 v10, v94, v94
	v_fmac_f32_e32 v10, v95, v95
	v_mul_f32_e32 v11, v112, v112
	v_fmac_f32_e32 v11, v113, v113
	v_fmac_f32_e32 v11, v114, v114
	v_fmac_f32_e32 v11, v115, v115
	v_fmac_f32_e32 v11, v116, v116
	v_fmac_f32_e32 v11, v117, v117
	v_fmac_f32_e32 v11, v118, v118
	v_fmac_f32_e32 v11, v119, v119
	v_fmac_f32_e32 v11, v120, v120
	v_fmac_f32_e32 v11, v121, v121
	v_fmac_f32_e32 v11, v122, v122
	v_fmac_f32_e32 v11, v123, v123
	v_fmac_f32_e32 v11, v124, v124
	v_fmac_f32_e32 v11, v125, v125
	v_fmac_f32_e32 v11, v126, v126
	v_fmac_f32_e32 v11, v127, v127
	ds_bpermute_b32 v12, v4, v10
	ds_bpermute_b32 v13, v4, v11
	s_waitcnt lgkmcnt(0)
	v_add_f32_e32 v10, v10, v12
	v_add_f32_e32 v11, v11, v13
	ds_bpermute_b32 v12, v5, v10
	ds_bpermute_b32 v13, v5, v11
	s_waitcnt lgkmcnt(0)
	v_add_f32_e32 v10, v10, v12
	v_add_f32_e32 v11, v11, v13
	ds_bpermute_b32 v12, v6, v10
	ds_bpermute_b32 v13, v6, v11
	s_waitcnt lgkmcnt(0)
	v_add_f32_e32 v10, v10, v12
	v_add_f32_e32 v11, v11, v13
	ds_bpermute_b32 v12, v7, v10
	ds_bpermute_b32 v13, v7, v11
	s_waitcnt lgkmcnt(0)
	v_add_f32_e32 v10, v10, v12
	v_add_f32_e32 v11, v11, v13
	ds_bpermute_b32 v12, v8, v10
	ds_bpermute_b32 v13, v8, v11
	s_waitcnt lgkmcnt(0)
	v_add_f32_e32 v10, v10, v12
	v_add_f32_e32 v11, v11, v13
	ds_bpermute_b32 v12, v9, v10
	ds_bpermute_b32 v13, v9, v11
	s_waitcnt lgkmcnt(0)
	v_add_f32_e32 v10, v10, v12
	v_add_f32_e32 v11, v11, v13
	v_fma_f32 v14, v10, s17, v3
	v_fma_f32 v15, v11, s17, v3
	v_rsq_f32_e32 v14, v14
	v_rsq_f32_e32 v15, v15
	s_nop 0
	v_mul_f32_e32 v64, v80, v14
	v_mul_f32_e32 v65, v81, v14
	v_mul_f32_e32 v66, v82, v14
	v_mul_f32_e32 v67, v83, v14
	v_mul_f32_e32 v68, v84, v14
	v_mul_f32_e32 v69, v85, v14
	v_mul_f32_e32 v70, v86, v14
	v_mul_f32_e32 v71, v87, v14
	v_mul_f32_e32 v72, v88, v14
	v_mul_f32_e32 v73, v89, v14
	v_mul_f32_e32 v74, v90, v14
	v_mul_f32_e32 v75, v91, v14
	v_mul_f32_e32 v76, v92, v14
	v_mul_f32_e32 v77, v93, v14
	v_mul_f32_e32 v78, v94, v14
	v_mul_f32_e32 v79, v95, v14
	v_mul_f32_e32 v64, v64, v36
	v_mul_f32_e32 v65, v65, v37
	v_mul_f32_e32 v66, v66, v38
	v_mul_f32_e32 v67, v67, v39
	v_mul_f32_e32 v68, v68, v40
	v_mul_f32_e32 v69, v69, v41
	v_mul_f32_e32 v70, v70, v42
	v_mul_f32_e32 v71, v71, v43
	v_mul_f32_e32 v72, v72, v44
	v_mul_f32_e32 v73, v73, v45
	v_mul_f32_e32 v74, v74, v46
	v_mul_f32_e32 v75, v75, v47
	v_mul_f32_e32 v76, v76, v48
	v_mul_f32_e32 v77, v77, v49
	v_mul_f32_e32 v78, v78, v50
	v_mul_f32_e32 v79, v79, v51
	v_cvt_pk_bf16_f32 v64, v64, v65
	v_cvt_pk_bf16_f32 v65, v66, v67
	v_cvt_pk_bf16_f32 v68, v68, v69
	v_cvt_pk_bf16_f32 v69, v70, v71
	v_cvt_pk_bf16_f32 v72, v72, v73
	v_cvt_pk_bf16_f32 v73, v74, v75
	v_cvt_pk_bf16_f32 v76, v76, v77
	v_cvt_pk_bf16_f32 v77, v78, v79
	global_store_dwordx2 v2, v[64:65], s[26:27] offset:0
	global_store_dwordx2 v2, v[68:69], s[26:27] offset:512
	global_store_dwordx2 v2, v[72:73], s[26:27] offset:1024
	global_store_dwordx2 v2, v[76:77], s[26:27] offset:1536
	v_mul_f32_e32 v96, v112, v15
	v_mul_f32_e32 v97, v113, v15
	v_mul_f32_e32 v98, v114, v15
	v_mul_f32_e32 v99, v115, v15
	v_mul_f32_e32 v100, v116, v15
	v_mul_f32_e32 v101, v117, v15
	v_mul_f32_e32 v102, v118, v15
	v_mul_f32_e32 v103, v119, v15
	v_mul_f32_e32 v104, v120, v15
	v_mul_f32_e32 v105, v121, v15
	v_mul_f32_e32 v106, v122, v15
	v_mul_f32_e32 v107, v123, v15
	v_mul_f32_e32 v108, v124, v15
	v_mul_f32_e32 v109, v125, v15
	v_mul_f32_e32 v110, v126, v15
	v_mul_f32_e32 v111, v127, v15
	v_mul_f32_e32 v96, v96, v36
	v_mul_f32_e32 v97, v97, v37
	v_mul_f32_e32 v98, v98, v38
	v_mul_f32_e32 v99, v99, v39
	v_mul_f32_e32 v100, v100, v40
	v_mul_f32_e32 v101, v101, v41
	v_mul_f32_e32 v102, v102, v42
	v_mul_f32_e32 v103, v103, v43
	v_mul_f32_e32 v104, v104, v44
	v_mul_f32_e32 v105, v105, v45
	v_mul_f32_e32 v106, v106, v46
	v_mul_f32_e32 v107, v107, v47
	v_mul_f32_e32 v108, v108, v48
	v_mul_f32_e32 v109, v109, v49
	v_mul_f32_e32 v110, v110, v50
	v_mul_f32_e32 v111, v111, v51
	v_cvt_pk_bf16_f32 v96, v96, v97
	v_cvt_pk_bf16_f32 v97, v98, v99
	v_cvt_pk_bf16_f32 v100, v100, v101
	v_cvt_pk_bf16_f32 v101, v102, v103
	v_cvt_pk_bf16_f32 v104, v104, v105
	v_cvt_pk_bf16_f32 v105, v106, v107
	v_cvt_pk_bf16_f32 v108, v108, v109
	v_cvt_pk_bf16_f32 v109, v110, v111
	global_store_dwordx2 v2, v[96:97], s[34:35] offset:0
	global_store_dwordx2 v2, v[100:101], s[34:35] offset:512
	global_store_dwordx2 v2, v[104:105], s[34:35] offset:1024
	global_store_dwordx2 v2, v[108:109], s[34:35] offset:1536
	s_add_u32 s53, s16, 0x2000
	s_lshl_b32 s18, s53, 12
	s_lshl_b32 s19, s53, 11
	s_add_u32 s20, s12, s18
	s_addc_u32 s21, s13, 0
	s_add_u32 s22, s6, s19
	s_addc_u32 s23, s7, 0
	s_add_u32 s22, s22, 0x5200000
	s_addc_u32 s23, s23, 0
	s_add_u32 s24, s4, s18
	s_addc_u32 s25, s5, 0
	s_add_u32 s26, s6, s19
	s_addc_u32 s27, s7, 0
	s_add_u32 s26, s26, 0x3100000
	s_addc_u32 s27, s27, 0
	global_load_dwordx2 v[66:67], v2, s[22:23] offset:0 nt
	global_load_dwordx2 v[70:71], v2, s[22:23] offset:512 nt
	global_load_dwordx2 v[74:75], v2, s[22:23] offset:1024 nt
	global_load_dwordx2 v[78:79], v2, s[22:23] offset:1536 nt
	global_load_dwordx4 v[80:83], v1, s[20:21] offset:0 nt
	global_load_dwordx4 v[84:87], v1, s[20:21] offset:1024 nt
	global_load_dwordx4 v[88:91], v1, s[20:21] offset:2048 nt
	global_load_dwordx4 v[92:95], v1, s[20:21] offset:3072 nt
	s_add_u32 s53, s16, 0x2800
	s_lshl_b32 s18, s53, 12
	s_lshl_b32 s19, s53, 11
	s_add_u32 s28, s12, s18
	s_addc_u32 s29, s13, 0
	s_add_u32 s30, s6, s19
	s_addc_u32 s31, s7, 0
	s_add_u32 s30, s30, 0x5200000
	s_addc_u32 s31, s31, 0
	s_add_u32 s32, s4, s18
	s_addc_u32 s33, s5, 0
	s_add_u32 s34, s6, s19
	s_addc_u32 s35, s7, 0
	s_add_u32 s34, s34, 0x3100000
	s_addc_u32 s35, s35, 0
	global_load_dwordx2 v[98:99], v2, s[30:31] offset:0 nt
	global_load_dwordx2 v[102:103], v2, s[30:31] offset:512 nt
	global_load_dwordx2 v[106:107], v2, s[30:31] offset:1024 nt
	global_load_dwordx2 v[110:111], v2, s[30:31] offset:1536 nt
	global_load_dwordx4 v[112:115], v1, s[28:29] offset:0 nt
	global_load_dwordx4 v[116:119], v1, s[28:29] offset:1024 nt
	global_load_dwordx4 v[120:123], v1, s[28:29] offset:2048 nt
	global_load_dwordx4 v[124:127], v1, s[28:29] offset:3072 nt
	s_waitcnt vmcnt(32)
	v_lshlrev_b32_e32 v128, 16, v130
	v_and_b32_e32 v129, 0xffff0000, v130
	v_lshlrev_b32_e32 v130, 16, v131
	v_and_b32_e32 v131, 0xffff0000, v131
	v_lshlrev_b32_e32 v132, 16, v134
	v_and_b32_e32 v133, 0xffff0000, v134
	v_lshlrev_b32_e32 v134, 16, v135
	v_and_b32_e32 v135, 0xffff0000, v135
	v_lshlrev_b32_e32 v136, 16, v138
	v_and_b32_e32 v137, 0xffff0000, v138
	v_lshlrev_b32_e32 v138, 16, v139
	v_and_b32_e32 v139, 0xffff0000, v139
	v_lshlrev_b32_e32 v140, 16, v142
	v_and_b32_e32 v141, 0xffff0000, v142
	v_lshlrev_b32_e32 v142, 16, v143
	v_and_b32_e32 v143, 0xffff0000, v143
	v_lshlrev_b32_e32 v160, 16, v162
	v_and_b32_e32 v161, 0xffff0000, v162
	v_lshlrev_b32_e32 v162, 16, v163
	v_and_b32_e32 v163, 0xffff0000, v163
	v_lshlrev_b32_e32 v164, 16, v166
	v_and_b32_e32 v165, 0xffff0000, v166
	v_lshlrev_b32_e32 v166, 16, v167
	v_and_b32_e32 v167, 0xffff0000, v167
	v_lshlrev_b32_e32 v168, 16, v170
	v_and_b32_e32 v169, 0xffff0000, v170
	v_lshlrev_b32_e32 v170, 16, v171
	v_and_b32_e32 v171, 0xffff0000, v171
	v_lshlrev_b32_e32 v172, 16, v174
	v_and_b32_e32 v173, 0xffff0000, v174
	v_lshlrev_b32_e32 v174, 16, v175
	v_and_b32_e32 v175, 0xffff0000, v175
	v_mul_f32_e32 v10, v128, v128
	v_fmac_f32_e32 v10, v129, v129
	v_fmac_f32_e32 v10, v130, v130
	v_fmac_f32_e32 v10, v131, v131
	v_fmac_f32_e32 v10, v132, v132
	v_fmac_f32_e32 v10, v133, v133
	v_fmac_f32_e32 v10, v134, v134
	v_fmac_f32_e32 v10, v135, v135
	v_fmac_f32_e32 v10, v136, v136
	v_fmac_f32_e32 v10, v137, v137
	v_fmac_f32_e32 v10, v138, v138
	v_fmac_f32_e32 v10, v139, v139
	v_fmac_f32_e32 v10, v140, v140
	v_fmac_f32_e32 v10, v141, v141
	v_fmac_f32_e32 v10, v142, v142
	v_fmac_f32_e32 v10, v143, v143
	v_mul_f32_e32 v11, v160, v160
	v_fmac_f32_e32 v11, v161, v161
	v_fmac_f32_e32 v11, v162, v162
	v_fmac_f32_e32 v11, v163, v163
	v_fmac_f32_e32 v11, v164, v164
	v_fmac_f32_e32 v11, v165, v165
	v_fmac_f32_e32 v11, v166, v166
	v_fmac_f32_e32 v11, v167, v167
	v_fmac_f32_e32 v11, v168, v168
	v_fmac_f32_e32 v11, v169, v169
	v_fmac_f32_e32 v11, v170, v170
	v_fmac_f32_e32 v11, v171, v171
	v_fmac_f32_e32 v11, v172, v172
	v_fmac_f32_e32 v11, v173, v173
	v_fmac_f32_e32 v11, v174, v174
	v_fmac_f32_e32 v11, v175, v175
	ds_bpermute_b32 v12, v4, v10
	ds_bpermute_b32 v13, v4, v11
	s_waitcnt lgkmcnt(0)
	v_add_f32_e32 v10, v10, v12
	v_add_f32_e32 v11, v11, v13
	ds_bpermute_b32 v12, v5, v10
	ds_bpermute_b32 v13, v5, v11
	s_waitcnt lgkmcnt(0)
	v_add_f32_e32 v10, v10, v12
	v_add_f32_e32 v11, v11, v13
	ds_bpermute_b32 v12, v6, v10
	ds_bpermute_b32 v13, v6, v11
	s_waitcnt lgkmcnt(0)
	v_add_f32_e32 v10, v10, v12
	v_add_f32_e32 v11, v11, v13
	ds_bpermute_b32 v12, v7, v10
	ds_bpermute_b32 v13, v7, v11
	s_waitcnt lgkmcnt(0)
	v_add_f32_e32 v10, v10, v12
	v_add_f32_e32 v11, v11, v13
	ds_bpermute_b32 v12, v8, v10
	ds_bpermute_b32 v13, v8, v11
	s_waitcnt lgkmcnt(0)
	v_add_f32_e32 v10, v10, v12
	v_add_f32_e32 v11, v11, v13
	ds_bpermute_b32 v12, v9, v10
	ds_bpermute_b32 v13, v9, v11
	s_waitcnt lgkmcnt(0)
	v_add_f32_e32 v10, v10, v12
	v_add_f32_e32 v11, v11, v13
	v_fma_f32 v14, v10, s17, v3
	v_fma_f32 v15, v11, s17, v3
	v_rsq_f32_e32 v14, v14
	v_rsq_f32_e32 v15, v15
	s_nop 0
	v_mul_f32_e32 v128, v128, v14
	v_mul_f32_e32 v129, v129, v14
	v_mul_f32_e32 v130, v130, v14
	v_mul_f32_e32 v131, v131, v14
	v_mul_f32_e32 v132, v132, v14
	v_mul_f32_e32 v133, v133, v14
	v_mul_f32_e32 v134, v134, v14
	v_mul_f32_e32 v135, v135, v14
	v_mul_f32_e32 v136, v136, v14
	v_mul_f32_e32 v137, v137, v14
	v_mul_f32_e32 v138, v138, v14
	v_mul_f32_e32 v139, v139, v14
	v_mul_f32_e32 v140, v140, v14
	v_mul_f32_e32 v141, v141, v14
	v_mul_f32_e32 v142, v142, v14
	v_mul_f32_e32 v143, v143, v14
	v_fmac_f32_e32 v144, v128, v20
	v_fmac_f32_e32 v145, v129, v21
	v_fmac_f32_e32 v146, v130, v22
	v_fmac_f32_e32 v147, v131, v23
	v_fmac_f32_e32 v148, v132, v24
	v_fmac_f32_e32 v149, v133, v25
	v_fmac_f32_e32 v150, v134, v26
	v_fmac_f32_e32 v151, v135, v27
	v_fmac_f32_e32 v152, v136, v28
	v_fmac_f32_e32 v153, v137, v29
	v_fmac_f32_e32 v154, v138, v30
	v_fmac_f32_e32 v155, v139, v31
	v_fmac_f32_e32 v156, v140, v32
	v_fmac_f32_e32 v157, v141, v33
	v_fmac_f32_e32 v158, v142, v34
	v_fmac_f32_e32 v159, v143, v35
	global_store_dwordx4 v1, v[144:147], s[40:41] offset:0 nt
	global_store_dwordx4 v1, v[148:151], s[40:41] offset:1024 nt
	global_store_dwordx4 v1, v[152:155], s[40:41] offset:2048 nt
	global_store_dwordx4 v1, v[156:159], s[40:41] offset:3072 nt
	v_mul_f32_e32 v160, v160, v15
	v_mul_f32_e32 v161, v161, v15
	v_mul_f32_e32 v162, v162, v15
	v_mul_f32_e32 v163, v163, v15
	v_mul_f32_e32 v164, v164, v15
	v_mul_f32_e32 v165, v165, v15
	v_mul_f32_e32 v166, v166, v15
	v_mul_f32_e32 v167, v167, v15
	v_mul_f32_e32 v168, v168, v15
	v_mul_f32_e32 v169, v169, v15
	v_mul_f32_e32 v170, v170, v15
	v_mul_f32_e32 v171, v171, v15
	v_mul_f32_e32 v172, v172, v15
	v_mul_f32_e32 v173, v173, v15
	v_mul_f32_e32 v174, v174, v15
	v_mul_f32_e32 v175, v175, v15
	v_fmac_f32_e32 v176, v160, v20
	v_fmac_f32_e32 v177, v161, v21
	v_fmac_f32_e32 v178, v162, v22
	v_fmac_f32_e32 v179, v163, v23
	v_fmac_f32_e32 v180, v164, v24
	v_fmac_f32_e32 v181, v165, v25
	v_fmac_f32_e32 v182, v166, v26
	v_fmac_f32_e32 v183, v167, v27
	v_fmac_f32_e32 v184, v168, v28
	v_fmac_f32_e32 v185, v169, v29
	v_fmac_f32_e32 v186, v170, v30
	v_fmac_f32_e32 v187, v171, v31
	v_fmac_f32_e32 v188, v172, v32
	v_fmac_f32_e32 v189, v173, v33
	v_fmac_f32_e32 v190, v174, v34
	v_fmac_f32_e32 v191, v175, v35
	global_store_dwordx4 v1, v[176:179], s[48:49] offset:0 nt
	global_store_dwordx4 v1, v[180:183], s[48:49] offset:1024 nt
	global_store_dwordx4 v1, v[184:187], s[48:49] offset:2048 nt
	global_store_dwordx4 v1, v[188:191], s[48:49] offset:3072 nt
	v_mul_f32_e32 v10, v144, v144
	v_fmac_f32_e32 v10, v145, v145
	v_fmac_f32_e32 v10, v146, v146
	v_fmac_f32_e32 v10, v147, v147
	v_fmac_f32_e32 v10, v148, v148
	v_fmac_f32_e32 v10, v149, v149
	v_fmac_f32_e32 v10, v150, v150
	v_fmac_f32_e32 v10, v151, v151
	v_fmac_f32_e32 v10, v152, v152
	v_fmac_f32_e32 v10, v153, v153
	v_fmac_f32_e32 v10, v154, v154
	v_fmac_f32_e32 v10, v155, v155
	v_fmac_f32_e32 v10, v156, v156
	v_fmac_f32_e32 v10, v157, v157
	v_fmac_f32_e32 v10, v158, v158
	v_fmac_f32_e32 v10, v159, v159
	v_mul_f32_e32 v11, v176, v176
	v_fmac_f32_e32 v11, v177, v177
	v_fmac_f32_e32 v11, v178, v178
	v_fmac_f32_e32 v11, v179, v179
	v_fmac_f32_e32 v11, v180, v180
	v_fmac_f32_e32 v11, v181, v181
	v_fmac_f32_e32 v11, v182, v182
	v_fmac_f32_e32 v11, v183, v183
	v_fmac_f32_e32 v11, v184, v184
	v_fmac_f32_e32 v11, v185, v185
	v_fmac_f32_e32 v11, v186, v186
	v_fmac_f32_e32 v11, v187, v187
	v_fmac_f32_e32 v11, v188, v188
	v_fmac_f32_e32 v11, v189, v189
	v_fmac_f32_e32 v11, v190, v190
	v_fmac_f32_e32 v11, v191, v191
	ds_bpermute_b32 v12, v4, v10
	ds_bpermute_b32 v13, v4, v11
	s_waitcnt lgkmcnt(0)
	v_add_f32_e32 v10, v10, v12
	v_add_f32_e32 v11, v11, v13
	ds_bpermute_b32 v12, v5, v10
	ds_bpermute_b32 v13, v5, v11
	s_waitcnt lgkmcnt(0)
	v_add_f32_e32 v10, v10, v12
	v_add_f32_e32 v11, v11, v13
	ds_bpermute_b32 v12, v6, v10
	ds_bpermute_b32 v13, v6, v11
	s_waitcnt lgkmcnt(0)
	v_add_f32_e32 v10, v10, v12
	v_add_f32_e32 v11, v11, v13
	ds_bpermute_b32 v12, v7, v10
	ds_bpermute_b32 v13, v7, v11
	s_waitcnt lgkmcnt(0)
	v_add_f32_e32 v10, v10, v12
	v_add_f32_e32 v11, v11, v13
	ds_bpermute_b32 v12, v8, v10
	ds_bpermute_b32 v13, v8, v11
	s_waitcnt lgkmcnt(0)
	v_add_f32_e32 v10, v10, v12
	v_add_f32_e32 v11, v11, v13
	ds_bpermute_b32 v12, v9, v10
	ds_bpermute_b32 v13, v9, v11
	s_waitcnt lgkmcnt(0)
	v_add_f32_e32 v10, v10, v12
	v_add_f32_e32 v11, v11, v13
	v_fma_f32 v14, v10, s17, v3
	v_fma_f32 v15, v11, s17, v3
	v_rsq_f32_e32 v14, v14
	v_rsq_f32_e32 v15, v15
	s_nop 0
	v_mul_f32_e32 v128, v144, v14
	v_mul_f32_e32 v129, v145, v14
	v_mul_f32_e32 v130, v146, v14
	v_mul_f32_e32 v131, v147, v14
	v_mul_f32_e32 v132, v148, v14
	v_mul_f32_e32 v133, v149, v14
	v_mul_f32_e32 v134, v150, v14
	v_mul_f32_e32 v135, v151, v14
	v_mul_f32_e32 v136, v152, v14
	v_mul_f32_e32 v137, v153, v14
	v_mul_f32_e32 v138, v154, v14
	v_mul_f32_e32 v139, v155, v14
	v_mul_f32_e32 v140, v156, v14
	v_mul_f32_e32 v141, v157, v14
	v_mul_f32_e32 v142, v158, v14
	v_mul_f32_e32 v143, v159, v14
	v_mul_f32_e32 v128, v128, v36
	v_mul_f32_e32 v129, v129, v37
	v_mul_f32_e32 v130, v130, v38
	v_mul_f32_e32 v131, v131, v39
	v_mul_f32_e32 v132, v132, v40
	v_mul_f32_e32 v133, v133, v41
	v_mul_f32_e32 v134, v134, v42
	v_mul_f32_e32 v135, v135, v43
	v_mul_f32_e32 v136, v136, v44
	v_mul_f32_e32 v137, v137, v45
	v_mul_f32_e32 v138, v138, v46
	v_mul_f32_e32 v139, v139, v47
	v_mul_f32_e32 v140, v140, v48
	v_mul_f32_e32 v141, v141, v49
	v_mul_f32_e32 v142, v142, v50
	v_mul_f32_e32 v143, v143, v51
	v_cvt_pk_bf16_f32 v128, v128, v129
	v_cvt_pk_bf16_f32 v129, v130, v131
	v_cvt_pk_bf16_f32 v132, v132, v133
	v_cvt_pk_bf16_f32 v133, v134, v135
	v_cvt_pk_bf16_f32 v136, v136, v137
	v_cvt_pk_bf16_f32 v137, v138, v139
	v_cvt_pk_bf16_f32 v140, v140, v141
	v_cvt_pk_bf16_f32 v141, v142, v143
	global_store_dwordx2 v2, v[128:129], s[42:43] offset:0
	global_store_dwordx2 v2, v[132:133], s[42:43] offset:512
	global_store_dwordx2 v2, v[136:137], s[42:43] offset:1024
	global_store_dwordx2 v2, v[140:141], s[42:43] offset:1536
	v_mul_f32_e32 v160, v176, v15
	v_mul_f32_e32 v161, v177, v15
	v_mul_f32_e32 v162, v178, v15
	v_mul_f32_e32 v163, v179, v15
	v_mul_f32_e32 v164, v180, v15
	v_mul_f32_e32 v165, v181, v15
	v_mul_f32_e32 v166, v182, v15
	v_mul_f32_e32 v167, v183, v15
	v_mul_f32_e32 v168, v184, v15
	v_mul_f32_e32 v169, v185, v15
	v_mul_f32_e32 v170, v186, v15
	v_mul_f32_e32 v171, v187, v15
	v_mul_f32_e32 v172, v188, v15
	v_mul_f32_e32 v173, v189, v15
	v_mul_f32_e32 v174, v190, v15
	v_mul_f32_e32 v175, v191, v15
	v_mul_f32_e32 v160, v160, v36
	v_mul_f32_e32 v161, v161, v37
	v_mul_f32_e32 v162, v162, v38
	v_mul_f32_e32 v163, v163, v39
	v_mul_f32_e32 v164, v164, v40
	v_mul_f32_e32 v165, v165, v41
	v_mul_f32_e32 v166, v166, v42
	v_mul_f32_e32 v167, v167, v43
	v_mul_f32_e32 v168, v168, v44
	v_mul_f32_e32 v169, v169, v45
	v_mul_f32_e32 v170, v170, v46
	v_mul_f32_e32 v171, v171, v47
	v_mul_f32_e32 v172, v172, v48
	v_mul_f32_e32 v173, v173, v49
	v_mul_f32_e32 v174, v174, v50
	v_mul_f32_e32 v175, v175, v51
	v_cvt_pk_bf16_f32 v160, v160, v161
	v_cvt_pk_bf16_f32 v161, v162, v163
	v_cvt_pk_bf16_f32 v164, v164, v165
	v_cvt_pk_bf16_f32 v165, v166, v167
	v_cvt_pk_bf16_f32 v168, v168, v169
	v_cvt_pk_bf16_f32 v169, v170, v171
	v_cvt_pk_bf16_f32 v172, v172, v173
	v_cvt_pk_bf16_f32 v173, v174, v175
	global_store_dwordx2 v2, v[160:161], s[50:51] offset:0
	global_store_dwordx2 v2, v[164:165], s[50:51] offset:512
	global_store_dwordx2 v2, v[168:169], s[50:51] offset:1024
	global_store_dwordx2 v2, v[172:173], s[50:51] offset:1536
	s_add_u32 s53, s16, 0x3000
	s_lshl_b32 s18, s53, 12
	s_lshl_b32 s19, s53, 11
	s_add_u32 s36, s12, s18
	s_addc_u32 s37, s13, 0
	s_add_u32 s38, s6, s19
	s_addc_u32 s39, s7, 0
	s_add_u32 s38, s38, 0x5200000
	s_addc_u32 s39, s39, 0
	s_add_u32 s40, s4, s18
	s_addc_u32 s41, s5, 0
	s_add_u32 s42, s6, s19
	s_addc_u32 s43, s7, 0
	s_add_u32 s42, s42, 0x3100000
	s_addc_u32 s43, s43, 0
	global_load_dwordx2 v[130:131], v2, s[38:39] offset:0 nt
	global_load_dwordx2 v[134:135], v2, s[38:39] offset:512 nt
	global_load_dwordx2 v[138:139], v2, s[38:39] offset:1024 nt
	global_load_dwordx2 v[142:143], v2, s[38:39] offset:1536 nt
	global_load_dwordx4 v[144:147], v1, s[36:37] offset:0 nt
	global_load_dwordx4 v[148:151], v1, s[36:37] offset:1024 nt
	global_load_dwordx4 v[152:155], v1, s[36:37] offset:2048 nt
	global_load_dwordx4 v[156:159], v1, s[36:37] offset:3072 nt
	s_add_u32 s53, s16, 0x3800
	s_lshl_b32 s18, s53, 12
	s_lshl_b32 s19, s53, 11
	s_add_u32 s44, s12, s18
	s_addc_u32 s45, s13, 0
	s_add_u32 s46, s6, s19
	s_addc_u32 s47, s7, 0
	s_add_u32 s46, s46, 0x5200000
	s_addc_u32 s47, s47, 0
	s_add_u32 s48, s4, s18
	s_addc_u32 s49, s5, 0
	s_add_u32 s50, s6, s19
	s_addc_u32 s51, s7, 0
	s_add_u32 s50, s50, 0x3100000
	s_addc_u32 s51, s51, 0
	global_load_dwordx2 v[162:163], v2, s[46:47] offset:0 nt
	global_load_dwordx2 v[166:167], v2, s[46:47] offset:512 nt
	global_load_dwordx2 v[170:171], v2, s[46:47] offset:1024 nt
	global_load_dwordx2 v[174:175], v2, s[46:47] offset:1536 nt
	global_load_dwordx4 v[176:179], v1, s[44:45] offset:0 nt
	global_load_dwordx4 v[180:183], v1, s[44:45] offset:1024 nt
	global_load_dwordx4 v[184:187], v1, s[44:45] offset:2048 nt
	global_load_dwordx4 v[188:191], v1, s[44:45] offset:3072 nt
	s_waitcnt vmcnt(32)
	v_lshlrev_b32_e32 v64, 16, v66
	v_and_b32_e32 v65, 0xffff0000, v66
	v_lshlrev_b32_e32 v66, 16, v67
	v_and_b32_e32 v67, 0xffff0000, v67
	v_lshlrev_b32_e32 v68, 16, v70
	v_and_b32_e32 v69, 0xffff0000, v70
	v_lshlrev_b32_e32 v70, 16, v71
	v_and_b32_e32 v71, 0xffff0000, v71
	v_lshlrev_b32_e32 v72, 16, v74
	v_and_b32_e32 v73, 0xffff0000, v74
	v_lshlrev_b32_e32 v74, 16, v75
	v_and_b32_e32 v75, 0xffff0000, v75
	v_lshlrev_b32_e32 v76, 16, v78
	v_and_b32_e32 v77, 0xffff0000, v78
	v_lshlrev_b32_e32 v78, 16, v79
	v_and_b32_e32 v79, 0xffff0000, v79
	v_lshlrev_b32_e32 v96, 16, v98
	v_and_b32_e32 v97, 0xffff0000, v98
	v_lshlrev_b32_e32 v98, 16, v99
	v_and_b32_e32 v99, 0xffff0000, v99
	v_lshlrev_b32_e32 v100, 16, v102
	v_and_b32_e32 v101, 0xffff0000, v102
	v_lshlrev_b32_e32 v102, 16, v103
	v_and_b32_e32 v103, 0xffff0000, v103
	v_lshlrev_b32_e32 v104, 16, v106
	v_and_b32_e32 v105, 0xffff0000, v106
	v_lshlrev_b32_e32 v106, 16, v107
	v_and_b32_e32 v107, 0xffff0000, v107
	v_lshlrev_b32_e32 v108, 16, v110
	v_and_b32_e32 v109, 0xffff0000, v110
	v_lshlrev_b32_e32 v110, 16, v111
	v_and_b32_e32 v111, 0xffff0000, v111
	v_mul_f32_e32 v10, v64, v64
	v_fmac_f32_e32 v10, v65, v65
	v_fmac_f32_e32 v10, v66, v66
	v_fmac_f32_e32 v10, v67, v67
	v_fmac_f32_e32 v10, v68, v68
	v_fmac_f32_e32 v10, v69, v69
	v_fmac_f32_e32 v10, v70, v70
	v_fmac_f32_e32 v10, v71, v71
	v_fmac_f32_e32 v10, v72, v72
	v_fmac_f32_e32 v10, v73, v73
	v_fmac_f32_e32 v10, v74, v74
	v_fmac_f32_e32 v10, v75, v75
	v_fmac_f32_e32 v10, v76, v76
	v_fmac_f32_e32 v10, v77, v77
	v_fmac_f32_e32 v10, v78, v78
	v_fmac_f32_e32 v10, v79, v79
	v_mul_f32_e32 v11, v96, v96
	v_fmac_f32_e32 v11, v97, v97
	v_fmac_f32_e32 v11, v98, v98
	v_fmac_f32_e32 v11, v99, v99
	v_fmac_f32_e32 v11, v100, v100
	v_fmac_f32_e32 v11, v101, v101
	v_fmac_f32_e32 v11, v102, v102
	v_fmac_f32_e32 v11, v103, v103
	v_fmac_f32_e32 v11, v104, v104
	v_fmac_f32_e32 v11, v105, v105
	v_fmac_f32_e32 v11, v106, v106
	v_fmac_f32_e32 v11, v107, v107
	v_fmac_f32_e32 v11, v108, v108
	v_fmac_f32_e32 v11, v109, v109
	v_fmac_f32_e32 v11, v110, v110
	v_fmac_f32_e32 v11, v111, v111
	ds_bpermute_b32 v12, v4, v10
	ds_bpermute_b32 v13, v4, v11
	s_waitcnt lgkmcnt(0)
	v_add_f32_e32 v10, v10, v12
	v_add_f32_e32 v11, v11, v13
	ds_bpermute_b32 v12, v5, v10
	ds_bpermute_b32 v13, v5, v11
	s_waitcnt lgkmcnt(0)
	v_add_f32_e32 v10, v10, v12
	v_add_f32_e32 v11, v11, v13
	ds_bpermute_b32 v12, v6, v10
	ds_bpermute_b32 v13, v6, v11
	s_waitcnt lgkmcnt(0)
	v_add_f32_e32 v10, v10, v12
	v_add_f32_e32 v11, v11, v13
	ds_bpermute_b32 v12, v7, v10
	ds_bpermute_b32 v13, v7, v11
	s_waitcnt lgkmcnt(0)
	v_add_f32_e32 v10, v10, v12
	v_add_f32_e32 v11, v11, v13
	ds_bpermute_b32 v12, v8, v10
	ds_bpermute_b32 v13, v8, v11
	s_waitcnt lgkmcnt(0)
	v_add_f32_e32 v10, v10, v12
	v_add_f32_e32 v11, v11, v13
	ds_bpermute_b32 v12, v9, v10
	ds_bpermute_b32 v13, v9, v11
	s_waitcnt lgkmcnt(0)
	v_add_f32_e32 v10, v10, v12
	v_add_f32_e32 v11, v11, v13
	v_fma_f32 v14, v10, s17, v3
	v_fma_f32 v15, v11, s17, v3
	v_rsq_f32_e32 v14, v14
	v_rsq_f32_e32 v15, v15
	s_nop 0
	v_mul_f32_e32 v64, v64, v14
	v_mul_f32_e32 v65, v65, v14
	v_mul_f32_e32 v66, v66, v14
	v_mul_f32_e32 v67, v67, v14
	v_mul_f32_e32 v68, v68, v14
	v_mul_f32_e32 v69, v69, v14
	v_mul_f32_e32 v70, v70, v14
	v_mul_f32_e32 v71, v71, v14
	v_mul_f32_e32 v72, v72, v14
	v_mul_f32_e32 v73, v73, v14
	v_mul_f32_e32 v74, v74, v14
	v_mul_f32_e32 v75, v75, v14
	v_mul_f32_e32 v76, v76, v14
	v_mul_f32_e32 v77, v77, v14
	v_mul_f32_e32 v78, v78, v14
	v_mul_f32_e32 v79, v79, v14
	v_fmac_f32_e32 v80, v64, v20
	v_fmac_f32_e32 v81, v65, v21
	v_fmac_f32_e32 v82, v66, v22
	v_fmac_f32_e32 v83, v67, v23
	v_fmac_f32_e32 v84, v68, v24
	v_fmac_f32_e32 v85, v69, v25
	v_fmac_f32_e32 v86, v70, v26
	v_fmac_f32_e32 v87, v71, v27
	v_fmac_f32_e32 v88, v72, v28
	v_fmac_f32_e32 v89, v73, v29
	v_fmac_f32_e32 v90, v74, v30
	v_fmac_f32_e32 v91, v75, v31
	v_fmac_f32_e32 v92, v76, v32
	v_fmac_f32_e32 v93, v77, v33
	v_fmac_f32_e32 v94, v78, v34
	v_fmac_f32_e32 v95, v79, v35
	global_store_dwordx4 v1, v[80:83], s[24:25] offset:0 nt
	global_store_dwordx4 v1, v[84:87], s[24:25] offset:1024 nt
	global_store_dwordx4 v1, v[88:91], s[24:25] offset:2048 nt
	global_store_dwordx4 v1, v[92:95], s[24:25] offset:3072 nt
	v_mul_f32_e32 v96, v96, v15
	v_mul_f32_e32 v97, v97, v15
	v_mul_f32_e32 v98, v98, v15
	v_mul_f32_e32 v99, v99, v15
	v_mul_f32_e32 v100, v100, v15
	v_mul_f32_e32 v101, v101, v15
	v_mul_f32_e32 v102, v102, v15
	v_mul_f32_e32 v103, v103, v15
	v_mul_f32_e32 v104, v104, v15
	v_mul_f32_e32 v105, v105, v15
	v_mul_f32_e32 v106, v106, v15
	v_mul_f32_e32 v107, v107, v15
	v_mul_f32_e32 v108, v108, v15
	v_mul_f32_e32 v109, v109, v15
	v_mul_f32_e32 v110, v110, v15
	v_mul_f32_e32 v111, v111, v15
	v_fmac_f32_e32 v112, v96, v20
	v_fmac_f32_e32 v113, v97, v21
	v_fmac_f32_e32 v114, v98, v22
	v_fmac_f32_e32 v115, v99, v23
	v_fmac_f32_e32 v116, v100, v24
	v_fmac_f32_e32 v117, v101, v25
	v_fmac_f32_e32 v118, v102, v26
	v_fmac_f32_e32 v119, v103, v27
	v_fmac_f32_e32 v120, v104, v28
	v_fmac_f32_e32 v121, v105, v29
	v_fmac_f32_e32 v122, v106, v30
	v_fmac_f32_e32 v123, v107, v31
	v_fmac_f32_e32 v124, v108, v32
	v_fmac_f32_e32 v125, v109, v33
	v_fmac_f32_e32 v126, v110, v34
	v_fmac_f32_e32 v127, v111, v35
	global_store_dwordx4 v1, v[112:115], s[32:33] offset:0 nt
	global_store_dwordx4 v1, v[116:119], s[32:33] offset:1024 nt
	global_store_dwordx4 v1, v[120:123], s[32:33] offset:2048 nt
	global_store_dwordx4 v1, v[124:127], s[32:33] offset:3072 nt
	v_mul_f32_e32 v10, v80, v80
	v_fmac_f32_e32 v10, v81, v81
	v_fmac_f32_e32 v10, v82, v82
	v_fmac_f32_e32 v10, v83, v83
	v_fmac_f32_e32 v10, v84, v84
	v_fmac_f32_e32 v10, v85, v85
	v_fmac_f32_e32 v10, v86, v86
	v_fmac_f32_e32 v10, v87, v87
	v_fmac_f32_e32 v10, v88, v88
	v_fmac_f32_e32 v10, v89, v89
	v_fmac_f32_e32 v10, v90, v90
	v_fmac_f32_e32 v10, v91, v91
	v_fmac_f32_e32 v10, v92, v92
	v_fmac_f32_e32 v10, v93, v93
	v_fmac_f32_e32 v10, v94, v94
	v_fmac_f32_e32 v10, v95, v95
	v_mul_f32_e32 v11, v112, v112
	v_fmac_f32_e32 v11, v113, v113
	v_fmac_f32_e32 v11, v114, v114
	v_fmac_f32_e32 v11, v115, v115
	v_fmac_f32_e32 v11, v116, v116
	v_fmac_f32_e32 v11, v117, v117
	v_fmac_f32_e32 v11, v118, v118
	v_fmac_f32_e32 v11, v119, v119
	v_fmac_f32_e32 v11, v120, v120
	v_fmac_f32_e32 v11, v121, v121
	v_fmac_f32_e32 v11, v122, v122
	v_fmac_f32_e32 v11, v123, v123
	v_fmac_f32_e32 v11, v124, v124
	v_fmac_f32_e32 v11, v125, v125
	v_fmac_f32_e32 v11, v126, v126
	v_fmac_f32_e32 v11, v127, v127
	ds_bpermute_b32 v12, v4, v10
	ds_bpermute_b32 v13, v4, v11
	s_waitcnt lgkmcnt(0)
	v_add_f32_e32 v10, v10, v12
	v_add_f32_e32 v11, v11, v13
	ds_bpermute_b32 v12, v5, v10
	ds_bpermute_b32 v13, v5, v11
	s_waitcnt lgkmcnt(0)
	v_add_f32_e32 v10, v10, v12
	v_add_f32_e32 v11, v11, v13
	ds_bpermute_b32 v12, v6, v10
	ds_bpermute_b32 v13, v6, v11
	s_waitcnt lgkmcnt(0)
	v_add_f32_e32 v10, v10, v12
	v_add_f32_e32 v11, v11, v13
	ds_bpermute_b32 v12, v7, v10
	ds_bpermute_b32 v13, v7, v11
	s_waitcnt lgkmcnt(0)
	v_add_f32_e32 v10, v10, v12
	v_add_f32_e32 v11, v11, v13
	ds_bpermute_b32 v12, v8, v10
	ds_bpermute_b32 v13, v8, v11
	s_waitcnt lgkmcnt(0)
	v_add_f32_e32 v10, v10, v12
	v_add_f32_e32 v11, v11, v13
	ds_bpermute_b32 v12, v9, v10
	ds_bpermute_b32 v13, v9, v11
	s_waitcnt lgkmcnt(0)
	v_add_f32_e32 v10, v10, v12
	v_add_f32_e32 v11, v11, v13
	v_fma_f32 v14, v10, s17, v3
	v_fma_f32 v15, v11, s17, v3
	v_rsq_f32_e32 v14, v14
	v_rsq_f32_e32 v15, v15
	s_nop 0
	v_mul_f32_e32 v64, v80, v14
	v_mul_f32_e32 v65, v81, v14
	v_mul_f32_e32 v66, v82, v14
	v_mul_f32_e32 v67, v83, v14
	v_mul_f32_e32 v68, v84, v14
	v_mul_f32_e32 v69, v85, v14
	v_mul_f32_e32 v70, v86, v14
	v_mul_f32_e32 v71, v87, v14
	v_mul_f32_e32 v72, v88, v14
	v_mul_f32_e32 v73, v89, v14
	v_mul_f32_e32 v74, v90, v14
	v_mul_f32_e32 v75, v91, v14
	v_mul_f32_e32 v76, v92, v14
	v_mul_f32_e32 v77, v93, v14
	v_mul_f32_e32 v78, v94, v14
	v_mul_f32_e32 v79, v95, v14
	v_mul_f32_e32 v64, v64, v36
	v_mul_f32_e32 v65, v65, v37
	v_mul_f32_e32 v66, v66, v38
	v_mul_f32_e32 v67, v67, v39
	v_mul_f32_e32 v68, v68, v40
	v_mul_f32_e32 v69, v69, v41
	v_mul_f32_e32 v70, v70, v42
	v_mul_f32_e32 v71, v71, v43
	v_mul_f32_e32 v72, v72, v44
	v_mul_f32_e32 v73, v73, v45
	v_mul_f32_e32 v74, v74, v46
	v_mul_f32_e32 v75, v75, v47
	v_mul_f32_e32 v76, v76, v48
	v_mul_f32_e32 v77, v77, v49
	v_mul_f32_e32 v78, v78, v50
	v_mul_f32_e32 v79, v79, v51
	v_cvt_pk_bf16_f32 v64, v64, v65
	v_cvt_pk_bf16_f32 v65, v66, v67
	v_cvt_pk_bf16_f32 v68, v68, v69
	v_cvt_pk_bf16_f32 v69, v70, v71
	v_cvt_pk_bf16_f32 v72, v72, v73
	v_cvt_pk_bf16_f32 v73, v74, v75
	v_cvt_pk_bf16_f32 v76, v76, v77
	v_cvt_pk_bf16_f32 v77, v78, v79
	global_store_dwordx2 v2, v[64:65], s[26:27] offset:0
	global_store_dwordx2 v2, v[68:69], s[26:27] offset:512
	global_store_dwordx2 v2, v[72:73], s[26:27] offset:1024
	global_store_dwordx2 v2, v[76:77], s[26:27] offset:1536
	v_mul_f32_e32 v96, v112, v15
	v_mul_f32_e32 v97, v113, v15
	v_mul_f32_e32 v98, v114, v15
	v_mul_f32_e32 v99, v115, v15
	v_mul_f32_e32 v100, v116, v15
	v_mul_f32_e32 v101, v117, v15
	v_mul_f32_e32 v102, v118, v15
	v_mul_f32_e32 v103, v119, v15
	v_mul_f32_e32 v104, v120, v15
	v_mul_f32_e32 v105, v121, v15
	v_mul_f32_e32 v106, v122, v15
	v_mul_f32_e32 v107, v123, v15
	v_mul_f32_e32 v108, v124, v15
	v_mul_f32_e32 v109, v125, v15
	v_mul_f32_e32 v110, v126, v15
	v_mul_f32_e32 v111, v127, v15
	v_mul_f32_e32 v96, v96, v36
	v_mul_f32_e32 v97, v97, v37
	v_mul_f32_e32 v98, v98, v38
	v_mul_f32_e32 v99, v99, v39
	v_mul_f32_e32 v100, v100, v40
	v_mul_f32_e32 v101, v101, v41
	v_mul_f32_e32 v102, v102, v42
	v_mul_f32_e32 v103, v103, v43
	v_mul_f32_e32 v104, v104, v44
	v_mul_f32_e32 v105, v105, v45
	v_mul_f32_e32 v106, v106, v46
	v_mul_f32_e32 v107, v107, v47
	v_mul_f32_e32 v108, v108, v48
	v_mul_f32_e32 v109, v109, v49
	v_mul_f32_e32 v110, v110, v50
	v_mul_f32_e32 v111, v111, v51
	v_cvt_pk_bf16_f32 v96, v96, v97
	v_cvt_pk_bf16_f32 v97, v98, v99
	v_cvt_pk_bf16_f32 v100, v100, v101
	v_cvt_pk_bf16_f32 v101, v102, v103
	v_cvt_pk_bf16_f32 v104, v104, v105
	v_cvt_pk_bf16_f32 v105, v106, v107
	v_cvt_pk_bf16_f32 v108, v108, v109
	v_cvt_pk_bf16_f32 v109, v110, v111
	global_store_dwordx2 v2, v[96:97], s[34:35] offset:0
	global_store_dwordx2 v2, v[100:101], s[34:35] offset:512
	global_store_dwordx2 v2, v[104:105], s[34:35] offset:1024
	global_store_dwordx2 v2, v[108:109], s[34:35] offset:1536
	s_waitcnt vmcnt(16)
	v_lshlrev_b32_e32 v128, 16, v130
	v_and_b32_e32 v129, 0xffff0000, v130
	v_lshlrev_b32_e32 v130, 16, v131
	v_and_b32_e32 v131, 0xffff0000, v131
	v_lshlrev_b32_e32 v132, 16, v134
	v_and_b32_e32 v133, 0xffff0000, v134
	v_lshlrev_b32_e32 v134, 16, v135
	v_and_b32_e32 v135, 0xffff0000, v135
	v_lshlrev_b32_e32 v136, 16, v138
	v_and_b32_e32 v137, 0xffff0000, v138
	v_lshlrev_b32_e32 v138, 16, v139
	v_and_b32_e32 v139, 0xffff0000, v139
	v_lshlrev_b32_e32 v140, 16, v142
	v_and_b32_e32 v141, 0xffff0000, v142
	v_lshlrev_b32_e32 v142, 16, v143
	v_and_b32_e32 v143, 0xffff0000, v143
	v_lshlrev_b32_e32 v160, 16, v162
	v_and_b32_e32 v161, 0xffff0000, v162
	v_lshlrev_b32_e32 v162, 16, v163
	v_and_b32_e32 v163, 0xffff0000, v163
	v_lshlrev_b32_e32 v164, 16, v166
	v_and_b32_e32 v165, 0xffff0000, v166
	v_lshlrev_b32_e32 v166, 16, v167
	v_and_b32_e32 v167, 0xffff0000, v167
	v_lshlrev_b32_e32 v168, 16, v170
	v_and_b32_e32 v169, 0xffff0000, v170
	v_lshlrev_b32_e32 v170, 16, v171
	v_and_b32_e32 v171, 0xffff0000, v171
	v_lshlrev_b32_e32 v172, 16, v174
	v_and_b32_e32 v173, 0xffff0000, v174
	v_lshlrev_b32_e32 v174, 16, v175
	v_and_b32_e32 v175, 0xffff0000, v175
	v_mul_f32_e32 v10, v128, v128
	v_fmac_f32_e32 v10, v129, v129
	v_fmac_f32_e32 v10, v130, v130
	v_fmac_f32_e32 v10, v131, v131
	v_fmac_f32_e32 v10, v132, v132
	v_fmac_f32_e32 v10, v133, v133
	v_fmac_f32_e32 v10, v134, v134
	v_fmac_f32_e32 v10, v135, v135
	v_fmac_f32_e32 v10, v136, v136
	v_fmac_f32_e32 v10, v137, v137
	v_fmac_f32_e32 v10, v138, v138
	v_fmac_f32_e32 v10, v139, v139
	v_fmac_f32_e32 v10, v140, v140
	v_fmac_f32_e32 v10, v141, v141
	v_fmac_f32_e32 v10, v142, v142
	v_fmac_f32_e32 v10, v143, v143
	v_mul_f32_e32 v11, v160, v160
	v_fmac_f32_e32 v11, v161, v161
	v_fmac_f32_e32 v11, v162, v162
	v_fmac_f32_e32 v11, v163, v163
	v_fmac_f32_e32 v11, v164, v164
	v_fmac_f32_e32 v11, v165, v165
	v_fmac_f32_e32 v11, v166, v166
	v_fmac_f32_e32 v11, v167, v167
	v_fmac_f32_e32 v11, v168, v168
	v_fmac_f32_e32 v11, v169, v169
	v_fmac_f32_e32 v11, v170, v170
	v_fmac_f32_e32 v11, v171, v171
	v_fmac_f32_e32 v11, v172, v172
	v_fmac_f32_e32 v11, v173, v173
	v_fmac_f32_e32 v11, v174, v174
	v_fmac_f32_e32 v11, v175, v175
	ds_bpermute_b32 v12, v4, v10
	ds_bpermute_b32 v13, v4, v11
	s_waitcnt lgkmcnt(0)
	v_add_f32_e32 v10, v10, v12
	v_add_f32_e32 v11, v11, v13
	ds_bpermute_b32 v12, v5, v10
	ds_bpermute_b32 v13, v5, v11
	s_waitcnt lgkmcnt(0)
	v_add_f32_e32 v10, v10, v12
	v_add_f32_e32 v11, v11, v13
	ds_bpermute_b32 v12, v6, v10
	ds_bpermute_b32 v13, v6, v11
	s_waitcnt lgkmcnt(0)
	v_add_f32_e32 v10, v10, v12
	v_add_f32_e32 v11, v11, v13
	ds_bpermute_b32 v12, v7, v10
	ds_bpermute_b32 v13, v7, v11
	s_waitcnt lgkmcnt(0)
	v_add_f32_e32 v10, v10, v12
	v_add_f32_e32 v11, v11, v13
	ds_bpermute_b32 v12, v8, v10
	ds_bpermute_b32 v13, v8, v11
	s_waitcnt lgkmcnt(0)
	v_add_f32_e32 v10, v10, v12
	v_add_f32_e32 v11, v11, v13
	ds_bpermute_b32 v12, v9, v10
	ds_bpermute_b32 v13, v9, v11
	s_waitcnt lgkmcnt(0)
	v_add_f32_e32 v10, v10, v12
	v_add_f32_e32 v11, v11, v13
	v_fma_f32 v14, v10, s17, v3
	v_fma_f32 v15, v11, s17, v3
	v_rsq_f32_e32 v14, v14
	v_rsq_f32_e32 v15, v15
	s_nop 0
	v_mul_f32_e32 v128, v128, v14
	v_mul_f32_e32 v129, v129, v14
	v_mul_f32_e32 v130, v130, v14
	v_mul_f32_e32 v131, v131, v14
	v_mul_f32_e32 v132, v132, v14
	v_mul_f32_e32 v133, v133, v14
	v_mul_f32_e32 v134, v134, v14
	v_mul_f32_e32 v135, v135, v14
	v_mul_f32_e32 v136, v136, v14
	v_mul_f32_e32 v137, v137, v14
	v_mul_f32_e32 v138, v138, v14
	v_mul_f32_e32 v139, v139, v14
	v_mul_f32_e32 v140, v140, v14
	v_mul_f32_e32 v141, v141, v14
	v_mul_f32_e32 v142, v142, v14
	v_mul_f32_e32 v143, v143, v14
	v_fmac_f32_e32 v144, v128, v20
	v_fmac_f32_e32 v145, v129, v21
	v_fmac_f32_e32 v146, v130, v22
	v_fmac_f32_e32 v147, v131, v23
	v_fmac_f32_e32 v148, v132, v24
	v_fmac_f32_e32 v149, v133, v25
	v_fmac_f32_e32 v150, v134, v26
	v_fmac_f32_e32 v151, v135, v27
	v_fmac_f32_e32 v152, v136, v28
	v_fmac_f32_e32 v153, v137, v29
	v_fmac_f32_e32 v154, v138, v30
	v_fmac_f32_e32 v155, v139, v31
	v_fmac_f32_e32 v156, v140, v32
	v_fmac_f32_e32 v157, v141, v33
	v_fmac_f32_e32 v158, v142, v34
	v_fmac_f32_e32 v159, v143, v35
	global_store_dwordx4 v1, v[144:147], s[40:41] offset:0 nt
	global_store_dwordx4 v1, v[148:151], s[40:41] offset:1024 nt
	global_store_dwordx4 v1, v[152:155], s[40:41] offset:2048 nt
	global_store_dwordx4 v1, v[156:159], s[40:41] offset:3072 nt
	v_mul_f32_e32 v160, v160, v15
	v_mul_f32_e32 v161, v161, v15
	v_mul_f32_e32 v162, v162, v15
	v_mul_f32_e32 v163, v163, v15
	v_mul_f32_e32 v164, v164, v15
	v_mul_f32_e32 v165, v165, v15
	v_mul_f32_e32 v166, v166, v15
	v_mul_f32_e32 v167, v167, v15
	v_mul_f32_e32 v168, v168, v15
	v_mul_f32_e32 v169, v169, v15
	v_mul_f32_e32 v170, v170, v15
	v_mul_f32_e32 v171, v171, v15
	v_mul_f32_e32 v172, v172, v15
	v_mul_f32_e32 v173, v173, v15
	v_mul_f32_e32 v174, v174, v15
	v_mul_f32_e32 v175, v175, v15
	v_fmac_f32_e32 v176, v160, v20
	v_fmac_f32_e32 v177, v161, v21
	v_fmac_f32_e32 v178, v162, v22
	v_fmac_f32_e32 v179, v163, v23
	v_fmac_f32_e32 v180, v164, v24
	v_fmac_f32_e32 v181, v165, v25
	v_fmac_f32_e32 v182, v166, v26
	v_fmac_f32_e32 v183, v167, v27
	v_fmac_f32_e32 v184, v168, v28
	v_fmac_f32_e32 v185, v169, v29
	v_fmac_f32_e32 v186, v170, v30
	v_fmac_f32_e32 v187, v171, v31
	v_fmac_f32_e32 v188, v172, v32
	v_fmac_f32_e32 v189, v173, v33
	v_fmac_f32_e32 v190, v174, v34
	v_fmac_f32_e32 v191, v175, v35
	global_store_dwordx4 v1, v[176:179], s[48:49] offset:0 nt
	global_store_dwordx4 v1, v[180:183], s[48:49] offset:1024 nt
	global_store_dwordx4 v1, v[184:187], s[48:49] offset:2048 nt
	global_store_dwordx4 v1, v[188:191], s[48:49] offset:3072 nt
	v_mul_f32_e32 v10, v144, v144
	v_fmac_f32_e32 v10, v145, v145
	v_fmac_f32_e32 v10, v146, v146
	v_fmac_f32_e32 v10, v147, v147
	v_fmac_f32_e32 v10, v148, v148
	v_fmac_f32_e32 v10, v149, v149
	v_fmac_f32_e32 v10, v150, v150
	v_fmac_f32_e32 v10, v151, v151
	v_fmac_f32_e32 v10, v152, v152
	v_fmac_f32_e32 v10, v153, v153
	v_fmac_f32_e32 v10, v154, v154
	v_fmac_f32_e32 v10, v155, v155
	v_fmac_f32_e32 v10, v156, v156
	v_fmac_f32_e32 v10, v157, v157
	v_fmac_f32_e32 v10, v158, v158
	v_fmac_f32_e32 v10, v159, v159
	v_mul_f32_e32 v11, v176, v176
	v_fmac_f32_e32 v11, v177, v177
	v_fmac_f32_e32 v11, v178, v178
	v_fmac_f32_e32 v11, v179, v179
	v_fmac_f32_e32 v11, v180, v180
	v_fmac_f32_e32 v11, v181, v181
	v_fmac_f32_e32 v11, v182, v182
	v_fmac_f32_e32 v11, v183, v183
	v_fmac_f32_e32 v11, v184, v184
	v_fmac_f32_e32 v11, v185, v185
	v_fmac_f32_e32 v11, v186, v186
	v_fmac_f32_e32 v11, v187, v187
	v_fmac_f32_e32 v11, v188, v188
	v_fmac_f32_e32 v11, v189, v189
	v_fmac_f32_e32 v11, v190, v190
	v_fmac_f32_e32 v11, v191, v191
	ds_bpermute_b32 v12, v4, v10
	ds_bpermute_b32 v13, v4, v11
	s_waitcnt lgkmcnt(0)
	v_add_f32_e32 v10, v10, v12
	v_add_f32_e32 v11, v11, v13
	ds_bpermute_b32 v12, v5, v10
	ds_bpermute_b32 v13, v5, v11
	s_waitcnt lgkmcnt(0)
	v_add_f32_e32 v10, v10, v12
	v_add_f32_e32 v11, v11, v13
	ds_bpermute_b32 v12, v6, v10
	ds_bpermute_b32 v13, v6, v11
	s_waitcnt lgkmcnt(0)
	v_add_f32_e32 v10, v10, v12
	v_add_f32_e32 v11, v11, v13
	ds_bpermute_b32 v12, v7, v10
	ds_bpermute_b32 v13, v7, v11
	s_waitcnt lgkmcnt(0)
	v_add_f32_e32 v10, v10, v12
	v_add_f32_e32 v11, v11, v13
	ds_bpermute_b32 v12, v8, v10
	ds_bpermute_b32 v13, v8, v11
	s_waitcnt lgkmcnt(0)
	v_add_f32_e32 v10, v10, v12
	v_add_f32_e32 v11, v11, v13
	ds_bpermute_b32 v12, v9, v10
	ds_bpermute_b32 v13, v9, v11
	s_waitcnt lgkmcnt(0)
	v_add_f32_e32 v10, v10, v12
	v_add_f32_e32 v11, v11, v13
	v_fma_f32 v14, v10, s17, v3
	v_fma_f32 v15, v11, s17, v3
	v_rsq_f32_e32 v14, v14
	v_rsq_f32_e32 v15, v15
	s_nop 0
	v_mul_f32_e32 v128, v144, v14
	v_mul_f32_e32 v129, v145, v14
	v_mul_f32_e32 v130, v146, v14
	v_mul_f32_e32 v131, v147, v14
	v_mul_f32_e32 v132, v148, v14
	v_mul_f32_e32 v133, v149, v14
	v_mul_f32_e32 v134, v150, v14
	v_mul_f32_e32 v135, v151, v14
	v_mul_f32_e32 v136, v152, v14
	v_mul_f32_e32 v137, v153, v14
	v_mul_f32_e32 v138, v154, v14
	v_mul_f32_e32 v139, v155, v14
	v_mul_f32_e32 v140, v156, v14
	v_mul_f32_e32 v141, v157, v14
	v_mul_f32_e32 v142, v158, v14
	v_mul_f32_e32 v143, v159, v14
	v_mul_f32_e32 v128, v128, v36
	v_mul_f32_e32 v129, v129, v37
	v_mul_f32_e32 v130, v130, v38
	v_mul_f32_e32 v131, v131, v39
	v_mul_f32_e32 v132, v132, v40
	v_mul_f32_e32 v133, v133, v41
	v_mul_f32_e32 v134, v134, v42
	v_mul_f32_e32 v135, v135, v43
	v_mul_f32_e32 v136, v136, v44
	v_mul_f32_e32 v137, v137, v45
	v_mul_f32_e32 v138, v138, v46
	v_mul_f32_e32 v139, v139, v47
	v_mul_f32_e32 v140, v140, v48
	v_mul_f32_e32 v141, v141, v49
	v_mul_f32_e32 v142, v142, v50
	v_mul_f32_e32 v143, v143, v51
	v_cvt_pk_bf16_f32 v128, v128, v129
	v_cvt_pk_bf16_f32 v129, v130, v131
	v_cvt_pk_bf16_f32 v132, v132, v133
	v_cvt_pk_bf16_f32 v133, v134, v135
	v_cvt_pk_bf16_f32 v136, v136, v137
	v_cvt_pk_bf16_f32 v137, v138, v139
	v_cvt_pk_bf16_f32 v140, v140, v141
	v_cvt_pk_bf16_f32 v141, v142, v143
	global_store_dwordx2 v2, v[128:129], s[42:43] offset:0
	global_store_dwordx2 v2, v[132:133], s[42:43] offset:512
	global_store_dwordx2 v2, v[136:137], s[42:43] offset:1024
	global_store_dwordx2 v2, v[140:141], s[42:43] offset:1536
	v_mul_f32_e32 v160, v176, v15
	v_mul_f32_e32 v161, v177, v15
	v_mul_f32_e32 v162, v178, v15
	v_mul_f32_e32 v163, v179, v15
	v_mul_f32_e32 v164, v180, v15
	v_mul_f32_e32 v165, v181, v15
	v_mul_f32_e32 v166, v182, v15
	v_mul_f32_e32 v167, v183, v15
	v_mul_f32_e32 v168, v184, v15
	v_mul_f32_e32 v169, v185, v15
	v_mul_f32_e32 v170, v186, v15
	v_mul_f32_e32 v171, v187, v15
	v_mul_f32_e32 v172, v188, v15
	v_mul_f32_e32 v173, v189, v15
	v_mul_f32_e32 v174, v190, v15
	v_mul_f32_e32 v175, v191, v15
	v_mul_f32_e32 v160, v160, v36
	v_mul_f32_e32 v161, v161, v37
	v_mul_f32_e32 v162, v162, v38
	v_mul_f32_e32 v163, v163, v39
	v_mul_f32_e32 v164, v164, v40
	v_mul_f32_e32 v165, v165, v41
	v_mul_f32_e32 v166, v166, v42
	v_mul_f32_e32 v167, v167, v43
	v_mul_f32_e32 v168, v168, v44
	v_mul_f32_e32 v169, v169, v45
	v_mul_f32_e32 v170, v170, v46
	v_mul_f32_e32 v171, v171, v47
	v_mul_f32_e32 v172, v172, v48
	v_mul_f32_e32 v173, v173, v49
	v_mul_f32_e32 v174, v174, v50
	v_mul_f32_e32 v175, v175, v51
	v_cvt_pk_bf16_f32 v160, v160, v161
	v_cvt_pk_bf16_f32 v161, v162, v163
	v_cvt_pk_bf16_f32 v164, v164, v165
	v_cvt_pk_bf16_f32 v165, v166, v167
	v_cvt_pk_bf16_f32 v168, v168, v169
	v_cvt_pk_bf16_f32 v169, v170, v171
	v_cvt_pk_bf16_f32 v172, v172, v173
	v_cvt_pk_bf16_f32 v173, v174, v175
	global_store_dwordx2 v2, v[160:161], s[50:51] offset:0
	global_store_dwordx2 v2, v[164:165], s[50:51] offset:512
	global_store_dwordx2 v2, v[168:169], s[50:51] offset:1024
	global_store_dwordx2 v2, v[172:173], s[50:51] offset:1536
	v_add_f32_e32 v208, v208, v212
	v_add_f32_e32 v209, v209, v213
	v_add_f32_e32 v210, v210, v214
	v_add_f32_e32 v211, v211, v215
	v_readfirstlane_b32 s18, v0
	s_lshr_b32 s18, s18, 6
	s_lshl_b32 s19, s18, 2
	s_and_b32 s52, s18, 4
	s_lshl_b32 s52, s52, 2
	v_mov_b32_e32 v16, s19
	v_mov_b32_e32 v17, s52
	v_mul_f32_e32 v10, v208, v208
	v_fmac_f32_e32 v10, v209, v209
	v_fmac_f32_e32 v10, v210, v210
	v_fmac_f32_e32 v10, v211, v211
	ds_bpermute_b32 v11, v4, v10
	s_waitcnt lgkmcnt(0)
	v_add_f32_e32 v10, v10, v11
	ds_bpermute_b32 v11, v5, v10
	s_waitcnt lgkmcnt(0)
	v_add_f32_e32 v10, v10, v11
	ds_bpermute_b32 v11, v6, v10
	s_waitcnt lgkmcnt(0)
	v_add_f32_e32 v10, v10, v11
	ds_bpermute_b32 v11, v7, v10
	s_waitcnt lgkmcnt(0)
	v_add_f32_e32 v10, v10, v11
	ds_bpermute_b32 v11, v8, v10
	s_waitcnt lgkmcnt(0)
	v_add_f32_e32 v10, v10, v11
	ds_bpermute_b32 v11, v9, v10
	s_waitcnt lgkmcnt(0)
	v_add_f32_e32 v10, v10, v11
	ds_write_b32 v16, v10 offset:0
	s_waitcnt lgkmcnt(0)
	s_barrier
	ds_read_b128 v[12:15], v17 offset:0
	s_waitcnt lgkmcnt(0)
	v_add_f32_e32 v12, v12, v13
	v_add_f32_e32 v14, v14, v15
	v_add_f32_e32 v10, v12, v14
	v_fma_f32 v11, v10, s17, v3
	v_rsq_f32_e32 v11, v11
	s_nop 0
	v_mul_f32_e32 v208, v208, v11
	v_mul_f32_e32 v209, v209, v11
	v_mul_f32_e32 v210, v210, v11
	v_mul_f32_e32 v211, v211, v11
	v_fmac_f32_e32 v240, v208, v244
	v_fmac_f32_e32 v241, v209, v245
	v_fmac_f32_e32 v242, v210, v246
	v_fmac_f32_e32 v243, v211, v247
	s_lshl_b32 s18, s54, 12
	s_add_u32 s18, s18, s55
	s_add_u32 s56, s4, s18
	s_addc_u32 s57, s5, 0
	s_add_u32 s56, s56, 0x4000000
	s_addc_u32 s57, s57, 0
	global_store_dwordx4 v1, v[240:243], s[56:57]
	v_mul_f32_e32 v10, v240, v240
	v_fmac_f32_e32 v10, v241, v241
	v_fmac_f32_e32 v10, v242, v242
	v_fmac_f32_e32 v10, v243, v243
	ds_bpermute_b32 v11, v4, v10
	s_waitcnt lgkmcnt(0)
	v_add_f32_e32 v10, v10, v11
	ds_bpermute_b32 v11, v5, v10
	s_waitcnt lgkmcnt(0)
	v_add_f32_e32 v10, v10, v11
	ds_bpermute_b32 v11, v6, v10
	s_waitcnt lgkmcnt(0)
	v_add_f32_e32 v10, v10, v11
	ds_bpermute_b32 v11, v7, v10
	s_waitcnt lgkmcnt(0)
	v_add_f32_e32 v10, v10, v11
	ds_bpermute_b32 v11, v8, v10
	s_waitcnt lgkmcnt(0)
	v_add_f32_e32 v10, v10, v11
	ds_bpermute_b32 v11, v9, v10
	s_waitcnt lgkmcnt(0)
	v_add_f32_e32 v10, v10, v11
	ds_write_b32 v16, v10 offset:64
	s_waitcnt lgkmcnt(0)
	s_barrier
	ds_read_b128 v[12:15], v17 offset:64
	s_waitcnt lgkmcnt(0)
	v_add_f32_e32 v12, v12, v13
	v_add_f32_e32 v14, v14, v15
	v_add_f32_e32 v10, v12, v14
	v_fma_f32 v11, v10, s17, v3
	v_rsq_f32_e32 v11, v11
	s_nop 0
	v_mul_f32_e32 v208, v240, v11
	v_mul_f32_e32 v209, v241, v11
	v_mul_f32_e32 v210, v242, v11
	v_mul_f32_e32 v211, v243, v11
	v_mul_f32_e32 v208, v208, v248
	v_mul_f32_e32 v209, v209, v249
	v_mul_f32_e32 v210, v210, v250
	v_mul_f32_e32 v211, v211, v251
	v_cvt_pk_bf16_f32 v208, v208, v209
	v_cvt_pk_bf16_f32 v209, v210, v211
	s_lshl_b32 s18, s54, 11
	s_lshr_b32 s19, s55, 1
	s_add_u32 s18, s18, s19
	s_add_u32 s56, s6, s18
	s_addc_u32 s57, s7, 0
	s_add_u32 s56, s56, 0x5100000
	s_addc_u32 s57, s57, 0
	global_store_dwordx2 v2, v[208:209], s[56:57]

_Z10fwd_kernelILi7ELi8EEv4Args:
	s_load_dword s3, s[0:1], 0xe8
	s_load_dwordx4 s[4:7], s[0:1], 0xd0
	s_load_dwordx2 s[8:9], s[0:1], 0xb8
	s_load_dwordx2 s[10:11], s[0:1], 0xa0
	s_waitcnt lgkmcnt(0)
	s_cmp_lg_u32 s3, 0x100
	s_cbranch_scc1 .Lrows7_orig
	s_add_u32 s10, s10, 0x1000
	s_addc_u32 s11, s11, 0
	v_readfirstlane_b32 s16, v0
	s_lshr_b32 s16, s16, 6
	s_lshl_b32 s18, s2, 3
	s_add_u32 s16, s16, s18
	s_mov_b32 s17, 0x3a800000
	v_mov_b32_e32 v3, 0x358637bd
	v_and_b32_e32 v10, 63, v0
	v_lshlrev_b32_e32 v1, 4, v10
	v_lshlrev_b32_e32 v2, 3, v10
	v_xor_b32_e32 v4, 1, v10
	v_xor_b32_e32 v5, 2, v10
	v_xor_b32_e32 v6, 4, v10
	v_xor_b32_e32 v7, 8, v10
	v_xor_b32_e32 v8, 16, v10
	v_xor_b32_e32 v9, 32, v10
	v_lshlrev_b32_e32 v4, 2, v4
	v_lshlrev_b32_e32 v5, 2, v5
	v_lshlrev_b32_e32 v6, 2, v6
	v_lshlrev_b32_e32 v7, 2, v7
	v_lshlrev_b32_e32 v8, 2, v8
	v_lshlrev_b32_e32 v9, 2, v9
	global_load_dwordx4 v[20:23], v1, s[8:9] offset:0
	global_load_dwordx4 v[24:27], v1, s[8:9] offset:1024
	global_load_dwordx4 v[28:31], v1, s[8:9] offset:2048
	global_load_dwordx4 v[32:35], v1, s[8:9] offset:3072
	global_load_dwordx4 v[36:39], v1, s[10:11] offset:0
	global_load_dwordx4 v[40:43], v1, s[10:11] offset:1024
	global_load_dwordx4 v[44:47], v1, s[10:11] offset:2048
	global_load_dwordx4 v[48:51], v1, s[10:11] offset:3072
	s_lshr_b32 s54, s16, 2
	s_and_b32 s55, s16, 3
	s_lshl_b32 s55, s55, 10
	s_lshl_b32 s18, s54, 12
	s_add_u32 s18, s18, s55
	s_add_u32 s56, s6, s18
	s_addc_u32 s57, s7, 0
	s_add_u32 s56, s56, 0x100000
	s_addc_u32 s57, s57, 0
	global_load_dwordx4 v[208:211], v1, s[56:57]
	s_add_u32 s56, s56, 0x200000
	s_addc_u32 s57, s57, 0
	global_load_dwordx4 v[212:215], v1, s[56:57]
	s_add_u32 s56, s56, 0x200000
	s_addc_u32 s57, s57, 0
	global_load_dwordx4 v[216:219], v1, s[56:57]
	s_add_u32 s56, s56, 0x200000
	s_addc_u32 s57, s57, 0
	global_load_dwordx4 v[220:223], v1, s[56:57]
	s_add_u32 s56, s56, 0x200000
	s_addc_u32 s57, s57, 0
	global_load_dwordx4 v[224:227], v1, s[56:57]
	s_add_u32 s56, s56, 0x200000
	s_addc_u32 s57, s57, 0
	global_load_dwordx4 v[228:231], v1, s[56:57]
	s_add_u32 s56, s56, 0x200000
	s_addc_u32 s57, s57, 0
	global_load_dwordx4 v[232:235], v1, s[56:57]
	s_add_u32 s56, s56, 0x200000
	s_addc_u32 s57, s57, 0
	global_load_dwordx4 v[236:239], v1, s[56:57]
	s_add_u32 s56, s4, s18
	s_addc_u32 s57, s5, 0
	s_add_u32 s56, s56, 0x4000000
	s_addc_u32 s57, s57, 0
	global_load_dwordx4 v[240:243], v1, s[56:57]
	s_add_u32 s56, s8, s55
	s_addc_u32 s57, s9, 0
	global_load_dwordx4 v[244:247], v1, s[56:57]
	s_add_u32 s56, s10, s55
	s_addc_u32 s57, s11, 0
	global_load_dwordx4 v[248:251], v1, s[56:57]
	s_add_u32 s53, s16, 0x0
	s_lshl_b32 s18, s53, 12
	s_lshl_b32 s19, s53, 11
	s_add_u32 s20, s4, s18
	s_addc_u32 s21, s5, 0
	s_add_u32 s22, s6, s19
	s_addc_u32 s23, s7, 0
	s_add_u32 s22, s22, 0x5200000
	s_addc_u32 s23, s23, 0
	s_add_u32 s24, s4, s18
	s_addc_u32 s25, s5, 0
	s_add_u32 s26, s6, s19
	s_addc_u32 s27, s7, 0
	s_add_u32 s26, s26, 0x3100000
	s_addc_u32 s27, s27, 0
	global_load_dwordx2 v[66:67], v2, s[22:23] offset:0 nt
	global_load_dwordx2 v[70:71], v2, s[22:23] offset:512 nt
	global_load_dwordx2 v[74:75], v2, s[22:23] offset:1024 nt
	global_load_dwordx2 v[78:79], v2, s[22:23] offset:1536 nt
	global_load_dwordx4 v[80:83], v1, s[20:21] offset:0 nt
	global_load_dwordx4 v[84:87], v1, s[20:21] offset:1024 nt
	global_load_dwordx4 v[88:91], v1, s[20:21] offset:2048 nt
	global_load_dwordx4 v[92:95], v1, s[20:21] offset:3072 nt
	s_add_u32 s53, s16, 0x800
	s_lshl_b32 s18, s53, 12
	s_lshl_b32 s19, s53, 11
	s_add_u32 s28, s4, s18
	s_addc_u32 s29, s5, 0
	s_add_u32 s30, s6, s19
	s_addc_u32 s31, s7, 0
	s_add_u32 s30, s30, 0x5200000
	s_addc_u32 s31, s31, 0
	s_add_u32 s32, s4, s18
	s_addc_u32 s33, s5, 0
	s_add_u32 s34, s6, s19
	s_addc_u32 s35, s7, 0
	s_add_u32 s34, s34, 0x3100000
	s_addc_u32 s35, s35, 0
	global_load_dwordx2 v[98:99], v2, s[30:31] offset:0 nt
	global_load_dwordx2 v[102:103], v2, s[30:31] offset:512 nt
	global_load_dwordx2 v[106:107], v2, s[30:31] offset:1024 nt
	global_load_dwordx2 v[110:111], v2, s[30:31] offset:1536 nt
	global_load_dwordx4 v[112:115], v1, s[28:29] offset:0 nt
	global_load_dwordx4 v[116:119], v1, s[28:29] offset:1024 nt
	global_load_dwordx4 v[120:123], v1, s[28:29] offset:2048 nt
	global_load_dwordx4 v[124:127], v1, s[28:29] offset:3072 nt
	s_add_u32 s53, s16, 0x1000
	s_lshl_b32 s18, s53, 12
	s_lshl_b32 s19, s53, 11
	s_add_u32 s36, s4, s18
	s_addc_u32 s37, s5, 0
	s_add_u32 s38, s6, s19
	s_addc_u32 s39, s7, 0
	s_add_u32 s38, s38, 0x5200000
	s_addc_u32 s39, s39, 0
	s_add_u32 s40, s4, s18
	s_addc_u32 s41, s5, 0
	s_add_u32 s42, s6, s19
	s_addc_u32 s43, s7, 0
	s_add_u32 s42, s42, 0x3100000
	s_addc_u32 s43, s43, 0
	global_load_dwordx2 v[130:131], v2, s[38:39] offset:0 nt
	global_load_dwordx2 v[134:135], v2, s[38:39] offset:512 nt
	global_load_dwordx2 v[138:139], v2, s[38:39] offset:1024 nt
	global_load_dwordx2 v[142:143], v2, s[38:39] offset:1536 nt
	global_load_dwordx4 v[144:147], v1, s[36:37] offset:0 nt
	global_load_dwordx4 v[148:151], v1, s[36:37] offset:1024 nt
	global_load_dwordx4 v[152:155], v1, s[36:37] offset:2048 nt
	global_load_dwordx4 v[156:159], v1, s[36:37] offset:3072 nt
	s_add_u32 s53, s16, 0x1800
	s_lshl_b32 s18, s53, 12
	s_lshl_b32 s19, s53, 11
	s_add_u32 s44, s4, s18
	s_addc_u32 s45, s5, 0
	s_add_u32 s46, s6, s19
	s_addc_u32 s47, s7, 0
	s_add_u32 s46, s46, 0x5200000
	s_addc_u32 s47, s47, 0
	s_add_u32 s48, s4, s18
	s_addc_u32 s49, s5, 0
	s_add_u32 s50, s6, s19
	s_addc_u32 s51, s7, 0
	s_add_u32 s50, s50, 0x3100000
	s_addc_u32 s51, s51, 0
	global_load_dwordx2 v[162:163], v2, s[46:47] offset:0 nt
	global_load_dwordx2 v[166:167], v2, s[46:47] offset:512 nt
	global_load_dwordx2 v[170:171], v2, s[46:47] offset:1024 nt
	global_load_dwordx2 v[174:175], v2, s[46:47] offset:1536 nt
	global_load_dwordx4 v[176:179], v1, s[44:45] offset:0 nt
	global_load_dwordx4 v[180:183], v1, s[44:45] offset:1024 nt
	global_load_dwordx4 v[184:187], v1, s[44:45] offset:2048 nt
	global_load_dwordx4 v[188:191], v1, s[44:45] offset:3072 nt
	s_waitcnt vmcnt(16)
	v_lshlrev_b32_e32 v64, 16, v66
	v_and_b32_e32 v65, 0xffff0000, v66
	v_lshlrev_b32_e32 v66, 16, v67
	v_and_b32_e32 v67, 0xffff0000, v67
	v_lshlrev_b32_e32 v68, 16, v70
	v_and_b32_e32 v69, 0xffff0000, v70
	v_lshlrev_b32_e32 v70, 16, v71
	v_and_b32_e32 v71, 0xffff0000, v71
	v_lshlrev_b32_e32 v72, 16, v74
	v_and_b32_e32 v73, 0xffff0000, v74
	v_lshlrev_b32_e32 v74, 16, v75
	v_and_b32_e32 v75, 0xffff0000, v75
	v_lshlrev_b32_e32 v76, 16, v78
	v_and_b32_e32 v77, 0xffff0000, v78
	v_lshlrev_b32_e32 v78, 16, v79
	v_and_b32_e32 v79, 0xffff0000, v79
	v_lshlrev_b32_e32 v96, 16, v98
	v_and_b32_e32 v97, 0xffff0000, v98
	v_lshlrev_b32_e32 v98, 16, v99
	v_and_b32_e32 v99, 0xffff0000, v99
	v_lshlrev_b32_e32 v100, 16, v102
	v_and_b32_e32 v101, 0xffff0000, v102
	v_lshlrev_b32_e32 v102, 16, v103
	v_and_b32_e32 v103, 0xffff0000, v103
	v_lshlrev_b32_e32 v104, 16, v106
	v_and_b32_e32 v105, 0xffff0000, v106
	v_lshlrev_b32_e32 v106, 16, v107
	v_and_b32_e32 v107, 0xffff0000, v107
	v_lshlrev_b32_e32 v108, 16, v110
	v_and_b32_e32 v109, 0xffff0000, v110
	v_lshlrev_b32_e32 v110, 16, v111
	v_and_b32_e32 v111, 0xffff0000, v111
	v_mul_f32_e32 v10, v64, v64
	v_fmac_f32_e32 v10, v65, v65
	v_fmac_f32_e32 v10, v66, v66
	v_fmac_f32_e32 v10, v67, v67
	v_fmac_f32_e32 v10, v68, v68
	v_fmac_f32_e32 v10, v69, v69
	v_fmac_f32_e32 v10, v70, v70
	v_fmac_f32_e32 v10, v71, v71
	v_fmac_f32_e32 v10, v72, v72
	v_fmac_f32_e32 v10, v73, v73
	v_fmac_f32_e32 v10, v74, v74
	v_fmac_f32_e32 v10, v75, v75
	v_fmac_f32_e32 v10, v76, v76
	v_fmac_f32_e32 v10, v77, v77
	v_fmac_f32_e32 v10, v78, v78
	v_fmac_f32_e32 v10, v79, v79
	v_mul_f32_e32 v11, v96, v96
	v_fmac_f32_e32 v11, v97, v97
	v_fmac_f32_e32 v11, v98, v98
	v_fmac_f32_e32 v11, v99, v99
	v_fmac_f32_e32 v11, v100, v100
	v_fmac_f32_e32 v11, v101, v101
	v_fmac_f32_e32 v11, v102, v102
	v_fmac_f32_e32 v11, v103, v103
	v_fmac_f32_e32 v11, v104, v104
	v_fmac_f32_e32 v11, v105, v105
	v_fmac_f32_e32 v11, v106, v106
	v_fmac_f32_e32 v11, v107, v107
	v_fmac_f32_e32 v11, v108, v108
	v_fmac_f32_e32 v11, v109, v109
	v_fmac_f32_e32 v11, v110, v110
	v_fmac_f32_e32 v11, v111, v111
	ds_bpermute_b32 v12, v4, v10
	ds_bpermute_b32 v13, v4, v11
	s_waitcnt lgkmcnt(0)
	v_add_f32_e32 v10, v10, v12
	v_add_f32_e32 v11, v11, v13
	ds_bpermute_b32 v12, v5, v10
	ds_bpermute_b32 v13, v5, v11
	s_waitcnt lgkmcnt(0)
	v_add_f32_e32 v10, v10, v12
	v_add_f32_e32 v11, v11, v13
	ds_bpermute_b32 v12, v6, v10
	ds_bpermute_b32 v13, v6, v11
	s_waitcnt lgkmcnt(0)
	v_add_f32_e32 v10, v10, v12
	v_add_f32_e32 v11, v11, v13
	ds_bpermute_b32 v12, v7, v10
	ds_bpermute_b32 v13, v7, v11
	s_waitcnt lgkmcnt(0)
	v_add_f32_e32 v10, v10, v12
	v_add_f32_e32 v11, v11, v13
	ds_bpermute_b32 v12, v8, v10
	ds_bpermute_b32 v13, v8, v11
	s_waitcnt lgkmcnt(0)
	v_add_f32_e32 v10, v10, v12
	v_add_f32_e32 v11, v11, v13
	ds_bpermute_b32 v12, v9, v10
	ds_bpermute_b32 v13, v9, v11
	s_waitcnt lgkmcnt(0)
	v_add_f32_e32 v10, v10, v12
	v_add_f32_e32 v11, v11, v13
	v_fma_f32 v14, v10, s17, v3
	v_fma_f32 v15, v11, s17, v3
	v_rsq_f32_e32 v14, v14
	v_rsq_f32_e32 v15, v15
	s_nop 0
	v_mul_f32_e32 v64, v64, v14
	v_mul_f32_e32 v65, v65, v14
	v_mul_f32_e32 v66, v66, v14
	v_mul_f32_e32 v67, v67, v14
	v_mul_f32_e32 v68, v68, v14
	v_mul_f32_e32 v69, v69, v14
	v_mul_f32_e32 v70, v70, v14
	v_mul_f32_e32 v71, v71, v14
	v_mul_f32_e32 v72, v72, v14
	v_mul_f32_e32 v73, v73, v14
	v_mul_f32_e32 v74, v74, v14
	v_mul_f32_e32 v75, v75, v14
	v_mul_f32_e32 v76, v76, v14
	v_mul_f32_e32 v77, v77, v14
	v_mul_f32_e32 v78, v78, v14
	v_mul_f32_e32 v79, v79, v14
	v_fmac_f32_e32 v80, v64, v20
	v_fmac_f32_e32 v81, v65, v21
	v_fmac_f32_e32 v82, v66, v22
	v_fmac_f32_e32 v83, v67, v23
	v_fmac_f32_e32 v84, v68, v24
	v_fmac_f32_e32 v85, v69, v25
	v_fmac_f32_e32 v86, v70, v26
	v_fmac_f32_e32 v87, v71, v27
	v_fmac_f32_e32 v88, v72, v28
	v_fmac_f32_e32 v89, v73, v29
	v_fmac_f32_e32 v90, v74, v30
	v_fmac_f32_e32 v91, v75, v31
	v_fmac_f32_e32 v92, v76, v32
	v_fmac_f32_e32 v93, v77, v33
	v_fmac_f32_e32 v94, v78, v34
	v_fmac_f32_e32 v95, v79, v35
	global_store_dwordx4 v1, v[80:83], s[24:25] offset:0 nt
	global_store_dwordx4 v1, v[84:87], s[24:25] offset:1024 nt
	global_store_dwordx4 v1, v[88:91], s[24:25] offset:2048 nt
	global_store_dwordx4 v1, v[92:95], s[24:25] offset:3072 nt
	v_mul_f32_e32 v96, v96, v15
	v_mul_f32_e32 v97, v97, v15
	v_mul_f32_e32 v98, v98, v15
	v_mul_f32_e32 v99, v99, v15
	v_mul_f32_e32 v100, v100, v15
	v_mul_f32_e32 v101, v101, v15
	v_mul_f32_e32 v102, v102, v15
	v_mul_f32_e32 v103, v103, v15
	v_mul_f32_e32 v104, v104, v15
	v_mul_f32_e32 v105, v105, v15
	v_mul_f32_e32 v106, v106, v15
	v_mul_f32_e32 v107, v107, v15
	v_mul_f32_e32 v108, v108, v15
	v_mul_f32_e32 v109, v109, v15
	v_mul_f32_e32 v110, v110, v15
	v_mul_f32_e32 v111, v111, v15
	v_fmac_f32_e32 v112, v96, v20
	v_fmac_f32_e32 v113, v97, v21
	v_fmac_f32_e32 v114, v98, v22
	v_fmac_f32_e32 v115, v99, v23
	v_fmac_f32_e32 v116, v100, v24
	v_fmac_f32_e32 v117, v101, v25
	v_fmac_f32_e32 v118, v102, v26
	v_fmac_f32_e32 v119, v103, v27
	v_fmac_f32_e32 v120, v104, v28
	v_fmac_f32_e32 v121, v105, v29
	v_fmac_f32_e32 v122, v106, v30
	v_fmac_f32_e32 v123, v107, v31
	v_fmac_f32_e32 v124, v108, v32
	v_fmac_f32_e32 v125, v109, v33
	v_fmac_f32_e32 v126, v110, v34
	v_fmac_f32_e32 v127, v111, v35
	global_store_dwordx4 v1, v[112:115], s[32:33] offset:0 nt
	global_store_dwordx4 v1, v[116:119], s[32:33] offset:1024 nt
	global_store_dwordx4 v1, v[120:123], s[32:33] offset:2048 nt
	global_store_dwordx4 v1, v[124:127], s[32:33] offset:3072 nt
	v_mul_f32_e32 v10, v80, v80
	v_fmac_f32_e32 v10, v81, v81
	v_fmac_f32_e32 v10, v82, v82
	v_fmac_f32_e32 v10, v83, v83
	v_fmac_f32_e32 v10, v84, v84
	v_fmac_f32_e32 v10, v85, v85
	v_fmac_f32_e32 v10, v86, v86
	v_fmac_f32_e32 v10, v87, v87
	v_fmac_f32_e32 v10, v88, v88
	v_fmac_f32_e32 v10, v89, v89
	v_fmac_f32_e32 v10, v90, v90
	v_fmac_f32_e32 v10, v91, v91
	v_fmac_f32_e32 v10, v92, v92
	v_fmac_f32_e32 v10, v93, v93
	v_fmac_f32_e32 v10, v94, v94
	v_fmac_f32_e32 v10, v95, v95
	v_mul_f32_e32 v11, v112, v112
	v_fmac_f32_e32 v11, v113, v113
	v_fmac_f32_e32 v11, v114, v114
	v_fmac_f32_e32 v11, v115, v115
	v_fmac_f32_e32 v11, v116, v116
	v_fmac_f32_e32 v11, v117, v117
	v_fmac_f32_e32 v11, v118, v118
	v_fmac_f32_e32 v11, v119, v119
	v_fmac_f32_e32 v11, v120, v120
	v_fmac_f32_e32 v11, v121, v121
	v_fmac_f32_e32 v11, v122, v122
	v_fmac_f32_e32 v11, v123, v123
	v_fmac_f32_e32 v11, v124, v124
	v_fmac_f32_e32 v11, v125, v125
	v_fmac_f32_e32 v11, v126, v126
	v_fmac_f32_e32 v11, v127, v127
	ds_bpermute_b32 v12, v4, v10
	ds_bpermute_b32 v13, v4, v11
	s_waitcnt lgkmcnt(0)
	v_add_f32_e32 v10, v10, v12
	v_add_f32_e32 v11, v11, v13
	ds_bpermute_b32 v12, v5, v10
	ds_bpermute_b32 v13, v5, v11
	s_waitcnt lgkmcnt(0)
	v_add_f32_e32 v10, v10, v12
	v_add_f32_e32 v11, v11, v13
	ds_bpermute_b32 v12, v6, v10
	ds_bpermute_b32 v13, v6, v11
	s_waitcnt lgkmcnt(0)
	v_add_f32_e32 v10, v10, v12
	v_add_f32_e32 v11, v11, v13
	ds_bpermute_b32 v12, v7, v10
	ds_bpermute_b32 v13, v7, v11
	s_waitcnt lgkmcnt(0)
	v_add_f32_e32 v10, v10, v12
	v_add_f32_e32 v11, v11, v13
	ds_bpermute_b32 v12, v8, v10
	ds_bpermute_b32 v13, v8, v11
	s_waitcnt lgkmcnt(0)
	v_add_f32_e32 v10, v10, v12
	v_add_f32_e32 v11, v11, v13
	ds_bpermute_b32 v12, v9, v10
	ds_bpermute_b32 v13, v9, v11
	s_waitcnt lgkmcnt(0)
	v_add_f32_e32 v10, v10, v12
	v_add_f32_e32 v11, v11, v13
	v_fma_f32 v14, v10, s17, v3
	v_fma_f32 v15, v11, s17, v3
	v_rsq_f32_e32 v14, v14
	v_rsq_f32_e32 v15, v15
	s_nop 0
	v_mul_f32_e32 v64, v80, v14
	v_mul_f32_e32 v65, v81, v14
	v_mul_f32_e32 v66, v82, v14
	v_mul_f32_e32 v67, v83, v14
	v_mul_f32_e32 v68, v84, v14
	v_mul_f32_e32 v69, v85, v14
	v_mul_f32_e32 v70, v86, v14
	v_mul_f32_e32 v71, v87, v14
	v_mul_f32_e32 v72, v88, v14
	v_mul_f32_e32 v73, v89, v14
	v_mul_f32_e32 v74, v90, v14
	v_mul_f32_e32 v75, v91, v14
	v_mul_f32_e32 v76, v92, v14
	v_mul_f32_e32 v77, v93, v14
	v_mul_f32_e32 v78, v94, v14
	v_mul_f32_e32 v79, v95, v14
	v_mul_f32_e32 v64, v64, v36
	v_mul_f32_e32 v65, v65, v37
	v_mul_f32_e32 v66, v66, v38
	v_mul_f32_e32 v67, v67, v39
	v_mul_f32_e32 v68, v68, v40
	v_mul_f32_e32 v69, v69, v41
	v_mul_f32_e32 v70, v70, v42
	v_mul_f32_e32 v71, v71, v43
	v_mul_f32_e32 v72, v72, v44
	v_mul_f32_e32 v73, v73, v45
	v_mul_f32_e32 v74, v74, v46
	v_mul_f32_e32 v75, v75, v47
	v_mul_f32_e32 v76, v76, v48
	v_mul_f32_e32 v77, v77, v49
	v_mul_f32_e32 v78, v78, v50
	v_mul_f32_e32 v79, v79, v51
	v_cvt_pk_bf16_f32 v64, v64, v65
	v_cvt_pk_bf16_f32 v65, v66, v67
	v_cvt_pk_bf16_f32 v68, v68, v69
	v_cvt_pk_bf16_f32 v69, v70, v71
	v_cvt_pk_bf16_f32 v72, v72, v73
	v_cvt_pk_bf16_f32 v73, v74, v75
	v_cvt_pk_bf16_f32 v76, v76, v77
	v_cvt_pk_bf16_f32 v77, v78, v79
	global_store_dwordx2 v2, v[64:65], s[26:27] offset:0
	global_store_dwordx2 v2, v[68:69], s[26:27] offset:512
	global_store_dwordx2 v2, v[72:73], s[26:27] offset:1024
	global_store_dwordx2 v2, v[76:77], s[26:27] offset:1536
	v_mul_f32_e32 v96, v112, v15
	v_mul_f32_e32 v97, v113, v15
	v_mul_f32_e32 v98, v114, v15
	v_mul_f32_e32 v99, v115, v15
	v_mul_f32_e32 v100, v116, v15
	v_mul_f32_e32 v101, v117, v15
	v_mul_f32_e32 v102, v118, v15
	v_mul_f32_e32 v103, v119, v15
	v_mul_f32_e32 v104, v120, v15
	v_mul_f32_e32 v105, v121, v15
	v_mul_f32_e32 v106, v122, v15
	v_mul_f32_e32 v107, v123, v15
	v_mul_f32_e32 v108, v124, v15
	v_mul_f32_e32 v109, v125, v15
	v_mul_f32_e32 v110, v126, v15
	v_mul_f32_e32 v111, v127, v15
	v_mul_f32_e32 v96, v96, v36
	v_mul_f32_e32 v97, v97, v37
	v_mul_f32_e32 v98, v98, v38
	v_mul_f32_e32 v99, v99, v39
	v_mul_f32_e32 v100, v100, v40
	v_mul_f32_e32 v101, v101, v41
	v_mul_f32_e32 v102, v102, v42
	v_mul_f32_e32 v103, v103, v43
	v_mul_f32_e32 v104, v104, v44
	v_mul_f32_e32 v105, v105, v45
	v_mul_f32_e32 v106, v106, v46
	v_mul_f32_e32 v107, v107, v47
	v_mul_f32_e32 v108, v108, v48
	v_mul_f32_e32 v109, v109, v49
	v_mul_f32_e32 v110, v110, v50
	v_mul_f32_e32 v111, v111, v51
	v_cvt_pk_bf16_f32 v96, v96, v97
	v_cvt_pk_bf16_f32 v97, v98, v99
	v_cvt_pk_bf16_f32 v100, v100, v101
	v_cvt_pk_bf16_f32 v101, v102, v103
	v_cvt_pk_bf16_f32 v104, v104, v105
	v_cvt_pk_bf16_f32 v105, v106, v107
	v_cvt_pk_bf16_f32 v108, v108, v109
	v_cvt_pk_bf16_f32 v109, v110, v111
	global_store_dwordx2 v2, v[96:97], s[34:35] offset:0
	global_store_dwordx2 v2, v[100:101], s[34:35] offset:512
	global_store_dwordx2 v2, v[104:105], s[34:35] offset:1024
	global_store_dwordx2 v2, v[108:109], s[34:35] offset:1536
	s_add_u32 s53, s16, 0x2000
	s_lshl_b32 s18, s53, 12
	s_lshl_b32 s19, s53, 11
	s_add_u32 s20, s4, s18
	s_addc_u32 s21, s5, 0
	s_add_u32 s22, s6, s19
	s_addc_u32 s23, s7, 0
	s_add_u32 s22, s22, 0x5200000
	s_addc_u32 s23, s23, 0
	s_add_u32 s24, s4, s18
	s_addc_u32 s25, s5, 0
	s_add_u32 s26, s6, s19
	s_addc_u32 s27, s7, 0
	s_add_u32 s26, s26, 0x3100000
	s_addc_u32 s27, s27, 0
	global_load_dwordx2 v[66:67], v2, s[22:23] offset:0 nt
	global_load_dwordx2 v[70:71], v2, s[22:23] offset:512 nt
	global_load_dwordx2 v[74:75], v2, s[22:23] offset:1024 nt
	global_load_dwordx2 v[78:79], v2, s[22:23] offset:1536 nt
	global_load_dwordx4 v[80:83], v1, s[20:21] offset:0 nt
	global_load_dwordx4 v[84:87], v1, s[20:21] offset:1024 nt
	global_load_dwordx4 v[88:91], v1, s[20:21] offset:2048 nt
	global_load_dwordx4 v[92:95], v1, s[20:21] offset:3072 nt
	s_add_u32 s53, s16, 0x2800
	s_lshl_b32 s18, s53, 12
	s_lshl_b32 s19, s53, 11
	s_add_u32 s28, s4, s18
	s_addc_u32 s29, s5, 0
	s_add_u32 s30, s6, s19
	s_addc_u32 s31, s7, 0
	s_add_u32 s30, s30, 0x5200000
	s_addc_u32 s31, s31, 0
	s_add_u32 s32, s4, s18
	s_addc_u32 s33, s5, 0
	s_add_u32 s34, s6, s19
	s_addc_u32 s35, s7, 0
	s_add_u32 s34, s34, 0x3100000
	s_addc_u32 s35, s35, 0
	global_load_dwordx2 v[98:99], v2, s[30:31] offset:0 nt
	global_load_dwordx2 v[102:103], v2, s[30:31] offset:512 nt
	global_load_dwordx2 v[106:107], v2, s[30:31] offset:1024 nt
	global_load_dwordx2 v[110:111], v2, s[30:31] offset:1536 nt
	global_load_dwordx4 v[112:115], v1, s[28:29] offset:0 nt
	global_load_dwordx4 v[116:119], v1, s[28:29] offset:1024 nt
	global_load_dwordx4 v[120:123], v1, s[28:29] offset:2048 nt
	global_load_dwordx4 v[124:127], v1, s[28:29] offset:3072 nt
	s_waitcnt vmcnt(32)
	v_lshlrev_b32_e32 v128, 16, v130
	v_and_b32_e32 v129, 0xffff0000, v130
	v_lshlrev_b32_e32 v130, 16, v131
	v_and_b32_e32 v131, 0xffff0000, v131
	v_lshlrev_b32_e32 v132, 16, v134
	v_and_b32_e32 v133, 0xffff0000, v134
	v_lshlrev_b32_e32 v134, 16, v135
	v_and_b32_e32 v135, 0xffff0000, v135
	v_lshlrev_b32_e32 v136, 16, v138
	v_and_b32_e32 v137, 0xffff0000, v138
	v_lshlrev_b32_e32 v138, 16, v139
	v_and_b32_e32 v139, 0xffff0000, v139
	v_lshlrev_b32_e32 v140, 16, v142
	v_and_b32_e32 v141, 0xffff0000, v142
	v_lshlrev_b32_e32 v142, 16, v143
	v_and_b32_e32 v143, 0xffff0000, v143
	v_lshlrev_b32_e32 v160, 16, v162
	v_and_b32_e32 v161, 0xffff0000, v162
	v_lshlrev_b32_e32 v162, 16, v163
	v_and_b32_e32 v163, 0xffff0000, v163
	v_lshlrev_b32_e32 v164, 16, v166
	v_and_b32_e32 v165, 0xffff0000, v166
	v_lshlrev_b32_e32 v166, 16, v167
	v_and_b32_e32 v167, 0xffff0000, v167
	v_lshlrev_b32_e32 v168, 16, v170
	v_and_b32_e32 v169, 0xffff0000, v170
	v_lshlrev_b32_e32 v170, 16, v171
	v_and_b32_e32 v171, 0xffff0000, v171
	v_lshlrev_b32_e32 v172, 16, v174
	v_and_b32_e32 v173, 0xffff0000, v174
	v_lshlrev_b32_e32 v174, 16, v175
	v_and_b32_e32 v175, 0xffff0000, v175
	v_mul_f32_e32 v10, v128, v128
	v_fmac_f32_e32 v10, v129, v129
	v_fmac_f32_e32 v10, v130, v130
	v_fmac_f32_e32 v10, v131, v131
	v_fmac_f32_e32 v10, v132, v132
	v_fmac_f32_e32 v10, v133, v133
	v_fmac_f32_e32 v10, v134, v134
	v_fmac_f32_e32 v10, v135, v135
	v_fmac_f32_e32 v10, v136, v136
	v_fmac_f32_e32 v10, v137, v137
	v_fmac_f32_e32 v10, v138, v138
	v_fmac_f32_e32 v10, v139, v139
	v_fmac_f32_e32 v10, v140, v140
	v_fmac_f32_e32 v10, v141, v141
	v_fmac_f32_e32 v10, v142, v142
	v_fmac_f32_e32 v10, v143, v143
	v_mul_f32_e32 v11, v160, v160
	v_fmac_f32_e32 v11, v161, v161
	v_fmac_f32_e32 v11, v162, v162
	v_fmac_f32_e32 v11, v163, v163
	v_fmac_f32_e32 v11, v164, v164
	v_fmac_f32_e32 v11, v165, v165
	v_fmac_f32_e32 v11, v166, v166
	v_fmac_f32_e32 v11, v167, v167
	v_fmac_f32_e32 v11, v168, v168
	v_fmac_f32_e32 v11, v169, v169
	v_fmac_f32_e32 v11, v170, v170
	v_fmac_f32_e32 v11, v171, v171
	v_fmac_f32_e32 v11, v172, v172
	v_fmac_f32_e32 v11, v173, v173
	v_fmac_f32_e32 v11, v174, v174
	v_fmac_f32_e32 v11, v175, v175
	ds_bpermute_b32 v12, v4, v10
	ds_bpermute_b32 v13, v4, v11
	s_waitcnt lgkmcnt(0)
	v_add_f32_e32 v10, v10, v12
	v_add_f32_e32 v11, v11, v13
	ds_bpermute_b32 v12, v5, v10
	ds_bpermute_b32 v13, v5, v11
	s_waitcnt lgkmcnt(0)
	v_add_f32_e32 v10, v10, v12
	v_add_f32_e32 v11, v11, v13
	ds_bpermute_b32 v12, v6, v10
	ds_bpermute_b32 v13, v6, v11
	s_waitcnt lgkmcnt(0)
	v_add_f32_e32 v10, v10, v12
	v_add_f32_e32 v11, v11, v13
	ds_bpermute_b32 v12, v7, v10
	ds_bpermute_b32 v13, v7, v11
	s_waitcnt lgkmcnt(0)
	v_add_f32_e32 v10, v10, v12
	v_add_f32_e32 v11, v11, v13
	ds_bpermute_b32 v12, v8, v10
	ds_bpermute_b32 v13, v8, v11
	s_waitcnt lgkmcnt(0)
	v_add_f32_e32 v10, v10, v12
	v_add_f32_e32 v11, v11, v13
	ds_bpermute_b32 v12, v9, v10
	ds_bpermute_b32 v13, v9, v11
	s_waitcnt lgkmcnt(0)
	v_add_f32_e32 v10, v10, v12
	v_add_f32_e32 v11, v11, v13
	v_fma_f32 v14, v10, s17, v3
	v_fma_f32 v15, v11, s17, v3
	v_rsq_f32_e32 v14, v14
	v_rsq_f32_e32 v15, v15
	s_nop 0
	v_mul_f32_e32 v128, v128, v14
	v_mul_f32_e32 v129, v129, v14
	v_mul_f32_e32 v130, v130, v14
	v_mul_f32_e32 v131, v131, v14
	v_mul_f32_e32 v132, v132, v14
	v_mul_f32_e32 v133, v133, v14
	v_mul_f32_e32 v134, v134, v14
	v_mul_f32_e32 v135, v135, v14
	v_mul_f32_e32 v136, v136, v14
	v_mul_f32_e32 v137, v137, v14
	v_mul_f32_e32 v138, v138, v14
	v_mul_f32_e32 v139, v139, v14
	v_mul_f32_e32 v140, v140, v14
	v_mul_f32_e32 v141, v141, v14
	v_mul_f32_e32 v142, v142, v14
	v_mul_f32_e32 v143, v143, v14
	v_fmac_f32_e32 v144, v128, v20
	v_fmac_f32_e32 v145, v129, v21
	v_fmac_f32_e32 v146, v130, v22
	v_fmac_f32_e32 v147, v131, v23
	v_fmac_f32_e32 v148, v132, v24
	v_fmac_f32_e32 v149, v133, v25
	v_fmac_f32_e32 v150, v134, v26
	v_fmac_f32_e32 v151, v135, v27
	v_fmac_f32_e32 v152, v136, v28
	v_fmac_f32_e32 v153, v137, v29
	v_fmac_f32_e32 v154, v138, v30
	v_fmac_f32_e32 v155, v139, v31
	v_fmac_f32_e32 v156, v140, v32
	v_fmac_f32_e32 v157, v141, v33
	v_fmac_f32_e32 v158, v142, v34
	v_fmac_f32_e32 v159, v143, v35
	global_store_dwordx4 v1, v[144:147], s[40:41] offset:0 nt
	global_store_dwordx4 v1, v[148:151], s[40:41] offset:1024 nt
	global_store_dwordx4 v1, v[152:155], s[40:41] offset:2048 nt
	global_store_dwordx4 v1, v[156:159], s[40:41] offset:3072 nt
	v_mul_f32_e32 v160, v160, v15
	v_mul_f32_e32 v161, v161, v15
	v_mul_f32_e32 v162, v162, v15
	v_mul_f32_e32 v163, v163, v15
	v_mul_f32_e32 v164, v164, v15
	v_mul_f32_e32 v165, v165, v15
	v_mul_f32_e32 v166, v166, v15
	v_mul_f32_e32 v167, v167, v15
	v_mul_f32_e32 v168, v168, v15
	v_mul_f32_e32 v169, v169, v15
	v_mul_f32_e32 v170, v170, v15
	v_mul_f32_e32 v171, v171, v15
	v_mul_f32_e32 v172, v172, v15
	v_mul_f32_e32 v173, v173, v15
	v_mul_f32_e32 v174, v174, v15
	v_mul_f32_e32 v175, v175, v15
	v_fmac_f32_e32 v176, v160, v20
	v_fmac_f32_e32 v177, v161, v21
	v_fmac_f32_e32 v178, v162, v22
	v_fmac_f32_e32 v179, v163, v23
	v_fmac_f32_e32 v180, v164, v24
	v_fmac_f32_e32 v181, v165, v25
	v_fmac_f32_e32 v182, v166, v26
	v_fmac_f32_e32 v183, v167, v27
	v_fmac_f32_e32 v184, v168, v28
	v_fmac_f32_e32 v185, v169, v29
	v_fmac_f32_e32 v186, v170, v30
	v_fmac_f32_e32 v187, v171, v31
	v_fmac_f32_e32 v188, v172, v32
	v_fmac_f32_e32 v189, v173, v33
	v_fmac_f32_e32 v190, v174, v34
	v_fmac_f32_e32 v191, v175, v35
	global_store_dwordx4 v1, v[176:179], s[48:49] offset:0 nt
	global_store_dwordx4 v1, v[180:183], s[48:49] offset:1024 nt
	global_store_dwordx4 v1, v[184:187], s[48:49] offset:2048 nt
	global_store_dwordx4 v1, v[188:191], s[48:49] offset:3072 nt
	v_mul_f32_e32 v10, v144, v144
	v_fmac_f32_e32 v10, v145, v145
	v_fmac_f32_e32 v10, v146, v146
	v_fmac_f32_e32 v10, v147, v147
	v_fmac_f32_e32 v10, v148, v148
	v_fmac_f32_e32 v10, v149, v149
	v_fmac_f32_e32 v10, v150, v150
	v_fmac_f32_e32 v10, v151, v151
	v_fmac_f32_e32 v10, v152, v152
	v_fmac_f32_e32 v10, v153, v153
	v_fmac_f32_e32 v10, v154, v154
	v_fmac_f32_e32 v10, v155, v155
	v_fmac_f32_e32 v10, v156, v156
	v_fmac_f32_e32 v10, v157, v157
	v_fmac_f32_e32 v10, v158, v158
	v_fmac_f32_e32 v10, v159, v159
	v_mul_f32_e32 v11, v176, v176
	v_fmac_f32_e32 v11, v177, v177
	v_fmac_f32_e32 v11, v178, v178
	v_fmac_f32_e32 v11, v179, v179
	v_fmac_f32_e32 v11, v180, v180
	v_fmac_f32_e32 v11, v181, v181
	v_fmac_f32_e32 v11, v182, v182
	v_fmac_f32_e32 v11, v183, v183
	v_fmac_f32_e32 v11, v184, v184
	v_fmac_f32_e32 v11, v185, v185
	v_fmac_f32_e32 v11, v186, v186
	v_fmac_f32_e32 v11, v187, v187
	v_fmac_f32_e32 v11, v188, v188
	v_fmac_f32_e32 v11, v189, v189
	v_fmac_f32_e32 v11, v190, v190
	v_fmac_f32_e32 v11, v191, v191
	ds_bpermute_b32 v12, v4, v10
	ds_bpermute_b32 v13, v4, v11
	s_waitcnt lgkmcnt(0)
	v_add_f32_e32 v10, v10, v12
	v_add_f32_e32 v11, v11, v13
	ds_bpermute_b32 v12, v5, v10
	ds_bpermute_b32 v13, v5, v11
	s_waitcnt lgkmcnt(0)
	v_add_f32_e32 v10, v10, v12
	v_add_f32_e32 v11, v11, v13
	ds_bpermute_b32 v12, v6, v10
	ds_bpermute_b32 v13, v6, v11
	s_waitcnt lgkmcnt(0)
	v_add_f32_e32 v10, v10, v12
	v_add_f32_e32 v11, v11, v13
	ds_bpermute_b32 v12, v7, v10
	ds_bpermute_b32 v13, v7, v11
	s_waitcnt lgkmcnt(0)
	v_add_f32_e32 v10, v10, v12
	v_add_f32_e32 v11, v11, v13
	ds_bpermute_b32 v12, v8, v10
	ds_bpermute_b32 v13, v8, v11
	s_waitcnt lgkmcnt(0)
	v_add_f32_e32 v10, v10, v12
	v_add_f32_e32 v11, v11, v13
	ds_bpermute_b32 v12, v9, v10
	ds_bpermute_b32 v13, v9, v11
	s_waitcnt lgkmcnt(0)
	v_add_f32_e32 v10, v10, v12
	v_add_f32_e32 v11, v11, v13
	v_fma_f32 v14, v10, s17, v3
	v_fma_f32 v15, v11, s17, v3
	v_rsq_f32_e32 v14, v14
	v_rsq_f32_e32 v15, v15
	s_nop 0
	v_mul_f32_e32 v128, v144, v14
	v_mul_f32_e32 v129, v145, v14
	v_mul_f32_e32 v130, v146, v14
	v_mul_f32_e32 v131, v147, v14
	v_mul_f32_e32 v132, v148, v14
	v_mul_f32_e32 v133, v149, v14
	v_mul_f32_e32 v134, v150, v14
	v_mul_f32_e32 v135, v151, v14
	v_mul_f32_e32 v136, v152, v14
	v_mul_f32_e32 v137, v153, v14
	v_mul_f32_e32 v138, v154, v14
	v_mul_f32_e32 v139, v155, v14
	v_mul_f32_e32 v140, v156, v14
	v_mul_f32_e32 v141, v157, v14
	v_mul_f32_e32 v142, v158, v14
	v_mul_f32_e32 v143, v159, v14
	v_mul_f32_e32 v128, v128, v36
	v_mul_f32_e32 v129, v129, v37
	v_mul_f32_e32 v130, v130, v38
	v_mul_f32_e32 v131, v131, v39
	v_mul_f32_e32 v132, v132, v40
	v_mul_f32_e32 v133, v133, v41
	v_mul_f32_e32 v134, v134, v42
	v_mul_f32_e32 v135, v135, v43
	v_mul_f32_e32 v136, v136, v44
	v_mul_f32_e32 v137, v137, v45
	v_mul_f32_e32 v138, v138, v46
	v_mul_f32_e32 v139, v139, v47
	v_mul_f32_e32 v140, v140, v48
	v_mul_f32_e32 v141, v141, v49
	v_mul_f32_e32 v142, v142, v50
	v_mul_f32_e32 v143, v143, v51
	v_cvt_pk_bf16_f32 v128, v128, v129
	v_cvt_pk_bf16_f32 v129, v130, v131
	v_cvt_pk_bf16_f32 v132, v132, v133
	v_cvt_pk_bf16_f32 v133, v134, v135
	v_cvt_pk_bf16_f32 v136, v136, v137
	v_cvt_pk_bf16_f32 v137, v138, v139
	v_cvt_pk_bf16_f32 v140, v140, v141
	v_cvt_pk_bf16_f32 v141, v142, v143
	global_store_dwordx2 v2, v[128:129], s[42:43] offset:0
	global_store_dwordx2 v2, v[132:133], s[42:43] offset:512
	global_store_dwordx2 v2, v[136:137], s[42:43] offset:1024
	global_store_dwordx2 v2, v[140:141], s[42:43] offset:1536
	v_mul_f32_e32 v160, v176, v15
	v_mul_f32_e32 v161, v177, v15
	v_mul_f32_e32 v162, v178, v15
	v_mul_f32_e32 v163, v179, v15
	v_mul_f32_e32 v164, v180, v15
	v_mul_f32_e32 v165, v181, v15
	v_mul_f32_e32 v166, v182, v15
	v_mul_f32_e32 v167, v183, v15
	v_mul_f32_e32 v168, v184, v15
	v_mul_f32_e32 v169, v185, v15
	v_mul_f32_e32 v170, v186, v15
	v_mul_f32_e32 v171, v187, v15
	v_mul_f32_e32 v172, v188, v15
	v_mul_f32_e32 v173, v189, v15
	v_mul_f32_e32 v174, v190, v15
	v_mul_f32_e32 v175, v191, v15
	v_mul_f32_e32 v160, v160, v36
	v_mul_f32_e32 v161, v161, v37
	v_mul_f32_e32 v162, v162, v38
	v_mul_f32_e32 v163, v163, v39
	v_mul_f32_e32 v164, v164, v40
	v_mul_f32_e32 v165, v165, v41
	v_mul_f32_e32 v166, v166, v42
	v_mul_f32_e32 v167, v167, v43
	v_mul_f32_e32 v168, v168, v44
	v_mul_f32_e32 v169, v169, v45
	v_mul_f32_e32 v170, v170, v46
	v_mul_f32_e32 v171, v171, v47
	v_mul_f32_e32 v172, v172, v48
	v_mul_f32_e32 v173, v173, v49
	v_mul_f32_e32 v174, v174, v50
	v_mul_f32_e32 v175, v175, v51
	v_cvt_pk_bf16_f32 v160, v160, v161
	v_cvt_pk_bf16_f32 v161, v162, v163
	v_cvt_pk_bf16_f32 v164, v164, v165
	v_cvt_pk_bf16_f32 v165, v166, v167
	v_cvt_pk_bf16_f32 v168, v168, v169
	v_cvt_pk_bf16_f32 v169, v170, v171
	v_cvt_pk_bf16_f32 v172, v172, v173
	v_cvt_pk_bf16_f32 v173, v174, v175
	global_store_dwordx2 v2, v[160:161], s[50:51] offset:0
	global_store_dwordx2 v2, v[164:165], s[50:51] offset:512
	global_store_dwordx2 v2, v[168:169], s[50:51] offset:1024
	global_store_dwordx2 v2, v[172:173], s[50:51] offset:1536
	s_add_u32 s53, s16, 0x3000
	s_lshl_b32 s18, s53, 12
	s_lshl_b32 s19, s53, 11
	s_add_u32 s36, s4, s18
	s_addc_u32 s37, s5, 0
	s_add_u32 s38, s6, s19
	s_addc_u32 s39, s7, 0
	s_add_u32 s38, s38, 0x5200000
	s_addc_u32 s39, s39, 0
	s_add_u32 s40, s4, s18
	s_addc_u32 s41, s5, 0
	s_add_u32 s42, s6, s19
	s_addc_u32 s43, s7, 0
	s_add_u32 s42, s42, 0x3100000
	s_addc_u32 s43, s43, 0
	global_load_dwordx2 v[130:131], v2, s[38:39] offset:0 nt
	global_load_dwordx2 v[134:135], v2, s[38:39] offset:512 nt
	global_load_dwordx2 v[138:139], v2, s[38:39] offset:1024 nt
	global_load_dwordx2 v[142:143], v2, s[38:39] offset:1536 nt
	global_load_dwordx4 v[144:147], v1, s[36:37] offset:0 nt
	global_load_dwordx4 v[148:151], v1, s[36:37] offset:1024 nt
	global_load_dwordx4 v[152:155], v1, s[36:37] offset:2048 nt
	global_load_dwordx4 v[156:159], v1, s[36:37] offset:3072 nt
	s_add_u32 s53, s16, 0x3800
	s_lshl_b32 s18, s53, 12
	s_lshl_b32 s19, s53, 11
	s_add_u32 s44, s4, s18
	s_addc_u32 s45, s5, 0
	s_add_u32 s46, s6, s19
	s_addc_u32 s47, s7, 0
	s_add_u32 s46, s46, 0x5200000
	s_addc_u32 s47, s47, 0
	s_add_u32 s48, s4, s18
	s_addc_u32 s49, s5, 0
	s_add_u32 s50, s6, s19
	s_addc_u32 s51, s7, 0
	s_add_u32 s50, s50, 0x3100000
	s_addc_u32 s51, s51, 0
	global_load_dwordx2 v[162:163], v2, s[46:47] offset:0 nt
	global_load_dwordx2 v[166:167], v2, s[46:47] offset:512 nt
	global_load_dwordx2 v[170:171], v2, s[46:47] offset:1024 nt
	global_load_dwordx2 v[174:175], v2, s[46:47] offset:1536 nt
	global_load_dwordx4 v[176:179], v1, s[44:45] offset:0 nt
	global_load_dwordx4 v[180:183], v1, s[44:45] offset:1024 nt
	global_load_dwordx4 v[184:187], v1, s[44:45] offset:2048 nt
	global_load_dwordx4 v[188:191], v1, s[44:45] offset:3072 nt
	s_waitcnt vmcnt(32)
	v_lshlrev_b32_e32 v64, 16, v66
	v_and_b32_e32 v65, 0xffff0000, v66
	v_lshlrev_b32_e32 v66, 16, v67
	v_and_b32_e32 v67, 0xffff0000, v67
	v_lshlrev_b32_e32 v68, 16, v70
	v_and_b32_e32 v69, 0xffff0000, v70
	v_lshlrev_b32_e32 v70, 16, v71
	v_and_b32_e32 v71, 0xffff0000, v71
	v_lshlrev_b32_e32 v72, 16, v74
	v_and_b32_e32 v73, 0xffff0000, v74
	v_lshlrev_b32_e32 v74, 16, v75
	v_and_b32_e32 v75, 0xffff0000, v75
	v_lshlrev_b32_e32 v76, 16, v78
	v_and_b32_e32 v77, 0xffff0000, v78
	v_lshlrev_b32_e32 v78, 16, v79
	v_and_b32_e32 v79, 0xffff0000, v79
	v_lshlrev_b32_e32 v96, 16, v98
	v_and_b32_e32 v97, 0xffff0000, v98
	v_lshlrev_b32_e32 v98, 16, v99
	v_and_b32_e32 v99, 0xffff0000, v99
	v_lshlrev_b32_e32 v100, 16, v102
	v_and_b32_e32 v101, 0xffff0000, v102
	v_lshlrev_b32_e32 v102, 16, v103
	v_and_b32_e32 v103, 0xffff0000, v103
	v_lshlrev_b32_e32 v104, 16, v106
	v_and_b32_e32 v105, 0xffff0000, v106
	v_lshlrev_b32_e32 v106, 16, v107
	v_and_b32_e32 v107, 0xffff0000, v107
	v_lshlrev_b32_e32 v108, 16, v110
	v_and_b32_e32 v109, 0xffff0000, v110
	v_lshlrev_b32_e32 v110, 16, v111
	v_and_b32_e32 v111, 0xffff0000, v111
	v_mul_f32_e32 v10, v64, v64
	v_fmac_f32_e32 v10, v65, v65
	v_fmac_f32_e32 v10, v66, v66
	v_fmac_f32_e32 v10, v67, v67
	v_fmac_f32_e32 v10, v68, v68
	v_fmac_f32_e32 v10, v69, v69
	v_fmac_f32_e32 v10, v70, v70
	v_fmac_f32_e32 v10, v71, v71
	v_fmac_f32_e32 v10, v72, v72
	v_fmac_f32_e32 v10, v73, v73
	v_fmac_f32_e32 v10, v74, v74
	v_fmac_f32_e32 v10, v75, v75
	v_fmac_f32_e32 v10, v76, v76
	v_fmac_f32_e32 v10, v77, v77
	v_fmac_f32_e32 v10, v78, v78
	v_fmac_f32_e32 v10, v79, v79
	v_mul_f32_e32 v11, v96, v96
	v_fmac_f32_e32 v11, v97, v97
	v_fmac_f32_e32 v11, v98, v98
	v_fmac_f32_e32 v11, v99, v99
	v_fmac_f32_e32 v11, v100, v100
	v_fmac_f32_e32 v11, v101, v101
	v_fmac_f32_e32 v11, v102, v102
	v_fmac_f32_e32 v11, v103, v103
	v_fmac_f32_e32 v11, v104, v104
	v_fmac_f32_e32 v11, v105, v105
	v_fmac_f32_e32 v11, v106, v106
	v_fmac_f32_e32 v11, v107, v107
	v_fmac_f32_e32 v11, v108, v108
	v_fmac_f32_e32 v11, v109, v109
	v_fmac_f32_e32 v11, v110, v110
	v_fmac_f32_e32 v11, v111, v111
	ds_bpermute_b32 v12, v4, v10
	ds_bpermute_b32 v13, v4, v11
	s_waitcnt lgkmcnt(0)
	v_add_f32_e32 v10, v10, v12
	v_add_f32_e32 v11, v11, v13
	ds_bpermute_b32 v12, v5, v10
	ds_bpermute_b32 v13, v5, v11
	s_waitcnt lgkmcnt(0)
	v_add_f32_e32 v10, v10, v12
	v_add_f32_e32 v11, v11, v13
	ds_bpermute_b32 v12, v6, v10
	ds_bpermute_b32 v13, v6, v11
	s_waitcnt lgkmcnt(0)
	v_add_f32_e32 v10, v10, v12
	v_add_f32_e32 v11, v11, v13
	ds_bpermute_b32 v12, v7, v10
	ds_bpermute_b32 v13, v7, v11
	s_waitcnt lgkmcnt(0)
	v_add_f32_e32 v10, v10, v12
	v_add_f32_e32 v11, v11, v13
	ds_bpermute_b32 v12, v8, v10
	ds_bpermute_b32 v13, v8, v11
	s_waitcnt lgkmcnt(0)
	v_add_f32_e32 v10, v10, v12
	v_add_f32_e32 v11, v11, v13
	ds_bpermute_b32 v12, v9, v10
	ds_bpermute_b32 v13, v9, v11
	s_waitcnt lgkmcnt(0)
	v_add_f32_e32 v10, v10, v12
	v_add_f32_e32 v11, v11, v13
	v_fma_f32 v14, v10, s17, v3
	v_fma_f32 v15, v11, s17, v3
	v_rsq_f32_e32 v14, v14
	v_rsq_f32_e32 v15, v15
	s_nop 0
	v_mul_f32_e32 v64, v64, v14
	v_mul_f32_e32 v65, v65, v14
	v_mul_f32_e32 v66, v66, v14
	v_mul_f32_e32 v67, v67, v14
	v_mul_f32_e32 v68, v68, v14
	v_mul_f32_e32 v69, v69, v14
	v_mul_f32_e32 v70, v70, v14
	v_mul_f32_e32 v71, v71, v14
	v_mul_f32_e32 v72, v72, v14
	v_mul_f32_e32 v73, v73, v14
	v_mul_f32_e32 v74, v74, v14
	v_mul_f32_e32 v75, v75, v14
	v_mul_f32_e32 v76, v76, v14
	v_mul_f32_e32 v77, v77, v14
	v_mul_f32_e32 v78, v78, v14
	v_mul_f32_e32 v79, v79, v14
	v_fmac_f32_e32 v80, v64, v20
	v_fmac_f32_e32 v81, v65, v21
	v_fmac_f32_e32 v82, v66, v22
	v_fmac_f32_e32 v83, v67, v23
	v_fmac_f32_e32 v84, v68, v24
	v_fmac_f32_e32 v85, v69, v25
	v_fmac_f32_e32 v86, v70, v26
	v_fmac_f32_e32 v87, v71, v27
	v_fmac_f32_e32 v88, v72, v28
	v_fmac_f32_e32 v89, v73, v29
	v_fmac_f32_e32 v90, v74, v30
	v_fmac_f32_e32 v91, v75, v31
	v_fmac_f32_e32 v92, v76, v32
	v_fmac_f32_e32 v93, v77, v33
	v_fmac_f32_e32 v94, v78, v34
	v_fmac_f32_e32 v95, v79, v35
	global_store_dwordx4 v1, v[80:83], s[24:25] offset:0 nt
	global_store_dwordx4 v1, v[84:87], s[24:25] offset:1024 nt
	global_store_dwordx4 v1, v[88:91], s[24:25] offset:2048 nt
	global_store_dwordx4 v1, v[92:95], s[24:25] offset:3072 nt
	v_mul_f32_e32 v96, v96, v15
	v_mul_f32_e32 v97, v97, v15
	v_mul_f32_e32 v98, v98, v15
	v_mul_f32_e32 v99, v99, v15
	v_mul_f32_e32 v100, v100, v15
	v_mul_f32_e32 v101, v101, v15
	v_mul_f32_e32 v102, v102, v15
	v_mul_f32_e32 v103, v103, v15
	v_mul_f32_e32 v104, v104, v15
	v_mul_f32_e32 v105, v105, v15
	v_mul_f32_e32 v106, v106, v15
	v_mul_f32_e32 v107, v107, v15
	v_mul_f32_e32 v108, v108, v15
	v_mul_f32_e32 v109, v109, v15
	v_mul_f32_e32 v110, v110, v15
	v_mul_f32_e32 v111, v111, v15
	v_fmac_f32_e32 v112, v96, v20
	v_fmac_f32_e32 v113, v97, v21
	v_fmac_f32_e32 v114, v98, v22
	v_fmac_f32_e32 v115, v99, v23
	v_fmac_f32_e32 v116, v100, v24
	v_fmac_f32_e32 v117, v101, v25
	v_fmac_f32_e32 v118, v102, v26
	v_fmac_f32_e32 v119, v103, v27
	v_fmac_f32_e32 v120, v104, v28
	v_fmac_f32_e32 v121, v105, v29
	v_fmac_f32_e32 v122, v106, v30
	v_fmac_f32_e32 v123, v107, v31
	v_fmac_f32_e32 v124, v108, v32
	v_fmac_f32_e32 v125, v109, v33
	v_fmac_f32_e32 v126, v110, v34
	v_fmac_f32_e32 v127, v111, v35
	global_store_dwordx4 v1, v[112:115], s[32:33] offset:0 nt
	global_store_dwordx4 v1, v[116:119], s[32:33] offset:1024 nt
	global_store_dwordx4 v1, v[120:123], s[32:33] offset:2048 nt
	global_store_dwordx4 v1, v[124:127], s[32:33] offset:3072 nt
	v_mul_f32_e32 v10, v80, v80
	v_fmac_f32_e32 v10, v81, v81
	v_fmac_f32_e32 v10, v82, v82
	v_fmac_f32_e32 v10, v83, v83
	v_fmac_f32_e32 v10, v84, v84
	v_fmac_f32_e32 v10, v85, v85
	v_fmac_f32_e32 v10, v86, v86
	v_fmac_f32_e32 v10, v87, v87
	v_fmac_f32_e32 v10, v88, v88
	v_fmac_f32_e32 v10, v89, v89
	v_fmac_f32_e32 v10, v90, v90
	v_fmac_f32_e32 v10, v91, v91
	v_fmac_f32_e32 v10, v92, v92
	v_fmac_f32_e32 v10, v93, v93
	v_fmac_f32_e32 v10, v94, v94
	v_fmac_f32_e32 v10, v95, v95
	v_mul_f32_e32 v11, v112, v112
	v_fmac_f32_e32 v11, v113, v113
	v_fmac_f32_e32 v11, v114, v114
	v_fmac_f32_e32 v11, v115, v115
	v_fmac_f32_e32 v11, v116, v116
	v_fmac_f32_e32 v11, v117, v117
	v_fmac_f32_e32 v11, v118, v118
	v_fmac_f32_e32 v11, v119, v119
	v_fmac_f32_e32 v11, v120, v120
	v_fmac_f32_e32 v11, v121, v121
	v_fmac_f32_e32 v11, v122, v122
	v_fmac_f32_e32 v11, v123, v123
	v_fmac_f32_e32 v11, v124, v124
	v_fmac_f32_e32 v11, v125, v125
	v_fmac_f32_e32 v11, v126, v126
	v_fmac_f32_e32 v11, v127, v127
	ds_bpermute_b32 v12, v4, v10
	ds_bpermute_b32 v13, v4, v11
	s_waitcnt lgkmcnt(0)
	v_add_f32_e32 v10, v10, v12
	v_add_f32_e32 v11, v11, v13
	ds_bpermute_b32 v12, v5, v10
	ds_bpermute_b32 v13, v5, v11
	s_waitcnt lgkmcnt(0)
	v_add_f32_e32 v10, v10, v12
	v_add_f32_e32 v11, v11, v13
	ds_bpermute_b32 v12, v6, v10
	ds_bpermute_b32 v13, v6, v11
	s_waitcnt lgkmcnt(0)
	v_add_f32_e32 v10, v10, v12
	v_add_f32_e32 v11, v11, v13
	ds_bpermute_b32 v12, v7, v10
	ds_bpermute_b32 v13, v7, v11
	s_waitcnt lgkmcnt(0)
	v_add_f32_e32 v10, v10, v12
	v_add_f32_e32 v11, v11, v13
	ds_bpermute_b32 v12, v8, v10
	ds_bpermute_b32 v13, v8, v11
	s_waitcnt lgkmcnt(0)
	v_add_f32_e32 v10, v10, v12
	v_add_f32_e32 v11, v11, v13
	ds_bpermute_b32 v12, v9, v10
	ds_bpermute_b32 v13, v9, v11
	s_waitcnt lgkmcnt(0)
	v_add_f32_e32 v10, v10, v12
	v_add_f32_e32 v11, v11, v13
	v_fma_f32 v14, v10, s17, v3
	v_fma_f32 v15, v11, s17, v3
	v_rsq_f32_e32 v14, v14
	v_rsq_f32_e32 v15, v15
	s_nop 0
	v_mul_f32_e32 v64, v80, v14
	v_mul_f32_e32 v65, v81, v14
	v_mul_f32_e32 v66, v82, v14
	v_mul_f32_e32 v67, v83, v14
	v_mul_f32_e32 v68, v84, v14
	v_mul_f32_e32 v69, v85, v14
	v_mul_f32_e32 v70, v86, v14
	v_mul_f32_e32 v71, v87, v14
	v_mul_f32_e32 v72, v88, v14
	v_mul_f32_e32 v73, v89, v14
	v_mul_f32_e32 v74, v90, v14
	v_mul_f32_e32 v75, v91, v14
	v_mul_f32_e32 v76, v92, v14
	v_mul_f32_e32 v77, v93, v14
	v_mul_f32_e32 v78, v94, v14
	v_mul_f32_e32 v79, v95, v14
	v_mul_f32_e32 v64, v64, v36
	v_mul_f32_e32 v65, v65, v37
	v_mul_f32_e32 v66, v66, v38
	v_mul_f32_e32 v67, v67, v39
	v_mul_f32_e32 v68, v68, v40
	v_mul_f32_e32 v69, v69, v41
	v_mul_f32_e32 v70, v70, v42
	v_mul_f32_e32 v71, v71, v43
	v_mul_f32_e32 v72, v72, v44
	v_mul_f32_e32 v73, v73, v45
	v_mul_f32_e32 v74, v74, v46
	v_mul_f32_e32 v75, v75, v47
	v_mul_f32_e32 v76, v76, v48
	v_mul_f32_e32 v77, v77, v49
	v_mul_f32_e32 v78, v78, v50
	v_mul_f32_e32 v79, v79, v51
	v_cvt_pk_bf16_f32 v64, v64, v65
	v_cvt_pk_bf16_f32 v65, v66, v67
	v_cvt_pk_bf16_f32 v68, v68, v69
	v_cvt_pk_bf16_f32 v69, v70, v71
	v_cvt_pk_bf16_f32 v72, v72, v73
	v_cvt_pk_bf16_f32 v73, v74, v75
	v_cvt_pk_bf16_f32 v76, v76, v77
	v_cvt_pk_bf16_f32 v77, v78, v79
	global_store_dwordx2 v2, v[64:65], s[26:27] offset:0
	global_store_dwordx2 v2, v[68:69], s[26:27] offset:512
	global_store_dwordx2 v2, v[72:73], s[26:27] offset:1024
	global_store_dwordx2 v2, v[76:77], s[26:27] offset:1536
	v_mul_f32_e32 v96, v112, v15
	v_mul_f32_e32 v97, v113, v15
	v_mul_f32_e32 v98, v114, v15
	v_mul_f32_e32 v99, v115, v15
	v_mul_f32_e32 v100, v116, v15
	v_mul_f32_e32 v101, v117, v15
	v_mul_f32_e32 v102, v118, v15
	v_mul_f32_e32 v103, v119, v15
	v_mul_f32_e32 v104, v120, v15
	v_mul_f32_e32 v105, v121, v15
	v_mul_f32_e32 v106, v122, v15
	v_mul_f32_e32 v107, v123, v15
	v_mul_f32_e32 v108, v124, v15
	v_mul_f32_e32 v109, v125, v15
	v_mul_f32_e32 v110, v126, v15
	v_mul_f32_e32 v111, v127, v15
	v_mul_f32_e32 v96, v96, v36
	v_mul_f32_e32 v97, v97, v37
	v_mul_f32_e32 v98, v98, v38
	v_mul_f32_e32 v99, v99, v39
	v_mul_f32_e32 v100, v100, v40
	v_mul_f32_e32 v101, v101, v41
	v_mul_f32_e32 v102, v102, v42
	v_mul_f32_e32 v103, v103, v43
	v_mul_f32_e32 v104, v104, v44
	v_mul_f32_e32 v105, v105, v45
	v_mul_f32_e32 v106, v106, v46
	v_mul_f32_e32 v107, v107, v47
	v_mul_f32_e32 v108, v108, v48
	v_mul_f32_e32 v109, v109, v49
	v_mul_f32_e32 v110, v110, v50
	v_mul_f32_e32 v111, v111, v51
	v_cvt_pk_bf16_f32 v96, v96, v97
	v_cvt_pk_bf16_f32 v97, v98, v99
	v_cvt_pk_bf16_f32 v100, v100, v101
	v_cvt_pk_bf16_f32 v101, v102, v103
	v_cvt_pk_bf16_f32 v104, v104, v105
	v_cvt_pk_bf16_f32 v105, v106, v107
	v_cvt_pk_bf16_f32 v108, v108, v109
	v_cvt_pk_bf16_f32 v109, v110, v111
	global_store_dwordx2 v2, v[96:97], s[34:35] offset:0
	global_store_dwordx2 v2, v[100:101], s[34:35] offset:512
	global_store_dwordx2 v2, v[104:105], s[34:35] offset:1024
	global_store_dwordx2 v2, v[108:109], s[34:35] offset:1536
	s_waitcnt vmcnt(16)
	v_lshlrev_b32_e32 v128, 16, v130
	v_and_b32_e32 v129, 0xffff0000, v130
	v_lshlrev_b32_e32 v130, 16, v131
	v_and_b32_e32 v131, 0xffff0000, v131
	v_lshlrev_b32_e32 v132, 16, v134
	v_and_b32_e32 v133, 0xffff0000, v134
	v_lshlrev_b32_e32 v134, 16, v135
	v_and_b32_e32 v135, 0xffff0000, v135
	v_lshlrev_b32_e32 v136, 16, v138
	v_and_b32_e32 v137, 0xffff0000, v138
	v_lshlrev_b32_e32 v138, 16, v139
	v_and_b32_e32 v139, 0xffff0000, v139
	v_lshlrev_b32_e32 v140, 16, v142
	v_and_b32_e32 v141, 0xffff0000, v142
	v_lshlrev_b32_e32 v142, 16, v143
	v_and_b32_e32 v143, 0xffff0000, v143
	v_lshlrev_b32_e32 v160, 16, v162
	v_and_b32_e32 v161, 0xffff0000, v162
	v_lshlrev_b32_e32 v162, 16, v163
	v_and_b32_e32 v163, 0xffff0000, v163
	v_lshlrev_b32_e32 v164, 16, v166
	v_and_b32_e32 v165, 0xffff0000, v166
	v_lshlrev_b32_e32 v166, 16, v167
	v_and_b32_e32 v167, 0xffff0000, v167
	v_lshlrev_b32_e32 v168, 16, v170
	v_and_b32_e32 v169, 0xffff0000, v170
	v_lshlrev_b32_e32 v170, 16, v171
	v_and_b32_e32 v171, 0xffff0000, v171
	v_lshlrev_b32_e32 v172, 16, v174
	v_and_b32_e32 v173, 0xffff0000, v174
	v_lshlrev_b32_e32 v174, 16, v175
	v_and_b32_e32 v175, 0xffff0000, v175
	v_mul_f32_e32 v10, v128, v128
	v_fmac_f32_e32 v10, v129, v129
	v_fmac_f32_e32 v10, v130, v130
	v_fmac_f32_e32 v10, v131, v131
	v_fmac_f32_e32 v10, v132, v132
	v_fmac_f32_e32 v10, v133, v133
	v_fmac_f32_e32 v10, v134, v134
	v_fmac_f32_e32 v10, v135, v135
	v_fmac_f32_e32 v10, v136, v136
	v_fmac_f32_e32 v10, v137, v137
	v_fmac_f32_e32 v10, v138, v138
	v_fmac_f32_e32 v10, v139, v139
	v_fmac_f32_e32 v10, v140, v140
	v_fmac_f32_e32 v10, v141, v141
	v_fmac_f32_e32 v10, v142, v142
	v_fmac_f32_e32 v10, v143, v143
	v_mul_f32_e32 v11, v160, v160
	v_fmac_f32_e32 v11, v161, v161
	v_fmac_f32_e32 v11, v162, v162
	v_fmac_f32_e32 v11, v163, v163
	v_fmac_f32_e32 v11, v164, v164
	v_fmac_f32_e32 v11, v165, v165
	v_fmac_f32_e32 v11, v166, v166
	v_fmac_f32_e32 v11, v167, v167
	v_fmac_f32_e32 v11, v168, v168
	v_fmac_f32_e32 v11, v169, v169
	v_fmac_f32_e32 v11, v170, v170
	v_fmac_f32_e32 v11, v171, v171
	v_fmac_f32_e32 v11, v172, v172
	v_fmac_f32_e32 v11, v173, v173
	v_fmac_f32_e32 v11, v174, v174
	v_fmac_f32_e32 v11, v175, v175
	ds_bpermute_b32 v12, v4, v10
	ds_bpermute_b32 v13, v4, v11
	s_waitcnt lgkmcnt(0)
	v_add_f32_e32 v10, v10, v12
	v_add_f32_e32 v11, v11, v13
	ds_bpermute_b32 v12, v5, v10
	ds_bpermute_b32 v13, v5, v11
	s_waitcnt lgkmcnt(0)
	v_add_f32_e32 v10, v10, v12
	v_add_f32_e32 v11, v11, v13
	ds_bpermute_b32 v12, v6, v10
	ds_bpermute_b32 v13, v6, v11
	s_waitcnt lgkmcnt(0)
	v_add_f32_e32 v10, v10, v12
	v_add_f32_e32 v11, v11, v13
	ds_bpermute_b32 v12, v7, v10
	ds_bpermute_b32 v13, v7, v11
	s_waitcnt lgkmcnt(0)
	v_add_f32_e32 v10, v10, v12
	v_add_f32_e32 v11, v11, v13
	ds_bpermute_b32 v12, v8, v10
	ds_bpermute_b32 v13, v8, v11
	s_waitcnt lgkmcnt(0)
	v_add_f32_e32 v10, v10, v12
	v_add_f32_e32 v11, v11, v13
	ds_bpermute_b32 v12, v9, v10
	ds_bpermute_b32 v13, v9, v11
	s_waitcnt lgkmcnt(0)
	v_add_f32_e32 v10, v10, v12
	v_add_f32_e32 v11, v11, v13
	v_fma_f32 v14, v10, s17, v3
	v_fma_f32 v15, v11, s17, v3
	v_rsq_f32_e32 v14, v14
	v_rsq_f32_e32 v15, v15
	s_nop 0
	v_mul_f32_e32 v128, v128, v14
	v_mul_f32_e32 v129, v129, v14
	v_mul_f32_e32 v130, v130, v14
	v_mul_f32_e32 v131, v131, v14
	v_mul_f32_e32 v132, v132, v14
	v_mul_f32_e32 v133, v133, v14
	v_mul_f32_e32 v134, v134, v14
	v_mul_f32_e32 v135, v135, v14
	v_mul_f32_e32 v136, v136, v14
	v_mul_f32_e32 v137, v137, v14
	v_mul_f32_e32 v138, v138, v14
	v_mul_f32_e32 v139, v139, v14
	v_mul_f32_e32 v140, v140, v14
	v_mul_f32_e32 v141, v141, v14
	v_mul_f32_e32 v142, v142, v14
	v_mul_f32_e32 v143, v143, v14
	v_fmac_f32_e32 v144, v128, v20
	v_fmac_f32_e32 v145, v129, v21
	v_fmac_f32_e32 v146, v130, v22
	v_fmac_f32_e32 v147, v131, v23
	v_fmac_f32_e32 v148, v132, v24
	v_fmac_f32_e32 v149, v133, v25
	v_fmac_f32_e32 v150, v134, v26
	v_fmac_f32_e32 v151, v135, v27
	v_fmac_f32_e32 v152, v136, v28
	v_fmac_f32_e32 v153, v137, v29
	v_fmac_f32_e32 v154, v138, v30
	v_fmac_f32_e32 v155, v139, v31
	v_fmac_f32_e32 v156, v140, v32
	v_fmac_f32_e32 v157, v141, v33
	v_fmac_f32_e32 v158, v142, v34
	v_fmac_f32_e32 v159, v143, v35
	global_store_dwordx4 v1, v[144:147], s[40:41] offset:0 nt
	global_store_dwordx4 v1, v[148:151], s[40:41] offset:1024 nt
	global_store_dwordx4 v1, v[152:155], s[40:41] offset:2048 nt
	global_store_dwordx4 v1, v[156:159], s[40:41] offset:3072 nt
	v_mul_f32_e32 v160, v160, v15
	v_mul_f32_e32 v161, v161, v15
	v_mul_f32_e32 v162, v162, v15
	v_mul_f32_e32 v163, v163, v15
	v_mul_f32_e32 v164, v164, v15
	v_mul_f32_e32 v165, v165, v15
	v_mul_f32_e32 v166, v166, v15
	v_mul_f32_e32 v167, v167, v15
	v_mul_f32_e32 v168, v168, v15
	v_mul_f32_e32 v169, v169, v15
	v_mul_f32_e32 v170, v170, v15
	v_mul_f32_e32 v171, v171, v15
	v_mul_f32_e32 v172, v172, v15
	v_mul_f32_e32 v173, v173, v15
	v_mul_f32_e32 v174, v174, v15
	v_mul_f32_e32 v175, v175, v15
	v_fmac_f32_e32 v176, v160, v20
	v_fmac_f32_e32 v177, v161, v21
	v_fmac_f32_e32 v178, v162, v22
	v_fmac_f32_e32 v179, v163, v23
	v_fmac_f32_e32 v180, v164, v24
	v_fmac_f32_e32 v181, v165, v25
	v_fmac_f32_e32 v182, v166, v26
	v_fmac_f32_e32 v183, v167, v27
	v_fmac_f32_e32 v184, v168, v28
	v_fmac_f32_e32 v185, v169, v29
	v_fmac_f32_e32 v186, v170, v30
	v_fmac_f32_e32 v187, v171, v31
	v_fmac_f32_e32 v188, v172, v32
	v_fmac_f32_e32 v189, v173, v33
	v_fmac_f32_e32 v190, v174, v34
	v_fmac_f32_e32 v191, v175, v35
	global_store_dwordx4 v1, v[176:179], s[48:49] offset:0 nt
	global_store_dwordx4 v1, v[180:183], s[48:49] offset:1024 nt
	global_store_dwordx4 v1, v[184:187], s[48:49] offset:2048 nt
	global_store_dwordx4 v1, v[188:191], s[48:49] offset:3072 nt
	v_mul_f32_e32 v10, v144, v144
	v_fmac_f32_e32 v10, v145, v145
	v_fmac_f32_e32 v10, v146, v146
	v_fmac_f32_e32 v10, v147, v147
	v_fmac_f32_e32 v10, v148, v148
	v_fmac_f32_e32 v10, v149, v149
	v_fmac_f32_e32 v10, v150, v150
	v_fmac_f32_e32 v10, v151, v151
	v_fmac_f32_e32 v10, v152, v152
	v_fmac_f32_e32 v10, v153, v153
	v_fmac_f32_e32 v10, v154, v154
	v_fmac_f32_e32 v10, v155, v155
	v_fmac_f32_e32 v10, v156, v156
	v_fmac_f32_e32 v10, v157, v157
	v_fmac_f32_e32 v10, v158, v158
	v_fmac_f32_e32 v10, v159, v159
	v_mul_f32_e32 v11, v176, v176
	v_fmac_f32_e32 v11, v177, v177
	v_fmac_f32_e32 v11, v178, v178
	v_fmac_f32_e32 v11, v179, v179
	v_fmac_f32_e32 v11, v180, v180
	v_fmac_f32_e32 v11, v181, v181
	v_fmac_f32_e32 v11, v182, v182
	v_fmac_f32_e32 v11, v183, v183
	v_fmac_f32_e32 v11, v184, v184
	v_fmac_f32_e32 v11, v185, v185
	v_fmac_f32_e32 v11, v186, v186
	v_fmac_f32_e32 v11, v187, v187
	v_fmac_f32_e32 v11, v188, v188
	v_fmac_f32_e32 v11, v189, v189
	v_fmac_f32_e32 v11, v190, v190
	v_fmac_f32_e32 v11, v191, v191
	ds_bpermute_b32 v12, v4, v10
	ds_bpermute_b32 v13, v4, v11
	s_waitcnt lgkmcnt(0)
	v_add_f32_e32 v10, v10, v12
	v_add_f32_e32 v11, v11, v13
	ds_bpermute_b32 v12, v5, v10
	ds_bpermute_b32 v13, v5, v11
	s_waitcnt lgkmcnt(0)
	v_add_f32_e32 v10, v10, v12
	v_add_f32_e32 v11, v11, v13
	ds_bpermute_b32 v12, v6, v10
	ds_bpermute_b32 v13, v6, v11
	s_waitcnt lgkmcnt(0)
	v_add_f32_e32 v10, v10, v12
	v_add_f32_e32 v11, v11, v13
	ds_bpermute_b32 v12, v7, v10
	ds_bpermute_b32 v13, v7, v11
	s_waitcnt lgkmcnt(0)
	v_add_f32_e32 v10, v10, v12
	v_add_f32_e32 v11, v11, v13
	ds_bpermute_b32 v12, v8, v10
	ds_bpermute_b32 v13, v8, v11
	s_waitcnt lgkmcnt(0)
	v_add_f32_e32 v10, v10, v12
	v_add_f32_e32 v11, v11, v13
	ds_bpermute_b32 v12, v9, v10
	ds_bpermute_b32 v13, v9, v11
	s_waitcnt lgkmcnt(0)
	v_add_f32_e32 v10, v10, v12
	v_add_f32_e32 v11, v11, v13
	v_fma_f32 v14, v10, s17, v3
	v_fma_f32 v15, v11, s17, v3
	v_rsq_f32_e32 v14, v14
	v_rsq_f32_e32 v15, v15
	s_nop 0
	v_mul_f32_e32 v128, v144, v14
	v_mul_f32_e32 v129, v145, v14
	v_mul_f32_e32 v130, v146, v14
	v_mul_f32_e32 v131, v147, v14
	v_mul_f32_e32 v132, v148, v14
	v_mul_f32_e32 v133, v149, v14
	v_mul_f32_e32 v134, v150, v14
	v_mul_f32_e32 v135, v151, v14
	v_mul_f32_e32 v136, v152, v14
	v_mul_f32_e32 v137, v153, v14
	v_mul_f32_e32 v138, v154, v14
	v_mul_f32_e32 v139, v155, v14
	v_mul_f32_e32 v140, v156, v14
	v_mul_f32_e32 v141, v157, v14
	v_mul_f32_e32 v142, v158, v14
	v_mul_f32_e32 v143, v159, v14
	v_mul_f32_e32 v128, v128, v36
	v_mul_f32_e32 v129, v129, v37
	v_mul_f32_e32 v130, v130, v38
	v_mul_f32_e32 v131, v131, v39
	v_mul_f32_e32 v132, v132, v40
	v_mul_f32_e32 v133, v133, v41
	v_mul_f32_e32 v134, v134, v42
	v_mul_f32_e32 v135, v135, v43
	v_mul_f32_e32 v136, v136, v44
	v_mul_f32_e32 v137, v137, v45
	v_mul_f32_e32 v138, v138, v46
	v_mul_f32_e32 v139, v139, v47
	v_mul_f32_e32 v140, v140, v48
	v_mul_f32_e32 v141, v141, v49
	v_mul_f32_e32 v142, v142, v50
	v_mul_f32_e32 v143, v143, v51
	v_cvt_pk_bf16_f32 v128, v128, v129
	v_cvt_pk_bf16_f32 v129, v130, v131
	v_cvt_pk_bf16_f32 v132, v132, v133
	v_cvt_pk_bf16_f32 v133, v134, v135
	v_cvt_pk_bf16_f32 v136, v136, v137
	v_cvt_pk_bf16_f32 v137, v138, v139
	v_cvt_pk_bf16_f32 v140, v140, v141
	v_cvt_pk_bf16_f32 v141, v142, v143
	global_store_dwordx2 v2, v[128:129], s[42:43] offset:0
	global_store_dwordx2 v2, v[132:133], s[42:43] offset:512
	global_store_dwordx2 v2, v[136:137], s[42:43] offset:1024
	global_store_dwordx2 v2, v[140:141], s[42:43] offset:1536
	v_mul_f32_e32 v160, v176, v15
	v_mul_f32_e32 v161, v177, v15
	v_mul_f32_e32 v162, v178, v15
	v_mul_f32_e32 v163, v179, v15
	v_mul_f32_e32 v164, v180, v15
	v_mul_f32_e32 v165, v181, v15
	v_mul_f32_e32 v166, v182, v15
	v_mul_f32_e32 v167, v183, v15
	v_mul_f32_e32 v168, v184, v15
	v_mul_f32_e32 v169, v185, v15
	v_mul_f32_e32 v170, v186, v15
	v_mul_f32_e32 v171, v187, v15
	v_mul_f32_e32 v172, v188, v15
	v_mul_f32_e32 v173, v189, v15
	v_mul_f32_e32 v174, v190, v15
	v_mul_f32_e32 v175, v191, v15
	v_mul_f32_e32 v160, v160, v36
	v_mul_f32_e32 v161, v161, v37
	v_mul_f32_e32 v162, v162, v38
	v_mul_f32_e32 v163, v163, v39
	v_mul_f32_e32 v164, v164, v40
	v_mul_f32_e32 v165, v165, v41
	v_mul_f32_e32 v166, v166, v42
	v_mul_f32_e32 v167, v167, v43
	v_mul_f32_e32 v168, v168, v44
	v_mul_f32_e32 v169, v169, v45
	v_mul_f32_e32 v170, v170, v46
	v_mul_f32_e32 v171, v171, v47
	v_mul_f32_e32 v172, v172, v48
	v_mul_f32_e32 v173, v173, v49
	v_mul_f32_e32 v174, v174, v50
	v_mul_f32_e32 v175, v175, v51
	v_cvt_pk_bf16_f32 v160, v160, v161
	v_cvt_pk_bf16_f32 v161, v162, v163
	v_cvt_pk_bf16_f32 v164, v164, v165
	v_cvt_pk_bf16_f32 v165, v166, v167
	v_cvt_pk_bf16_f32 v168, v168, v169
	v_cvt_pk_bf16_f32 v169, v170, v171
	v_cvt_pk_bf16_f32 v172, v172, v173
	v_cvt_pk_bf16_f32 v173, v174, v175
	global_store_dwordx2 v2, v[160:161], s[50:51] offset:0
	global_store_dwordx2 v2, v[164:165], s[50:51] offset:512
	global_store_dwordx2 v2, v[168:169], s[50:51] offset:1024
	global_store_dwordx2 v2, v[172:173], s[50:51] offset:1536
	v_add_f32_e32 v208, v208, v212
	v_add_f32_e32 v209, v209, v213
	v_add_f32_e32 v210, v210, v214
	v_add_f32_e32 v211, v211, v215
	v_add_f32_e32 v216, v216, v220
	v_add_f32_e32 v217, v217, v221
	v_add_f32_e32 v218, v218, v222
	v_add_f32_e32 v219, v219, v223
	v_add_f32_e32 v224, v224, v228
	v_add_f32_e32 v225, v225, v229
	v_add_f32_e32 v226, v226, v230
	v_add_f32_e32 v227, v227, v231
	v_add_f32_e32 v232, v232, v236
	v_add_f32_e32 v233, v233, v237
	v_add_f32_e32 v234, v234, v238
	v_add_f32_e32 v235, v235, v239
	v_add_f32_e32 v208, v208, v216
	v_add_f32_e32 v209, v209, v217
	v_add_f32_e32 v210, v210, v218
	v_add_f32_e32 v211, v211, v219
	v_add_f32_e32 v224, v224, v232
	v_add_f32_e32 v225, v225, v233
	v_add_f32_e32 v226, v226, v234
	v_add_f32_e32 v227, v227, v235
	v_add_f32_e32 v208, v208, v224
	v_add_f32_e32 v209, v209, v225
	v_add_f32_e32 v210, v210, v226
	v_add_f32_e32 v211, v211, v227
	v_readfirstlane_b32 s18, v0
	s_lshr_b32 s18, s18, 6
	s_lshl_b32 s19, s18, 2
	s_and_b32 s52, s18, 4
	s_lshl_b32 s52, s52, 2
	v_mov_b32_e32 v16, s19
	v_mov_b32_e32 v17, s52
	v_mul_f32_e32 v10, v208, v208
	v_fmac_f32_e32 v10, v209, v209
	v_fmac_f32_e32 v10, v210, v210
	v_fmac_f32_e32 v10, v211, v211
	ds_bpermute_b32 v11, v4, v10
	s_waitcnt lgkmcnt(0)
	v_add_f32_e32 v10, v10, v11
	ds_bpermute_b32 v11, v5, v10
	s_waitcnt lgkmcnt(0)
	v_add_f32_e32 v10, v10, v11
	ds_bpermute_b32 v11, v6, v10
	s_waitcnt lgkmcnt(0)
	v_add_f32_e32 v10, v10, v11
	ds_bpermute_b32 v11, v7, v10
	s_waitcnt lgkmcnt(0)
	v_add_f32_e32 v10, v10, v11
	ds_bpermute_b32 v11, v8, v10
	s_waitcnt lgkmcnt(0)
	v_add_f32_e32 v10, v10, v11
	ds_bpermute_b32 v11, v9, v10
	s_waitcnt lgkmcnt(0)
	v_add_f32_e32 v10, v10, v11
	ds_write_b32 v16, v10 offset:0
	s_waitcnt lgkmcnt(0)
	s_barrier
	ds_read_b128 v[12:15], v17 offset:0
	s_waitcnt lgkmcnt(0)
	v_add_f32_e32 v12, v12, v13
	v_add_f32_e32 v14, v14, v15
	v_add_f32_e32 v10, v12, v14
	v_fma_f32 v11, v10, s17, v3
	v_rsq_f32_e32 v11, v11
	s_nop 0
	v_mul_f32_e32 v208, v208, v11
	v_mul_f32_e32 v209, v209, v11
	v_mul_f32_e32 v210, v210, v11
	v_mul_f32_e32 v211, v211, v11
	v_fmac_f32_e32 v240, v208, v244
	v_fmac_f32_e32 v241, v209, v245
	v_fmac_f32_e32 v242, v210, v246
	v_fmac_f32_e32 v243, v211, v247
	s_lshl_b32 s18, s54, 12
	s_add_u32 s18, s18, s55
	s_add_u32 s56, s4, s18
	s_addc_u32 s57, s5, 0
	s_add_u32 s56, s56, 0x4000000
	s_addc_u32 s57, s57, 0
	global_store_dwordx4 v1, v[240:243], s[56:57]
	v_mul_f32_e32 v10, v240, v240
	v_fmac_f32_e32 v10, v241, v241
	v_fmac_f32_e32 v10, v242, v242
	v_fmac_f32_e32 v10, v243, v243
	ds_bpermute_b32 v11, v4, v10
	s_waitcnt lgkmcnt(0)
	v_add_f32_e32 v10, v10, v11
	ds_bpermute_b32 v11, v5, v10
	s_waitcnt lgkmcnt(0)
	v_add_f32_e32 v10, v10, v11
	ds_bpermute_b32 v11, v6, v10
	s_waitcnt lgkmcnt(0)
	v_add_f32_e32 v10, v10, v11
	ds_bpermute_b32 v11, v7, v10
	s_waitcnt lgkmcnt(0)
	v_add_f32_e32 v10, v10, v11
	ds_bpermute_b32 v11, v8, v10
	s_waitcnt lgkmcnt(0)
	v_add_f32_e32 v10, v10, v11
	ds_bpermute_b32 v11, v9, v10
	s_waitcnt lgkmcnt(0)
	v_add_f32_e32 v10, v10, v11
	ds_write_b32 v16, v10 offset:64
	s_waitcnt lgkmcnt(0)
	s_barrier
	ds_read_b128 v[12:15], v17 offset:64
	s_waitcnt lgkmcnt(0)
	v_add_f32_e32 v12, v12, v13
	v_add_f32_e32 v14, v14, v15
	v_add_f32_e32 v10, v12, v14
	v_fma_f32 v11, v10, s17, v3
	v_rsq_f32_e32 v11, v11
	s_nop 0
	v_mul_f32_e32 v208, v240, v11
	v_mul_f32_e32 v209, v241, v11
	v_mul_f32_e32 v210, v242, v11
	v_mul_f32_e32 v211, v243, v11
	v_mul_f32_e32 v208, v208, v248
	v_mul_f32_e32 v209, v209, v249
	v_mul_f32_e32 v210, v210, v250
	v_mul_f32_e32 v211, v211, v251
	v_cvt_pk_bf16_f32 v208, v208, v209
	v_cvt_pk_bf16_f32 v209, v210, v211
	s_lshl_b32 s18, s54, 11
	s_lshr_b32 s19, s55, 1
	s_add_u32 s18, s18, s19
	s_add_u32 s56, s6, s18
	s_addc_u32 s57, s7, 0
	s_add_u32 s56, s56, 0x5100000
	s_addc_u32 s57, s57, 0
	global_store_dwordx2 v2, v[208:209], s[56:57]

_Z10fwd_kernelILi11ELi12EEv4Args:
	s_load_dword s3, s[0:1], 0xe8
	s_load_dwordx4 s[4:7], s[0:1], 0xd0
	s_load_dwordx2 s[8:9], s[0:1], 0xa8
	s_load_dwordx2 s[10:11], s[0:1], 0xb0
	s_waitcnt lgkmcnt(0)
	s_cmp_lg_u32 s3, 0x100
	s_cbranch_scc1 .Lrows11_orig
	s_add_u32 s8, s8, 0x1000
	s_addc_u32 s9, s9, 0
	s_add_u32 s10, s10, 0x1000
	s_addc_u32 s11, s11, 0
	v_readfirstlane_b32 s16, v0
	s_lshr_b32 s16, s16, 6
	s_lshl_b32 s18, s2, 3
	s_add_u32 s16, s16, s18
	s_mov_b32 s17, 0x3a800000
	v_mov_b32_e32 v3, 0x358637bd
	v_and_b32_e32 v10, 63, v0
	v_lshlrev_b32_e32 v1, 4, v10
	v_lshlrev_b32_e32 v2, 3, v10
	v_xor_b32_e32 v4, 1, v10
	v_xor_b32_e32 v5, 2, v10
	v_xor_b32_e32 v6, 4, v10
	v_xor_b32_e32 v7, 8, v10
	v_xor_b32_e32 v8, 16, v10
	v_xor_b32_e32 v9, 32, v10
	v_lshlrev_b32_e32 v4, 2, v4
	v_lshlrev_b32_e32 v5, 2, v5
	v_lshlrev_b32_e32 v6, 2, v6
	v_lshlrev_b32_e32 v7, 2, v7
	v_lshlrev_b32_e32 v8, 2, v8
	v_lshlrev_b32_e32 v9, 2, v9
	global_load_dwordx4 v[20:23], v1, s[8:9] offset:0
	global_load_dwordx4 v[24:27], v1, s[8:9] offset:1024
	global_load_dwordx4 v[28:31], v1, s[8:9] offset:2048
	global_load_dwordx4 v[32:35], v1, s[8:9] offset:3072
	global_load_dwordx4 v[36:39], v1, s[10:11] offset:0
	global_load_dwordx4 v[40:43], v1, s[10:11] offset:1024
	global_load_dwordx4 v[44:47], v1, s[10:11] offset:2048
	global_load_dwordx4 v[48:51], v1, s[10:11] offset:3072
	s_lshr_b32 s54, s16, 2
	s_and_b32 s55, s16, 3
	s_lshl_b32 s55, s55, 10
	s_lshl_b32 s18, s54, 12
	s_add_u32 s18, s18, s55
	s_add_u32 s56, s6, s18
	s_addc_u32 s57, s7, 0
	s_add_u32 s56, s56, 0x7400000
	s_addc_u32 s57, s57, 0
	global_load_dwordx4 v[208:211], v1, s[56:57]
	s_add_u32 s56, s56, 0x200000
	s_addc_u32 s57, s57, 0
	global_load_dwordx4 v[212:215], v1, s[56:57]
	s_add_u32 s56, s4, s18
	s_addc_u32 s57, s5, 0
	s_add_u32 s56, s56, 0x4000000
	s_addc_u32 s57, s57, 0
	global_load_dwordx4 v[240:243], v1, s[56:57]
	s_add_u32 s56, s8, s55
	s_addc_u32 s57, s9, 0
	global_load_dwordx4 v[244:247], v1, s[56:57]
	s_add_u32 s56, s10, s55
	s_addc_u32 s57, s11, 0
	global_load_dwordx4 v[248:251], v1, s[56:57]
	s_add_u32 s53, s16, 0x0
	s_lshl_b32 s18, s53, 12
	s_lshl_b32 s19, s53, 11
	s_add_u32 s20, s4, s18
	s_addc_u32 s21, s5, 0
	s_add_u32 s22, s6, s19
	s_addc_u32 s23, s7, 0
	s_add_u32 s22, s22, 0x5200000
	s_addc_u32 s23, s23, 0
	s_add_u32 s24, s4, s18
	s_addc_u32 s25, s5, 0
	s_add_u32 s26, s6, s19
	s_addc_u32 s27, s7, 0
	s_add_u32 s26, s26, 0x3100000
	s_addc_u32 s27, s27, 0
	global_load_dwordx2 v[66:67], v2, s[22:23] offset:0 nt
	global_load_dwordx2 v[70:71], v2, s[22:23] offset:512 nt
	global_load_dwordx2 v[74:75], v2, s[22:23] offset:1024 nt
	global_load_dwordx2 v[78:79], v2, s[22:23] offset:1536 nt
	global_load_dwordx4 v[80:83], v1, s[20:21] offset:0 nt
	global_load_dwordx4 v[84:87], v1, s[20:21] offset:1024 nt
	global_load_dwordx4 v[88:91], v1, s[20:21] offset:2048 nt
	global_load_dwordx4 v[92:95], v1, s[20:21] offset:3072 nt
	s_add_u32 s53, s16, 0x800
	s_lshl_b32 s18, s53, 12
	s_lshl_b32 s19, s53, 11
	s_add_u32 s28, s4, s18
	s_addc_u32 s29, s5, 0
	s_add_u32 s30, s6, s19
	s_addc_u32 s31, s7, 0
	s_add_u32 s30, s30, 0x5200000
	s_addc_u32 s31, s31, 0
	s_add_u32 s32, s4, s18
	s_addc_u32 s33, s5, 0
	s_add_u32 s34, s6, s19
	s_addc_u32 s35, s7, 0
	s_add_u32 s34, s34, 0x3100000
	s_addc_u32 s35, s35, 0
	global_load_dwordx2 v[98:99], v2, s[30:31] offset:0 nt
	global_load_dwordx2 v[102:103], v2, s[30:31] offset:512 nt
	global_load_dwordx2 v[106:107], v2, s[30:31] offset:1024 nt
	global_load_dwordx2 v[110:111], v2, s[30:31] offset:1536 nt
	global_load_dwordx4 v[112:115], v1, s[28:29] offset:0 nt
	global_load_dwordx4 v[116:119], v1, s[28:29] offset:1024 nt
	global_load_dwordx4 v[120:123], v1, s[28:29] offset:2048 nt
	global_load_dwordx4 v[124:127], v1, s[28:29] offset:3072 nt
	s_add_u32 s53, s16, 0x1000
	s_lshl_b32 s18, s53, 12
	s_lshl_b32 s19, s53, 11
	s_add_u32 s36, s4, s18
	s_addc_u32 s37, s5, 0
	s_add_u32 s38, s6, s19
	s_addc_u32 s39, s7, 0
	s_add_u32 s38, s38, 0x5200000
	s_addc_u32 s39, s39, 0
	s_add_u32 s40, s4, s18
	s_addc_u32 s41, s5, 0
	s_add_u32 s42, s6, s19
	s_addc_u32 s43, s7, 0
	s_add_u32 s42, s42, 0x3100000
	s_addc_u32 s43, s43, 0
	global_load_dwordx2 v[130:131], v2, s[38:39] offset:0 nt
	global_load_dwordx2 v[134:135], v2, s[38:39] offset:512 nt
	global_load_dwordx2 v[138:139], v2, s[38:39] offset:1024 nt
	global_load_dwordx2 v[142:143], v2, s[38:39] offset:1536 nt
	global_load_dwordx4 v[144:147], v1, s[36:37] offset:0 nt
	global_load_dwordx4 v[148:151], v1, s[36:37] offset:1024 nt
	global_load_dwordx4 v[152:155], v1, s[36:37] offset:2048 nt
	global_load_dwordx4 v[156:159], v1, s[36:37] offset:3072 nt
	s_add_u32 s53, s16, 0x1800
	s_lshl_b32 s18, s53, 12
	s_lshl_b32 s19, s53, 11
	s_add_u32 s44, s4, s18
	s_addc_u32 s45, s5, 0
	s_add_u32 s46, s6, s19
	s_addc_u32 s47, s7, 0
	s_add_u32 s46, s46, 0x5200000
	s_addc_u32 s47, s47, 0
	s_add_u32 s48, s4, s18
	s_addc_u32 s49, s5, 0
	s_add_u32 s50, s6, s19
	s_addc_u32 s51, s7, 0
	s_add_u32 s50, s50, 0x3100000
	s_addc_u32 s51, s51, 0
	global_load_dwordx2 v[162:163], v2, s[46:47] offset:0 nt
	global_load_dwordx2 v[166:167], v2, s[46:47] offset:512 nt
	global_load_dwordx2 v[170:171], v2, s[46:47] offset:1024 nt
	global_load_dwordx2 v[174:175], v2, s[46:47] offset:1536 nt
	global_load_dwordx4 v[176:179], v1, s[44:45] offset:0 nt
	global_load_dwordx4 v[180:183], v1, s[44:45] offset:1024 nt
	global_load_dwordx4 v[184:187], v1, s[44:45] offset:2048 nt
	global_load_dwordx4 v[188:191], v1, s[44:45] offset:3072 nt
	s_waitcnt vmcnt(16)
	v_lshlrev_b32_e32 v64, 16, v66
	v_and_b32_e32 v65, 0xffff0000, v66
	v_lshlrev_b32_e32 v66, 16, v67
	v_and_b32_e32 v67, 0xffff0000, v67
	v_lshlrev_b32_e32 v68, 16, v70
	v_and_b32_e32 v69, 0xffff0000, v70
	v_lshlrev_b32_e32 v70, 16, v71
	v_and_b32_e32 v71, 0xffff0000, v71
	v_lshlrev_b32_e32 v72, 16, v74
	v_and_b32_e32 v73, 0xffff0000, v74
	v_lshlrev_b32_e32 v74, 16, v75
	v_and_b32_e32 v75, 0xffff0000, v75
	v_lshlrev_b32_e32 v76, 16, v78
	v_and_b32_e32 v77, 0xffff0000, v78
	v_lshlrev_b32_e32 v78, 16, v79
	v_and_b32_e32 v79, 0xffff0000, v79
	v_lshlrev_b32_e32 v96, 16, v98
	v_and_b32_e32 v97, 0xffff0000, v98
	v_lshlrev_b32_e32 v98, 16, v99
	v_and_b32_e32 v99, 0xffff0000, v99
	v_lshlrev_b32_e32 v100, 16, v102
	v_and_b32_e32 v101, 0xffff0000, v102
	v_lshlrev_b32_e32 v102, 16, v103
	v_and_b32_e32 v103, 0xffff0000, v103
	v_lshlrev_b32_e32 v104, 16, v106
	v_and_b32_e32 v105, 0xffff0000, v106
	v_lshlrev_b32_e32 v106, 16, v107
	v_and_b32_e32 v107, 0xffff0000, v107
	v_lshlrev_b32_e32 v108, 16, v110
	v_and_b32_e32 v109, 0xffff0000, v110
	v_lshlrev_b32_e32 v110, 16, v111
	v_and_b32_e32 v111, 0xffff0000, v111
	v_mul_f32_e32 v10, v64, v64
	v_fmac_f32_e32 v10, v65, v65
	v_fmac_f32_e32 v10, v66, v66
	v_fmac_f32_e32 v10, v67, v67
	v_fmac_f32_e32 v10, v68, v68
	v_fmac_f32_e32 v10, v69, v69
	v_fmac_f32_e32 v10, v70, v70
	v_fmac_f32_e32 v10, v71, v71
	v_fmac_f32_e32 v10, v72, v72
	v_fmac_f32_e32 v10, v73, v73
	v_fmac_f32_e32 v10, v74, v74
	v_fmac_f32_e32 v10, v75, v75
	v_fmac_f32_e32 v10, v76, v76
	v_fmac_f32_e32 v10, v77, v77
	v_fmac_f32_e32 v10, v78, v78
	v_fmac_f32_e32 v10, v79, v79
	v_mul_f32_e32 v11, v96, v96
	v_fmac_f32_e32 v11, v97, v97
	v_fmac_f32_e32 v11, v98, v98
	v_fmac_f32_e32 v11, v99, v99
	v_fmac_f32_e32 v11, v100, v100
	v_fmac_f32_e32 v11, v101, v101
	v_fmac_f32_e32 v11, v102, v102
	v_fmac_f32_e32 v11, v103, v103
	v_fmac_f32_e32 v11, v104, v104
	v_fmac_f32_e32 v11, v105, v105
	v_fmac_f32_e32 v11, v106, v106
	v_fmac_f32_e32 v11, v107, v107
	v_fmac_f32_e32 v11, v108, v108
	v_fmac_f32_e32 v11, v109, v109
	v_fmac_f32_e32 v11, v110, v110
	v_fmac_f32_e32 v11, v111, v111
	ds_bpermute_b32 v12, v4, v10
	ds_bpermute_b32 v13, v4, v11
	s_waitcnt lgkmcnt(0)
	v_add_f32_e32 v10, v10, v12
	v_add_f32_e32 v11, v11, v13
	ds_bpermute_b32 v12, v5, v10
	ds_bpermute_b32 v13, v5, v11
	s_waitcnt lgkmcnt(0)
	v_add_f32_e32 v10, v10, v12
	v_add_f32_e32 v11, v11, v13
	ds_bpermute_b32 v12, v6, v10
	ds_bpermute_b32 v13, v6, v11
	s_waitcnt lgkmcnt(0)
	v_add_f32_e32 v10, v10, v12
	v_add_f32_e32 v11, v11, v13
	ds_bpermute_b32 v12, v7, v10
	ds_bpermute_b32 v13, v7, v11
	s_waitcnt lgkmcnt(0)
	v_add_f32_e32 v10, v10, v12
	v_add_f32_e32 v11, v11, v13
	ds_bpermute_b32 v12, v8, v10
	ds_bpermute_b32 v13, v8, v11
	s_waitcnt lgkmcnt(0)
	v_add_f32_e32 v10, v10, v12
	v_add_f32_e32 v11, v11, v13
	ds_bpermute_b32 v12, v9, v10
	ds_bpermute_b32 v13, v9, v11
	s_waitcnt lgkmcnt(0)
	v_add_f32_e32 v10, v10, v12
	v_add_f32_e32 v11, v11, v13
	v_fma_f32 v14, v10, s17, v3
	v_fma_f32 v15, v11, s17, v3
	v_rsq_f32_e32 v14, v14
	v_rsq_f32_e32 v15, v15
	s_nop 0
	v_mul_f32_e32 v64, v64, v14
	v_mul_f32_e32 v65, v65, v14
	v_mul_f32_e32 v66, v66, v14
	v_mul_f32_e32 v67, v67, v14
	v_mul_f32_e32 v68, v68, v14
	v_mul_f32_e32 v69, v69, v14
	v_mul_f32_e32 v70, v70, v14
	v_mul_f32_e32 v71, v71, v14
	v_mul_f32_e32 v72, v72, v14
	v_mul_f32_e32 v73, v73, v14
	v_mul_f32_e32 v74, v74, v14
	v_mul_f32_e32 v75, v75, v14
	v_mul_f32_e32 v76, v76, v14
	v_mul_f32_e32 v77, v77, v14
	v_mul_f32_e32 v78, v78, v14
	v_mul_f32_e32 v79, v79, v14
	v_fmac_f32_e32 v80, v64, v20
	v_fmac_f32_e32 v81, v65, v21
	v_fmac_f32_e32 v82, v66, v22
	v_fmac_f32_e32 v83, v67, v23
	v_fmac_f32_e32 v84, v68, v24
	v_fmac_f32_e32 v85, v69, v25
	v_fmac_f32_e32 v86, v70, v26
	v_fmac_f32_e32 v87, v71, v27
	v_fmac_f32_e32 v88, v72, v28
	v_fmac_f32_e32 v89, v73, v29
	v_fmac_f32_e32 v90, v74, v30
	v_fmac_f32_e32 v91, v75, v31
	v_fmac_f32_e32 v92, v76, v32
	v_fmac_f32_e32 v93, v77, v33
	v_fmac_f32_e32 v94, v78, v34
	v_fmac_f32_e32 v95, v79, v35
	global_store_dwordx4 v1, v[80:83], s[24:25] offset:0 nt
	global_store_dwordx4 v1, v[84:87], s[24:25] offset:1024 nt
	global_store_dwordx4 v1, v[88:91], s[24:25] offset:2048 nt
	global_store_dwordx4 v1, v[92:95], s[24:25] offset:3072 nt
	v_mul_f32_e32 v96, v96, v15
	v_mul_f32_e32 v97, v97, v15
	v_mul_f32_e32 v98, v98, v15
	v_mul_f32_e32 v99, v99, v15
	v_mul_f32_e32 v100, v100, v15
	v_mul_f32_e32 v101, v101, v15
	v_mul_f32_e32 v102, v102, v15
	v_mul_f32_e32 v103, v103, v15
	v_mul_f32_e32 v104, v104, v15
	v_mul_f32_e32 v105, v105, v15
	v_mul_f32_e32 v106, v106, v15
	v_mul_f32_e32 v107, v107, v15
	v_mul_f32_e32 v108, v108, v15
	v_mul_f32_e32 v109, v109, v15
	v_mul_f32_e32 v110, v110, v15
	v_mul_f32_e32 v111, v111, v15
	v_fmac_f32_e32 v112, v96, v20
	v_fmac_f32_e32 v113, v97, v21
	v_fmac_f32_e32 v114, v98, v22
	v_fmac_f32_e32 v115, v99, v23
	v_fmac_f32_e32 v116, v100, v24
	v_fmac_f32_e32 v117, v101, v25
	v_fmac_f32_e32 v118, v102, v26
	v_fmac_f32_e32 v119, v103, v27
	v_fmac_f32_e32 v120, v104, v28
	v_fmac_f32_e32 v121, v105, v29
	v_fmac_f32_e32 v122, v106, v30
	v_fmac_f32_e32 v123, v107, v31
	v_fmac_f32_e32 v124, v108, v32
	v_fmac_f32_e32 v125, v109, v33
	v_fmac_f32_e32 v126, v110, v34
	v_fmac_f32_e32 v127, v111, v35
	global_store_dwordx4 v1, v[112:115], s[32:33] offset:0 nt
	global_store_dwordx4 v1, v[116:119], s[32:33] offset:1024 nt
	global_store_dwordx4 v1, v[120:123], s[32:33] offset:2048 nt
	global_store_dwordx4 v1, v[124:127], s[32:33] offset:3072 nt
	v_mul_f32_e32 v10, v80, v80
	v_fmac_f32_e32 v10, v81, v81
	v_fmac_f32_e32 v10, v82, v82
	v_fmac_f32_e32 v10, v83, v83
	v_fmac_f32_e32 v10, v84, v84
	v_fmac_f32_e32 v10, v85, v85
	v_fmac_f32_e32 v10, v86, v86
	v_fmac_f32_e32 v10, v87, v87
	v_fmac_f32_e32 v10, v88, v88
	v_fmac_f32_e32 v10, v89, v89
	v_fmac_f32_e32 v10, v90, v90
	v_fmac_f32_e32 v10, v91, v91
	v_fmac_f32_e32 v10, v92, v92
	v_fmac_f32_e32 v10, v93, v93
	v_fmac_f32_e32 v10, v94, v94
	v_fmac_f32_e32 v10, v95, v95
	v_mul_f32_e32 v11, v112, v112
	v_fmac_f32_e32 v11, v113, v113
	v_fmac_f32_e32 v11, v114, v114
	v_fmac_f32_e32 v11, v115, v115
	v_fmac_f32_e32 v11, v116, v116
	v_fmac_f32_e32 v11, v117, v117
	v_fmac_f32_e32 v11, v118, v118
	v_fmac_f32_e32 v11, v119, v119
	v_fmac_f32_e32 v11, v120, v120
	v_fmac_f32_e32 v11, v121, v121
	v_fmac_f32_e32 v11, v122, v122
	v_fmac_f32_e32 v11, v123, v123
	v_fmac_f32_e32 v11, v124, v124
	v_fmac_f32_e32 v11, v125, v125
	v_fmac_f32_e32 v11, v126, v126
	v_fmac_f32_e32 v11, v127, v127
	ds_bpermute_b32 v12, v4, v10
	ds_bpermute_b32 v13, v4, v11
	s_waitcnt lgkmcnt(0)
	v_add_f32_e32 v10, v10, v12
	v_add_f32_e32 v11, v11, v13
	ds_bpermute_b32 v12, v5, v10
	ds_bpermute_b32 v13, v5, v11
	s_waitcnt lgkmcnt(0)
	v_add_f32_e32 v10, v10, v12
	v_add_f32_e32 v11, v11, v13
	ds_bpermute_b32 v12, v6, v10
	ds_bpermute_b32 v13, v6, v11
	s_waitcnt lgkmcnt(0)
	v_add_f32_e32 v10, v10, v12
	v_add_f32_e32 v11, v11, v13
	ds_bpermute_b32 v12, v7, v10
	ds_bpermute_b32 v13, v7, v11
	s_waitcnt lgkmcnt(0)
	v_add_f32_e32 v10, v10, v12
	v_add_f32_e32 v11, v11, v13
	ds_bpermute_b32 v12, v8, v10
	ds_bpermute_b32 v13, v8, v11
	s_waitcnt lgkmcnt(0)
	v_add_f32_e32 v10, v10, v12
	v_add_f32_e32 v11, v11, v13
	ds_bpermute_b32 v12, v9, v10
	ds_bpermute_b32 v13, v9, v11
	s_waitcnt lgkmcnt(0)
	v_add_f32_e32 v10, v10, v12
	v_add_f32_e32 v11, v11, v13
	v_fma_f32 v14, v10, s17, v3
	v_fma_f32 v15, v11, s17, v3
	v_rsq_f32_e32 v14, v14
	v_rsq_f32_e32 v15, v15
	s_nop 0
	v_mul_f32_e32 v64, v80, v14
	v_mul_f32_e32 v65, v81, v14
	v_mul_f32_e32 v66, v82, v14
	v_mul_f32_e32 v67, v83, v14
	v_mul_f32_e32 v68, v84, v14
	v_mul_f32_e32 v69, v85, v14
	v_mul_f32_e32 v70, v86, v14
	v_mul_f32_e32 v71, v87, v14
	v_mul_f32_e32 v72, v88, v14
	v_mul_f32_e32 v73, v89, v14
	v_mul_f32_e32 v74, v90, v14
	v_mul_f32_e32 v75, v91, v14
	v_mul_f32_e32 v76, v92, v14
	v_mul_f32_e32 v77, v93, v14
	v_mul_f32_e32 v78, v94, v14
	v_mul_f32_e32 v79, v95, v14
	v_mul_f32_e32 v64, v64, v36
	v_mul_f32_e32 v65, v65, v37
	v_mul_f32_e32 v66, v66, v38
	v_mul_f32_e32 v67, v67, v39
	v_mul_f32_e32 v68, v68, v40
	v_mul_f32_e32 v69, v69, v41
	v_mul_f32_e32 v70, v70, v42
	v_mul_f32_e32 v71, v71, v43
	v_mul_f32_e32 v72, v72, v44
	v_mul_f32_e32 v73, v73, v45
	v_mul_f32_e32 v74, v74, v46
	v_mul_f32_e32 v75, v75, v47
	v_mul_f32_e32 v76, v76, v48
	v_mul_f32_e32 v77, v77, v49
	v_mul_f32_e32 v78, v78, v50
	v_mul_f32_e32 v79, v79, v51
	v_cvt_pk_bf16_f32 v64, v64, v65
	v_cvt_pk_bf16_f32 v65, v66, v67
	v_cvt_pk_bf16_f32 v68, v68, v69
	v_cvt_pk_bf16_f32 v69, v70, v71
	v_cvt_pk_bf16_f32 v72, v72, v73
	v_cvt_pk_bf16_f32 v73, v74, v75
	v_cvt_pk_bf16_f32 v76, v76, v77
	v_cvt_pk_bf16_f32 v77, v78, v79
	global_store_dwordx2 v2, v[64:65], s[26:27] offset:0
	global_store_dwordx2 v2, v[68:69], s[26:27] offset:512
	global_store_dwordx2 v2, v[72:73], s[26:27] offset:1024
	global_store_dwordx2 v2, v[76:77], s[26:27] offset:1536
	v_mul_f32_e32 v96, v112, v15
	v_mul_f32_e32 v97, v113, v15
	v_mul_f32_e32 v98, v114, v15
	v_mul_f32_e32 v99, v115, v15
	v_mul_f32_e32 v100, v116, v15
	v_mul_f32_e32 v101, v117, v15
	v_mul_f32_e32 v102, v118, v15
	v_mul_f32_e32 v103, v119, v15
	v_mul_f32_e32 v104, v120, v15
	v_mul_f32_e32 v105, v121, v15
	v_mul_f32_e32 v106, v122, v15
	v_mul_f32_e32 v107, v123, v15
	v_mul_f32_e32 v108, v124, v15
	v_mul_f32_e32 v109, v125, v15
	v_mul_f32_e32 v110, v126, v15
	v_mul_f32_e32 v111, v127, v15
	v_mul_f32_e32 v96, v96, v36
	v_mul_f32_e32 v97, v97, v37
	v_mul_f32_e32 v98, v98, v38
	v_mul_f32_e32 v99, v99, v39
	v_mul_f32_e32 v100, v100, v40
	v_mul_f32_e32 v101, v101, v41
	v_mul_f32_e32 v102, v102, v42
	v_mul_f32_e32 v103, v103, v43
	v_mul_f32_e32 v104, v104, v44
	v_mul_f32_e32 v105, v105, v45
	v_mul_f32_e32 v106, v106, v46
	v_mul_f32_e32 v107, v107, v47
	v_mul_f32_e32 v108, v108, v48
	v_mul_f32_e32 v109, v109, v49
	v_mul_f32_e32 v110, v110, v50
	v_mul_f32_e32 v111, v111, v51
	v_cvt_pk_bf16_f32 v96, v96, v97
	v_cvt_pk_bf16_f32 v97, v98, v99
	v_cvt_pk_bf16_f32 v100, v100, v101
	v_cvt_pk_bf16_f32 v101, v102, v103
	v_cvt_pk_bf16_f32 v104, v104, v105
	v_cvt_pk_bf16_f32 v105, v106, v107
	v_cvt_pk_bf16_f32 v108, v108, v109
	v_cvt_pk_bf16_f32 v109, v110, v111
	global_store_dwordx2 v2, v[96:97], s[34:35] offset:0
	global_store_dwordx2 v2, v[100:101], s[34:35] offset:512
	global_store_dwordx2 v2, v[104:105], s[34:35] offset:1024
	global_store_dwordx2 v2, v[108:109], s[34:35] offset:1536
	s_add_u32 s53, s16, 0x2000
	s_lshl_b32 s18, s53, 12
	s_lshl_b32 s19, s53, 11
	s_add_u32 s20, s4, s18
	s_addc_u32 s21, s5, 0
	s_add_u32 s22, s6, s19
	s_addc_u32 s23, s7, 0
	s_add_u32 s22, s22, 0x5200000
	s_addc_u32 s23, s23, 0
	s_add_u32 s24, s4, s18
	s_addc_u32 s25, s5, 0
	s_add_u32 s26, s6, s19
	s_addc_u32 s27, s7, 0
	s_add_u32 s26, s26, 0x3100000
	s_addc_u32 s27, s27, 0
	global_load_dwordx2 v[66:67], v2, s[22:23] offset:0 nt
	global_load_dwordx2 v[70:71], v2, s[22:23] offset:512 nt
	global_load_dwordx2 v[74:75], v2, s[22:23] offset:1024 nt
	global_load_dwordx2 v[78:79], v2, s[22:23] offset:1536 nt
	global_load_dwordx4 v[80:83], v1, s[20:21] offset:0 nt
	global_load_dwordx4 v[84:87], v1, s[20:21] offset:1024 nt
	global_load_dwordx4 v[88:91], v1, s[20:21] offset:2048 nt
	global_load_dwordx4 v[92:95], v1, s[20:21] offset:3072 nt
	s_add_u32 s53, s16, 0x2800
	s_lshl_b32 s18, s53, 12
	s_lshl_b32 s19, s53, 11
	s_add_u32 s28, s4, s18
	s_addc_u32 s29, s5, 0
	s_add_u32 s30, s6, s19
	s_addc_u32 s31, s7, 0
	s_add_u32 s30, s30, 0x5200000
	s_addc_u32 s31, s31, 0
	s_add_u32 s32, s4, s18
	s_addc_u32 s33, s5, 0
	s_add_u32 s34, s6, s19
	s_addc_u32 s35, s7, 0
	s_add_u32 s34, s34, 0x3100000
	s_addc_u32 s35, s35, 0
	global_load_dwordx2 v[98:99], v2, s[30:31] offset:0 nt
	global_load_dwordx2 v[102:103], v2, s[30:31] offset:512 nt
	global_load_dwordx2 v[106:107], v2, s[30:31] offset:1024 nt
	global_load_dwordx2 v[110:111], v2, s[30:31] offset:1536 nt
	global_load_dwordx4 v[112:115], v1, s[28:29] offset:0 nt
	global_load_dwordx4 v[116:119], v1, s[28:29] offset:1024 nt
	global_load_dwordx4 v[120:123], v1, s[28:29] offset:2048 nt
	global_load_dwordx4 v[124:127], v1, s[28:29] offset:3072 nt
	s_waitcnt vmcnt(32)
	v_lshlrev_b32_e32 v128, 16, v130
	v_and_b32_e32 v129, 0xffff0000, v130
	v_lshlrev_b32_e32 v130, 16, v131
	v_and_b32_e32 v131, 0xffff0000, v131
	v_lshlrev_b32_e32 v132, 16, v134
	v_and_b32_e32 v133, 0xffff0000, v134
	v_lshlrev_b32_e32 v134, 16, v135
	v_and_b32_e32 v135, 0xffff0000, v135
	v_lshlrev_b32_e32 v136, 16, v138
	v_and_b32_e32 v137, 0xffff0000, v138
	v_lshlrev_b32_e32 v138, 16, v139
	v_and_b32_e32 v139, 0xffff0000, v139
	v_lshlrev_b32_e32 v140, 16, v142
	v_and_b32_e32 v141, 0xffff0000, v142
	v_lshlrev_b32_e32 v142, 16, v143
	v_and_b32_e32 v143, 0xffff0000, v143
	v_lshlrev_b32_e32 v160, 16, v162
	v_and_b32_e32 v161, 0xffff0000, v162
	v_lshlrev_b32_e32 v162, 16, v163
	v_and_b32_e32 v163, 0xffff0000, v163
	v_lshlrev_b32_e32 v164, 16, v166
	v_and_b32_e32 v165, 0xffff0000, v166
	v_lshlrev_b32_e32 v166, 16, v167
	v_and_b32_e32 v167, 0xffff0000, v167
	v_lshlrev_b32_e32 v168, 16, v170
	v_and_b32_e32 v169, 0xffff0000, v170
	v_lshlrev_b32_e32 v170, 16, v171
	v_and_b32_e32 v171, 0xffff0000, v171
	v_lshlrev_b32_e32 v172, 16, v174
	v_and_b32_e32 v173, 0xffff0000, v174
	v_lshlrev_b32_e32 v174, 16, v175
	v_and_b32_e32 v175, 0xffff0000, v175
	v_mul_f32_e32 v10, v128, v128
	v_fmac_f32_e32 v10, v129, v129
	v_fmac_f32_e32 v10, v130, v130
	v_fmac_f32_e32 v10, v131, v131
	v_fmac_f32_e32 v10, v132, v132
	v_fmac_f32_e32 v10, v133, v133
	v_fmac_f32_e32 v10, v134, v134
	v_fmac_f32_e32 v10, v135, v135
	v_fmac_f32_e32 v10, v136, v136
	v_fmac_f32_e32 v10, v137, v137
	v_fmac_f32_e32 v10, v138, v138
	v_fmac_f32_e32 v10, v139, v139
	v_fmac_f32_e32 v10, v140, v140
	v_fmac_f32_e32 v10, v141, v141
	v_fmac_f32_e32 v10, v142, v142
	v_fmac_f32_e32 v10, v143, v143
	v_mul_f32_e32 v11, v160, v160
	v_fmac_f32_e32 v11, v161, v161
	v_fmac_f32_e32 v11, v162, v162
	v_fmac_f32_e32 v11, v163, v163
	v_fmac_f32_e32 v11, v164, v164
	v_fmac_f32_e32 v11, v165, v165
	v_fmac_f32_e32 v11, v166, v166
	v_fmac_f32_e32 v11, v167, v167
	v_fmac_f32_e32 v11, v168, v168
	v_fmac_f32_e32 v11, v169, v169
	v_fmac_f32_e32 v11, v170, v170
	v_fmac_f32_e32 v11, v171, v171
	v_fmac_f32_e32 v11, v172, v172
	v_fmac_f32_e32 v11, v173, v173
	v_fmac_f32_e32 v11, v174, v174
	v_fmac_f32_e32 v11, v175, v175
	ds_bpermute_b32 v12, v4, v10
	ds_bpermute_b32 v13, v4, v11
	s_waitcnt lgkmcnt(0)
	v_add_f32_e32 v10, v10, v12
	v_add_f32_e32 v11, v11, v13
	ds_bpermute_b32 v12, v5, v10
	ds_bpermute_b32 v13, v5, v11
	s_waitcnt lgkmcnt(0)
	v_add_f32_e32 v10, v10, v12
	v_add_f32_e32 v11, v11, v13
	ds_bpermute_b32 v12, v6, v10
	ds_bpermute_b32 v13, v6, v11
	s_waitcnt lgkmcnt(0)
	v_add_f32_e32 v10, v10, v12
	v_add_f32_e32 v11, v11, v13
	ds_bpermute_b32 v12, v7, v10
	ds_bpermute_b32 v13, v7, v11
	s_waitcnt lgkmcnt(0)
	v_add_f32_e32 v10, v10, v12
	v_add_f32_e32 v11, v11, v13
	ds_bpermute_b32 v12, v8, v10
	ds_bpermute_b32 v13, v8, v11
	s_waitcnt lgkmcnt(0)
	v_add_f32_e32 v10, v10, v12
	v_add_f32_e32 v11, v11, v13
	ds_bpermute_b32 v12, v9, v10
	ds_bpermute_b32 v13, v9, v11
	s_waitcnt lgkmcnt(0)
	v_add_f32_e32 v10, v10, v12
	v_add_f32_e32 v11, v11, v13
	v_fma_f32 v14, v10, s17, v3
	v_fma_f32 v15, v11, s17, v3
	v_rsq_f32_e32 v14, v14
	v_rsq_f32_e32 v15, v15
	s_nop 0
	v_mul_f32_e32 v128, v128, v14
	v_mul_f32_e32 v129, v129, v14
	v_mul_f32_e32 v130, v130, v14
	v_mul_f32_e32 v131, v131, v14
	v_mul_f32_e32 v132, v132, v14
	v_mul_f32_e32 v133, v133, v14
	v_mul_f32_e32 v134, v134, v14
	v_mul_f32_e32 v135, v135, v14
	v_mul_f32_e32 v136, v136, v14
	v_mul_f32_e32 v137, v137, v14
	v_mul_f32_e32 v138, v138, v14
	v_mul_f32_e32 v139, v139, v14
	v_mul_f32_e32 v140, v140, v14
	v_mul_f32_e32 v141, v141, v14
	v_mul_f32_e32 v142, v142, v14
	v_mul_f32_e32 v143, v143, v14
	v_fmac_f32_e32 v144, v128, v20
	v_fmac_f32_e32 v145, v129, v21
	v_fmac_f32_e32 v146, v130, v22
	v_fmac_f32_e32 v147, v131, v23
	v_fmac_f32_e32 v148, v132, v24
	v_fmac_f32_e32 v149, v133, v25
	v_fmac_f32_e32 v150, v134, v26
	v_fmac_f32_e32 v151, v135, v27
	v_fmac_f32_e32 v152, v136, v28
	v_fmac_f32_e32 v153, v137, v29
	v_fmac_f32_e32 v154, v138, v30
	v_fmac_f32_e32 v155, v139, v31
	v_fmac_f32_e32 v156, v140, v32
	v_fmac_f32_e32 v157, v141, v33
	v_fmac_f32_e32 v158, v142, v34
	v_fmac_f32_e32 v159, v143, v35
	global_store_dwordx4 v1, v[144:147], s[40:41] offset:0 nt
	global_store_dwordx4 v1, v[148:151], s[40:41] offset:1024 nt
	global_store_dwordx4 v1, v[152:155], s[40:41] offset:2048 nt
	global_store_dwordx4 v1, v[156:159], s[40:41] offset:3072 nt
	v_mul_f32_e32 v160, v160, v15
	v_mul_f32_e32 v161, v161, v15
	v_mul_f32_e32 v162, v162, v15
	v_mul_f32_e32 v163, v163, v15
	v_mul_f32_e32 v164, v164, v15
	v_mul_f32_e32 v165, v165, v15
	v_mul_f32_e32 v166, v166, v15
	v_mul_f32_e32 v167, v167, v15
	v_mul_f32_e32 v168, v168, v15
	v_mul_f32_e32 v169, v169, v15
	v_mul_f32_e32 v170, v170, v15
	v_mul_f32_e32 v171, v171, v15
	v_mul_f32_e32 v172, v172, v15
	v_mul_f32_e32 v173, v173, v15
	v_mul_f32_e32 v174, v174, v15
	v_mul_f32_e32 v175, v175, v15
	v_fmac_f32_e32 v176, v160, v20
	v_fmac_f32_e32 v177, v161, v21
	v_fmac_f32_e32 v178, v162, v22
	v_fmac_f32_e32 v179, v163, v23
	v_fmac_f32_e32 v180, v164, v24
	v_fmac_f32_e32 v181, v165, v25
	v_fmac_f32_e32 v182, v166, v26
	v_fmac_f32_e32 v183, v167, v27
	v_fmac_f32_e32 v184, v168, v28
	v_fmac_f32_e32 v185, v169, v29
	v_fmac_f32_e32 v186, v170, v30
	v_fmac_f32_e32 v187, v171, v31
	v_fmac_f32_e32 v188, v172, v32
	v_fmac_f32_e32 v189, v173, v33
	v_fmac_f32_e32 v190, v174, v34
	v_fmac_f32_e32 v191, v175, v35
	global_store_dwordx4 v1, v[176:179], s[48:49] offset:0 nt
	global_store_dwordx4 v1, v[180:183], s[48:49] offset:1024 nt
	global_store_dwordx4 v1, v[184:187], s[48:49] offset:2048 nt
	global_store_dwordx4 v1, v[188:191], s[48:49] offset:3072 nt
	v_mul_f32_e32 v10, v144, v144
	v_fmac_f32_e32 v10, v145, v145
	v_fmac_f32_e32 v10, v146, v146
	v_fmac_f32_e32 v10, v147, v147
	v_fmac_f32_e32 v10, v148, v148
	v_fmac_f32_e32 v10, v149, v149
	v_fmac_f32_e32 v10, v150, v150
	v_fmac_f32_e32 v10, v151, v151
	v_fmac_f32_e32 v10, v152, v152
	v_fmac_f32_e32 v10, v153, v153
	v_fmac_f32_e32 v10, v154, v154
	v_fmac_f32_e32 v10, v155, v155
	v_fmac_f32_e32 v10, v156, v156
	v_fmac_f32_e32 v10, v157, v157
	v_fmac_f32_e32 v10, v158, v158
	v_fmac_f32_e32 v10, v159, v159
	v_mul_f32_e32 v11, v176, v176
	v_fmac_f32_e32 v11, v177, v177
	v_fmac_f32_e32 v11, v178, v178
	v_fmac_f32_e32 v11, v179, v179
	v_fmac_f32_e32 v11, v180, v180
	v_fmac_f32_e32 v11, v181, v181
	v_fmac_f32_e32 v11, v182, v182
	v_fmac_f32_e32 v11, v183, v183
	v_fmac_f32_e32 v11, v184, v184
	v_fmac_f32_e32 v11, v185, v185
	v_fmac_f32_e32 v11, v186, v186
	v_fmac_f32_e32 v11, v187, v187
	v_fmac_f32_e32 v11, v188, v188
	v_fmac_f32_e32 v11, v189, v189
	v_fmac_f32_e32 v11, v190, v190
	v_fmac_f32_e32 v11, v191, v191
	ds_bpermute_b32 v12, v4, v10
	ds_bpermute_b32 v13, v4, v11
	s_waitcnt lgkmcnt(0)
	v_add_f32_e32 v10, v10, v12
	v_add_f32_e32 v11, v11, v13
	ds_bpermute_b32 v12, v5, v10
	ds_bpermute_b32 v13, v5, v11
	s_waitcnt lgkmcnt(0)
	v_add_f32_e32 v10, v10, v12
	v_add_f32_e32 v11, v11, v13
	ds_bpermute_b32 v12, v6, v10
	ds_bpermute_b32 v13, v6, v11
	s_waitcnt lgkmcnt(0)
	v_add_f32_e32 v10, v10, v12
	v_add_f32_e32 v11, v11, v13
	ds_bpermute_b32 v12, v7, v10
	ds_bpermute_b32 v13, v7, v11
	s_waitcnt lgkmcnt(0)
	v_add_f32_e32 v10, v10, v12
	v_add_f32_e32 v11, v11, v13
	ds_bpermute_b32 v12, v8, v10
	ds_bpermute_b32 v13, v8, v11
	s_waitcnt lgkmcnt(0)
	v_add_f32_e32 v10, v10, v12
	v_add_f32_e32 v11, v11, v13
	ds_bpermute_b32 v12, v9, v10
	ds_bpermute_b32 v13, v9, v11
	s_waitcnt lgkmcnt(0)
	v_add_f32_e32 v10, v10, v12
	v_add_f32_e32 v11, v11, v13
	v_fma_f32 v14, v10, s17, v3
	v_fma_f32 v15, v11, s17, v3
	v_rsq_f32_e32 v14, v14
	v_rsq_f32_e32 v15, v15
	s_nop 0
	v_mul_f32_e32 v128, v144, v14
	v_mul_f32_e32 v129, v145, v14
	v_mul_f32_e32 v130, v146, v14
	v_mul_f32_e32 v131, v147, v14
	v_mul_f32_e32 v132, v148, v14
	v_mul_f32_e32 v133, v149, v14
	v_mul_f32_e32 v134, v150, v14
	v_mul_f32_e32 v135, v151, v14
	v_mul_f32_e32 v136, v152, v14
	v_mul_f32_e32 v137, v153, v14
	v_mul_f32_e32 v138, v154, v14
	v_mul_f32_e32 v139, v155, v14
	v_mul_f32_e32 v140, v156, v14
	v_mul_f32_e32 v141, v157, v14
	v_mul_f32_e32 v142, v158, v14
	v_mul_f32_e32 v143, v159, v14
	v_mul_f32_e32 v128, v128, v36
	v_mul_f32_e32 v129, v129, v37
	v_mul_f32_e32 v130, v130, v38
	v_mul_f32_e32 v131, v131, v39
	v_mul_f32_e32 v132, v132, v40
	v_mul_f32_e32 v133, v133, v41
	v_mul_f32_e32 v134, v134, v42
	v_mul_f32_e32 v135, v135, v43
	v_mul_f32_e32 v136, v136, v44
	v_mul_f32_e32 v137, v137, v45
	v_mul_f32_e32 v138, v138, v46
	v_mul_f32_e32 v139, v139, v47
	v_mul_f32_e32 v140, v140, v48
	v_mul_f32_e32 v141, v141, v49
	v_mul_f32_e32 v142, v142, v50
	v_mul_f32_e32 v143, v143, v51
	v_cvt_pk_bf16_f32 v128, v128, v129
	v_cvt_pk_bf16_f32 v129, v130, v131
	v_cvt_pk_bf16_f32 v132, v132, v133
	v_cvt_pk_bf16_f32 v133, v134, v135
	v_cvt_pk_bf16_f32 v136, v136, v137
	v_cvt_pk_bf16_f32 v137, v138, v139
	v_cvt_pk_bf16_f32 v140, v140, v141
	v_cvt_pk_bf16_f32 v141, v142, v143
	global_store_dwordx2 v2, v[128:129], s[42:43] offset:0
	global_store_dwordx2 v2, v[132:133], s[42:43] offset:512
	global_store_dwordx2 v2, v[136:137], s[42:43] offset:1024
	global_store_dwordx2 v2, v[140:141], s[42:43] offset:1536
	v_mul_f32_e32 v160, v176, v15
	v_mul_f32_e32 v161, v177, v15
	v_mul_f32_e32 v162, v178, v15
	v_mul_f32_e32 v163, v179, v15
	v_mul_f32_e32 v164, v180, v15
	v_mul_f32_e32 v165, v181, v15
	v_mul_f32_e32 v166, v182, v15
	v_mul_f32_e32 v167, v183, v15
	v_mul_f32_e32 v168, v184, v15
	v_mul_f32_e32 v169, v185, v15
	v_mul_f32_e32 v170, v186, v15
	v_mul_f32_e32 v171, v187, v15
	v_mul_f32_e32 v172, v188, v15
	v_mul_f32_e32 v173, v189, v15
	v_mul_f32_e32 v174, v190, v15
	v_mul_f32_e32 v175, v191, v15
	v_mul_f32_e32 v160, v160, v36
	v_mul_f32_e32 v161, v161, v37
	v_mul_f32_e32 v162, v162, v38
	v_mul_f32_e32 v163, v163, v39
	v_mul_f32_e32 v164, v164, v40
	v_mul_f32_e32 v165, v165, v41
	v_mul_f32_e32 v166, v166, v42
	v_mul_f32_e32 v167, v167, v43
	v_mul_f32_e32 v168, v168, v44
	v_mul_f32_e32 v169, v169, v45
	v_mul_f32_e32 v170, v170, v46
	v_mul_f32_e32 v171, v171, v47
	v_mul_f32_e32 v172, v172, v48
	v_mul_f32_e32 v173, v173, v49
	v_mul_f32_e32 v174, v174, v50
	v_mul_f32_e32 v175, v175, v51
	v_cvt_pk_bf16_f32 v160, v160, v161
	v_cvt_pk_bf16_f32 v161, v162, v163
	v_cvt_pk_bf16_f32 v164, v164, v165
	v_cvt_pk_bf16_f32 v165, v166, v167
	v_cvt_pk_bf16_f32 v168, v168, v169
	v_cvt_pk_bf16_f32 v169, v170, v171
	v_cvt_pk_bf16_f32 v172, v172, v173
	v_cvt_pk_bf16_f32 v173, v174, v175
	global_store_dwordx2 v2, v[160:161], s[50:51] offset:0
	global_store_dwordx2 v2, v[164:165], s[50:51] offset:512
	global_store_dwordx2 v2, v[168:169], s[50:51] offset:1024
	global_store_dwordx2 v2, v[172:173], s[50:51] offset:1536
	s_add_u32 s53, s16, 0x3000
	s_lshl_b32 s18, s53, 12
	s_lshl_b32 s19, s53, 11
	s_add_u32 s36, s4, s18
	s_addc_u32 s37, s5, 0
	s_add_u32 s38, s6, s19
	s_addc_u32 s39, s7, 0
	s_add_u32 s38, s38, 0x5200000
	s_addc_u32 s39, s39, 0
	s_add_u32 s40, s4, s18
	s_addc_u32 s41, s5, 0
	s_add_u32 s42, s6, s19
	s_addc_u32 s43, s7, 0
	s_add_u32 s42, s42, 0x3100000
	s_addc_u32 s43, s43, 0
	global_load_dwordx2 v[130:131], v2, s[38:39] offset:0 nt
	global_load_dwordx2 v[134:135], v2, s[38:39] offset:512 nt
	global_load_dwordx2 v[138:139], v2, s[38:39] offset:1024 nt
	global_load_dwordx2 v[142:143], v2, s[38:39] offset:1536 nt
	global_load_dwordx4 v[144:147], v1, s[36:37] offset:0 nt
	global_load_dwordx4 v[148:151], v1, s[36:37] offset:1024 nt
	global_load_dwordx4 v[152:155], v1, s[36:37] offset:2048 nt
	global_load_dwordx4 v[156:159], v1, s[36:37] offset:3072 nt
	s_add_u32 s53, s16, 0x3800
	s_lshl_b32 s18, s53, 12
	s_lshl_b32 s19, s53, 11
	s_add_u32 s44, s4, s18
	s_addc_u32 s45, s5, 0
	s_add_u32 s46, s6, s19
	s_addc_u32 s47, s7, 0
	s_add_u32 s46, s46, 0x5200000
	s_addc_u32 s47, s47, 0
	s_add_u32 s48, s4, s18
	s_addc_u32 s49, s5, 0
	s_add_u32 s50, s6, s19
	s_addc_u32 s51, s7, 0
	s_add_u32 s50, s50, 0x3100000
	s_addc_u32 s51, s51, 0
	global_load_dwordx2 v[162:163], v2, s[46:47] offset:0 nt
	global_load_dwordx2 v[166:167], v2, s[46:47] offset:512 nt
	global_load_dwordx2 v[170:171], v2, s[46:47] offset:1024 nt
	global_load_dwordx2 v[174:175], v2, s[46:47] offset:1536 nt
	global_load_dwordx4 v[176:179], v1, s[44:45] offset:0 nt
	global_load_dwordx4 v[180:183], v1, s[44:45] offset:1024 nt
	global_load_dwordx4 v[184:187], v1, s[44:45] offset:2048 nt
	global_load_dwordx4 v[188:191], v1, s[44:45] offset:3072 nt
	s_waitcnt vmcnt(32)
	v_lshlrev_b32_e32 v64, 16, v66
	v_and_b32_e32 v65, 0xffff0000, v66
	v_lshlrev_b32_e32 v66, 16, v67
	v_and_b32_e32 v67, 0xffff0000, v67
	v_lshlrev_b32_e32 v68, 16, v70
	v_and_b32_e32 v69, 0xffff0000, v70
	v_lshlrev_b32_e32 v70, 16, v71
	v_and_b32_e32 v71, 0xffff0000, v71
	v_lshlrev_b32_e32 v72, 16, v74
	v_and_b32_e32 v73, 0xffff0000, v74
	v_lshlrev_b32_e32 v74, 16, v75
	v_and_b32_e32 v75, 0xffff0000, v75
	v_lshlrev_b32_e32 v76, 16, v78
	v_and_b32_e32 v77, 0xffff0000, v78
	v_lshlrev_b32_e32 v78, 16, v79
	v_and_b32_e32 v79, 0xffff0000, v79
	v_lshlrev_b32_e32 v96, 16, v98
	v_and_b32_e32 v97, 0xffff0000, v98
	v_lshlrev_b32_e32 v98, 16, v99
	v_and_b32_e32 v99, 0xffff0000, v99
	v_lshlrev_b32_e32 v100, 16, v102
	v_and_b32_e32 v101, 0xffff0000, v102
	v_lshlrev_b32_e32 v102, 16, v103
	v_and_b32_e32 v103, 0xffff0000, v103
	v_lshlrev_b32_e32 v104, 16, v106
	v_and_b32_e32 v105, 0xffff0000, v106
	v_lshlrev_b32_e32 v106, 16, v107
	v_and_b32_e32 v107, 0xffff0000, v107
	v_lshlrev_b32_e32 v108, 16, v110
	v_and_b32_e32 v109, 0xffff0000, v110
	v_lshlrev_b32_e32 v110, 16, v111
	v_and_b32_e32 v111, 0xffff0000, v111
	v_mul_f32_e32 v10, v64, v64
	v_fmac_f32_e32 v10, v65, v65
	v_fmac_f32_e32 v10, v66, v66
	v_fmac_f32_e32 v10, v67, v67
	v_fmac_f32_e32 v10, v68, v68
	v_fmac_f32_e32 v10, v69, v69
	v_fmac_f32_e32 v10, v70, v70
	v_fmac_f32_e32 v10, v71, v71
	v_fmac_f32_e32 v10, v72, v72
	v_fmac_f32_e32 v10, v73, v73
	v_fmac_f32_e32 v10, v74, v74
	v_fmac_f32_e32 v10, v75, v75
	v_fmac_f32_e32 v10, v76, v76
	v_fmac_f32_e32 v10, v77, v77
	v_fmac_f32_e32 v10, v78, v78
	v_fmac_f32_e32 v10, v79, v79
	v_mul_f32_e32 v11, v96, v96
	v_fmac_f32_e32 v11, v97, v97
	v_fmac_f32_e32 v11, v98, v98
	v_fmac_f32_e32 v11, v99, v99
	v_fmac_f32_e32 v11, v100, v100
	v_fmac_f32_e32 v11, v101, v101
	v_fmac_f32_e32 v11, v102, v102
	v_fmac_f32_e32 v11, v103, v103
	v_fmac_f32_e32 v11, v104, v104
	v_fmac_f32_e32 v11, v105, v105
	v_fmac_f32_e32 v11, v106, v106
	v_fmac_f32_e32 v11, v107, v107
	v_fmac_f32_e32 v11, v108, v108
	v_fmac_f32_e32 v11, v109, v109
	v_fmac_f32_e32 v11, v110, v110
	v_fmac_f32_e32 v11, v111, v111
	ds_bpermute_b32 v12, v4, v10
	ds_bpermute_b32 v13, v4, v11
	s_waitcnt lgkmcnt(0)
	v_add_f32_e32 v10, v10, v12
	v_add_f32_e32 v11, v11, v13
	ds_bpermute_b32 v12, v5, v10
	ds_bpermute_b32 v13, v5, v11
	s_waitcnt lgkmcnt(0)
	v_add_f32_e32 v10, v10, v12
	v_add_f32_e32 v11, v11, v13
	ds_bpermute_b32 v12, v6, v10
	ds_bpermute_b32 v13, v6, v11
	s_waitcnt lgkmcnt(0)
	v_add_f32_e32 v10, v10, v12
	v_add_f32_e32 v11, v11, v13
	ds_bpermute_b32 v12, v7, v10
	ds_bpermute_b32 v13, v7, v11
	s_waitcnt lgkmcnt(0)
	v_add_f32_e32 v10, v10, v12
	v_add_f32_e32 v11, v11, v13
	ds_bpermute_b32 v12, v8, v10
	ds_bpermute_b32 v13, v8, v11
	s_waitcnt lgkmcnt(0)
	v_add_f32_e32 v10, v10, v12
	v_add_f32_e32 v11, v11, v13
	ds_bpermute_b32 v12, v9, v10
	ds_bpermute_b32 v13, v9, v11
	s_waitcnt lgkmcnt(0)
	v_add_f32_e32 v10, v10, v12
	v_add_f32_e32 v11, v11, v13
	v_fma_f32 v14, v10, s17, v3
	v_fma_f32 v15, v11, s17, v3
	v_rsq_f32_e32 v14, v14
	v_rsq_f32_e32 v15, v15
	s_nop 0
	v_mul_f32_e32 v64, v64, v14
	v_mul_f32_e32 v65, v65, v14
	v_mul_f32_e32 v66, v66, v14
	v_mul_f32_e32 v67, v67, v14
	v_mul_f32_e32 v68, v68, v14
	v_mul_f32_e32 v69, v69, v14
	v_mul_f32_e32 v70, v70, v14
	v_mul_f32_e32 v71, v71, v14
	v_mul_f32_e32 v72, v72, v14
	v_mul_f32_e32 v73, v73, v14
	v_mul_f32_e32 v74, v74, v14
	v_mul_f32_e32 v75, v75, v14
	v_mul_f32_e32 v76, v76, v14
	v_mul_f32_e32 v77, v77, v14
	v_mul_f32_e32 v78, v78, v14
	v_mul_f32_e32 v79, v79, v14
	v_fmac_f32_e32 v80, v64, v20
	v_fmac_f32_e32 v81, v65, v21
	v_fmac_f32_e32 v82, v66, v22
	v_fmac_f32_e32 v83, v67, v23
	v_fmac_f32_e32 v84, v68, v24
	v_fmac_f32_e32 v85, v69, v25
	v_fmac_f32_e32 v86, v70, v26
	v_fmac_f32_e32 v87, v71, v27
	v_fmac_f32_e32 v88, v72, v28
	v_fmac_f32_e32 v89, v73, v29
	v_fmac_f32_e32 v90, v74, v30
	v_fmac_f32_e32 v91, v75, v31
	v_fmac_f32_e32 v92, v76, v32
	v_fmac_f32_e32 v93, v77, v33
	v_fmac_f32_e32 v94, v78, v34
	v_fmac_f32_e32 v95, v79, v35
	global_store_dwordx4 v1, v[80:83], s[24:25] offset:0 nt
	global_store_dwordx4 v1, v[84:87], s[24:25] offset:1024 nt
	global_store_dwordx4 v1, v[88:91], s[24:25] offset:2048 nt
	global_store_dwordx4 v1, v[92:95], s[24:25] offset:3072 nt
	v_mul_f32_e32 v96, v96, v15
	v_mul_f32_e32 v97, v97, v15
	v_mul_f32_e32 v98, v98, v15
	v_mul_f32_e32 v99, v99, v15
	v_mul_f32_e32 v100, v100, v15
	v_mul_f32_e32 v101, v101, v15
	v_mul_f32_e32 v102, v102, v15
	v_mul_f32_e32 v103, v103, v15
	v_mul_f32_e32 v104, v104, v15
	v_mul_f32_e32 v105, v105, v15
	v_mul_f32_e32 v106, v106, v15
	v_mul_f32_e32 v107, v107, v15
	v_mul_f32_e32 v108, v108, v15
	v_mul_f32_e32 v109, v109, v15
	v_mul_f32_e32 v110, v110, v15
	v_mul_f32_e32 v111, v111, v15
	v_fmac_f32_e32 v112, v96, v20
	v_fmac_f32_e32 v113, v97, v21
	v_fmac_f32_e32 v114, v98, v22
	v_fmac_f32_e32 v115, v99, v23
	v_fmac_f32_e32 v116, v100, v24
	v_fmac_f32_e32 v117, v101, v25
	v_fmac_f32_e32 v118, v102, v26
	v_fmac_f32_e32 v119, v103, v27
	v_fmac_f32_e32 v120, v104, v28
	v_fmac_f32_e32 v121, v105, v29
	v_fmac_f32_e32 v122, v106, v30
	v_fmac_f32_e32 v123, v107, v31
	v_fmac_f32_e32 v124, v108, v32
	v_fmac_f32_e32 v125, v109, v33
	v_fmac_f32_e32 v126, v110, v34
	v_fmac_f32_e32 v127, v111, v35
	global_store_dwordx4 v1, v[112:115], s[32:33] offset:0 nt
	global_store_dwordx4 v1, v[116:119], s[32:33] offset:1024 nt
	global_store_dwordx4 v1, v[120:123], s[32:33] offset:2048 nt
	global_store_dwordx4 v1, v[124:127], s[32:33] offset:3072 nt
	v_mul_f32_e32 v10, v80, v80
	v_fmac_f32_e32 v10, v81, v81
	v_fmac_f32_e32 v10, v82, v82
	v_fmac_f32_e32 v10, v83, v83
	v_fmac_f32_e32 v10, v84, v84
	v_fmac_f32_e32 v10, v85, v85
	v_fmac_f32_e32 v10, v86, v86
	v_fmac_f32_e32 v10, v87, v87
	v_fmac_f32_e32 v10, v88, v88
	v_fmac_f32_e32 v10, v89, v89
	v_fmac_f32_e32 v10, v90, v90
	v_fmac_f32_e32 v10, v91, v91
	v_fmac_f32_e32 v10, v92, v92
	v_fmac_f32_e32 v10, v93, v93
	v_fmac_f32_e32 v10, v94, v94
	v_fmac_f32_e32 v10, v95, v95
	v_mul_f32_e32 v11, v112, v112
	v_fmac_f32_e32 v11, v113, v113
	v_fmac_f32_e32 v11, v114, v114
	v_fmac_f32_e32 v11, v115, v115
	v_fmac_f32_e32 v11, v116, v116
	v_fmac_f32_e32 v11, v117, v117
	v_fmac_f32_e32 v11, v118, v118
	v_fmac_f32_e32 v11, v119, v119
	v_fmac_f32_e32 v11, v120, v120
	v_fmac_f32_e32 v11, v121, v121
	v_fmac_f32_e32 v11, v122, v122
	v_fmac_f32_e32 v11, v123, v123
	v_fmac_f32_e32 v11, v124, v124
	v_fmac_f32_e32 v11, v125, v125
	v_fmac_f32_e32 v11, v126, v126
	v_fmac_f32_e32 v11, v127, v127
	ds_bpermute_b32 v12, v4, v10
	ds_bpermute_b32 v13, v4, v11
	s_waitcnt lgkmcnt(0)
	v_add_f32_e32 v10, v10, v12
	v_add_f32_e32 v11, v11, v13
	ds_bpermute_b32 v12, v5, v10
	ds_bpermute_b32 v13, v5, v11
	s_waitcnt lgkmcnt(0)
	v_add_f32_e32 v10, v10, v12
	v_add_f32_e32 v11, v11, v13
	ds_bpermute_b32 v12, v6, v10
	ds_bpermute_b32 v13, v6, v11
	s_waitcnt lgkmcnt(0)
	v_add_f32_e32 v10, v10, v12
	v_add_f32_e32 v11, v11, v13
	ds_bpermute_b32 v12, v7, v10
	ds_bpermute_b32 v13, v7, v11
	s_waitcnt lgkmcnt(0)
	v_add_f32_e32 v10, v10, v12
	v_add_f32_e32 v11, v11, v13
	ds_bpermute_b32 v12, v8, v10
	ds_bpermute_b32 v13, v8, v11
	s_waitcnt lgkmcnt(0)
	v_add_f32_e32 v10, v10, v12
	v_add_f32_e32 v11, v11, v13
	ds_bpermute_b32 v12, v9, v10
	ds_bpermute_b32 v13, v9, v11
	s_waitcnt lgkmcnt(0)
	v_add_f32_e32 v10, v10, v12
	v_add_f32_e32 v11, v11, v13
	v_fma_f32 v14, v10, s17, v3
	v_fma_f32 v15, v11, s17, v3
	v_rsq_f32_e32 v14, v14
	v_rsq_f32_e32 v15, v15
	s_nop 0
	v_mul_f32_e32 v64, v80, v14
	v_mul_f32_e32 v65, v81, v14
	v_mul_f32_e32 v66, v82, v14
	v_mul_f32_e32 v67, v83, v14
	v_mul_f32_e32 v68, v84, v14
	v_mul_f32_e32 v69, v85, v14
	v_mul_f32_e32 v70, v86, v14
	v_mul_f32_e32 v71, v87, v14
	v_mul_f32_e32 v72, v88, v14
	v_mul_f32_e32 v73, v89, v14
	v_mul_f32_e32 v74, v90, v14
	v_mul_f32_e32 v75, v91, v14
	v_mul_f32_e32 v76, v92, v14
	v_mul_f32_e32 v77, v93, v14
	v_mul_f32_e32 v78, v94, v14
	v_mul_f32_e32 v79, v95, v14
	v_mul_f32_e32 v64, v64, v36
	v_mul_f32_e32 v65, v65, v37
	v_mul_f32_e32 v66, v66, v38
	v_mul_f32_e32 v67, v67, v39
	v_mul_f32_e32 v68, v68, v40
	v_mul_f32_e32 v69, v69, v41
	v_mul_f32_e32 v70, v70, v42
	v_mul_f32_e32 v71, v71, v43
	v_mul_f32_e32 v72, v72, v44
	v_mul_f32_e32 v73, v73, v45
	v_mul_f32_e32 v74, v74, v46
	v_mul_f32_e32 v75, v75, v47
	v_mul_f32_e32 v76, v76, v48
	v_mul_f32_e32 v77, v77, v49
	v_mul_f32_e32 v78, v78, v50
	v_mul_f32_e32 v79, v79, v51
	v_cvt_pk_bf16_f32 v64, v64, v65
	v_cvt_pk_bf16_f32 v65, v66, v67
	v_cvt_pk_bf16_f32 v68, v68, v69
	v_cvt_pk_bf16_f32 v69, v70, v71
	v_cvt_pk_bf16_f32 v72, v72, v73
	v_cvt_pk_bf16_f32 v73, v74, v75
	v_cvt_pk_bf16_f32 v76, v76, v77
	v_cvt_pk_bf16_f32 v77, v78, v79
	global_store_dwordx2 v2, v[64:65], s[26:27] offset:0
	global_store_dwordx2 v2, v[68:69], s[26:27] offset:512
	global_store_dwordx2 v2, v[72:73], s[26:27] offset:1024
	global_store_dwordx2 v2, v[76:77], s[26:27] offset:1536
	v_mul_f32_e32 v96, v112, v15
	v_mul_f32_e32 v97, v113, v15
	v_mul_f32_e32 v98, v114, v15
	v_mul_f32_e32 v99, v115, v15
	v_mul_f32_e32 v100, v116, v15
	v_mul_f32_e32 v101, v117, v15
	v_mul_f32_e32 v102, v118, v15
	v_mul_f32_e32 v103, v119, v15
	v_mul_f32_e32 v104, v120, v15
	v_mul_f32_e32 v105, v121, v15
	v_mul_f32_e32 v106, v122, v15
	v_mul_f32_e32 v107, v123, v15
	v_mul_f32_e32 v108, v124, v15
	v_mul_f32_e32 v109, v125, v15
	v_mul_f32_e32 v110, v126, v15
	v_mul_f32_e32 v111, v127, v15
	v_mul_f32_e32 v96, v96, v36
	v_mul_f32_e32 v97, v97, v37
	v_mul_f32_e32 v98, v98, v38
	v_mul_f32_e32 v99, v99, v39
	v_mul_f32_e32 v100, v100, v40
	v_mul_f32_e32 v101, v101, v41
	v_mul_f32_e32 v102, v102, v42
	v_mul_f32_e32 v103, v103, v43
	v_mul_f32_e32 v104, v104, v44
	v_mul_f32_e32 v105, v105, v45
	v_mul_f32_e32 v106, v106, v46
	v_mul_f32_e32 v107, v107, v47
	v_mul_f32_e32 v108, v108, v48
	v_mul_f32_e32 v109, v109, v49
	v_mul_f32_e32 v110, v110, v50
	v_mul_f32_e32 v111, v111, v51
	v_cvt_pk_bf16_f32 v96, v96, v97
	v_cvt_pk_bf16_f32 v97, v98, v99
	v_cvt_pk_bf16_f32 v100, v100, v101
	v_cvt_pk_bf16_f32 v101, v102, v103
	v_cvt_pk_bf16_f32 v104, v104, v105
	v_cvt_pk_bf16_f32 v105, v106, v107
	v_cvt_pk_bf16_f32 v108, v108, v109
	v_cvt_pk_bf16_f32 v109, v110, v111
	global_store_dwordx2 v2, v[96:97], s[34:35] offset:0
	global_store_dwordx2 v2, v[100:101], s[34:35] offset:512
	global_store_dwordx2 v2, v[104:105], s[34:35] offset:1024
	global_store_dwordx2 v2, v[108:109], s[34:35] offset:1536
	s_waitcnt vmcnt(16)
	v_lshlrev_b32_e32 v128, 16, v130
	v_and_b32_e32 v129, 0xffff0000, v130
	v_lshlrev_b32_e32 v130, 16, v131
	v_and_b32_e32 v131, 0xffff0000, v131
	v_lshlrev_b32_e32 v132, 16, v134
	v_and_b32_e32 v133, 0xffff0000, v134
	v_lshlrev_b32_e32 v134, 16, v135
	v_and_b32_e32 v135, 0xffff0000, v135
	v_lshlrev_b32_e32 v136, 16, v138
	v_and_b32_e32 v137, 0xffff0000, v138
	v_lshlrev_b32_e32 v138, 16, v139
	v_and_b32_e32 v139, 0xffff0000, v139
	v_lshlrev_b32_e32 v140, 16, v142
	v_and_b32_e32 v141, 0xffff0000, v142
	v_lshlrev_b32_e32 v142, 16, v143
	v_and_b32_e32 v143, 0xffff0000, v143
	v_lshlrev_b32_e32 v160, 16, v162
	v_and_b32_e32 v161, 0xffff0000, v162
	v_lshlrev_b32_e32 v162, 16, v163
	v_and_b32_e32 v163, 0xffff0000, v163
	v_lshlrev_b32_e32 v164, 16, v166
	v_and_b32_e32 v165, 0xffff0000, v166
	v_lshlrev_b32_e32 v166, 16, v167
	v_and_b32_e32 v167, 0xffff0000, v167
	v_lshlrev_b32_e32 v168, 16, v170
	v_and_b32_e32 v169, 0xffff0000, v170
	v_lshlrev_b32_e32 v170, 16, v171
	v_and_b32_e32 v171, 0xffff0000, v171
	v_lshlrev_b32_e32 v172, 16, v174
	v_and_b32_e32 v173, 0xffff0000, v174
	v_lshlrev_b32_e32 v174, 16, v175
	v_and_b32_e32 v175, 0xffff0000, v175
	v_mul_f32_e32 v10, v128, v128
	v_fmac_f32_e32 v10, v129, v129
	v_fmac_f32_e32 v10, v130, v130
	v_fmac_f32_e32 v10, v131, v131
	v_fmac_f32_e32 v10, v132, v132
	v_fmac_f32_e32 v10, v133, v133
	v_fmac_f32_e32 v10, v134, v134
	v_fmac_f32_e32 v10, v135, v135
	v_fmac_f32_e32 v10, v136, v136
	v_fmac_f32_e32 v10, v137, v137
	v_fmac_f32_e32 v10, v138, v138
	v_fmac_f32_e32 v10, v139, v139
	v_fmac_f32_e32 v10, v140, v140
	v_fmac_f32_e32 v10, v141, v141
	v_fmac_f32_e32 v10, v142, v142
	v_fmac_f32_e32 v10, v143, v143
	v_mul_f32_e32 v11, v160, v160
	v_fmac_f32_e32 v11, v161, v161
	v_fmac_f32_e32 v11, v162, v162
	v_fmac_f32_e32 v11, v163, v163
	v_fmac_f32_e32 v11, v164, v164
	v_fmac_f32_e32 v11, v165, v165
	v_fmac_f32_e32 v11, v166, v166
	v_fmac_f32_e32 v11, v167, v167
	v_fmac_f32_e32 v11, v168, v168
	v_fmac_f32_e32 v11, v169, v169
	v_fmac_f32_e32 v11, v170, v170
	v_fmac_f32_e32 v11, v171, v171
	v_fmac_f32_e32 v11, v172, v172
	v_fmac_f32_e32 v11, v173, v173
	v_fmac_f32_e32 v11, v174, v174
	v_fmac_f32_e32 v11, v175, v175
	ds_bpermute_b32 v12, v4, v10
	ds_bpermute_b32 v13, v4, v11
	s_waitcnt lgkmcnt(0)
	v_add_f32_e32 v10, v10, v12
	v_add_f32_e32 v11, v11, v13
	ds_bpermute_b32 v12, v5, v10
	ds_bpermute_b32 v13, v5, v11
	s_waitcnt lgkmcnt(0)
	v_add_f32_e32 v10, v10, v12
	v_add_f32_e32 v11, v11, v13
	ds_bpermute_b32 v12, v6, v10
	ds_bpermute_b32 v13, v6, v11
	s_waitcnt lgkmcnt(0)
	v_add_f32_e32 v10, v10, v12
	v_add_f32_e32 v11, v11, v13
	ds_bpermute_b32 v12, v7, v10
	ds_bpermute_b32 v13, v7, v11
	s_waitcnt lgkmcnt(0)
	v_add_f32_e32 v10, v10, v12
	v_add_f32_e32 v11, v11, v13
	ds_bpermute_b32 v12, v8, v10
	ds_bpermute_b32 v13, v8, v11
	s_waitcnt lgkmcnt(0)
	v_add_f32_e32 v10, v10, v12
	v_add_f32_e32 v11, v11, v13
	ds_bpermute_b32 v12, v9, v10
	ds_bpermute_b32 v13, v9, v11
	s_waitcnt lgkmcnt(0)
	v_add_f32_e32 v10, v10, v12
	v_add_f32_e32 v11, v11, v13
	v_fma_f32 v14, v10, s17, v3
	v_fma_f32 v15, v11, s17, v3
	v_rsq_f32_e32 v14, v14
	v_rsq_f32_e32 v15, v15
	s_nop 0
	v_mul_f32_e32 v128, v128, v14
	v_mul_f32_e32 v129, v129, v14
	v_mul_f32_e32 v130, v130, v14
	v_mul_f32_e32 v131, v131, v14
	v_mul_f32_e32 v132, v132, v14
	v_mul_f32_e32 v133, v133, v14
	v_mul_f32_e32 v134, v134, v14
	v_mul_f32_e32 v135, v135, v14
	v_mul_f32_e32 v136, v136, v14
	v_mul_f32_e32 v137, v137, v14
	v_mul_f32_e32 v138, v138, v14
	v_mul_f32_e32 v139, v139, v14
	v_mul_f32_e32 v140, v140, v14
	v_mul_f32_e32 v141, v141, v14
	v_mul_f32_e32 v142, v142, v14
	v_mul_f32_e32 v143, v143, v14
	v_fmac_f32_e32 v144, v128, v20
	v_fmac_f32_e32 v145, v129, v21
	v_fmac_f32_e32 v146, v130, v22
	v_fmac_f32_e32 v147, v131, v23
	v_fmac_f32_e32 v148, v132, v24
	v_fmac_f32_e32 v149, v133, v25
	v_fmac_f32_e32 v150, v134, v26
	v_fmac_f32_e32 v151, v135, v27
	v_fmac_f32_e32 v152, v136, v28
	v_fmac_f32_e32 v153, v137, v29
	v_fmac_f32_e32 v154, v138, v30
	v_fmac_f32_e32 v155, v139, v31
	v_fmac_f32_e32 v156, v140, v32
	v_fmac_f32_e32 v157, v141, v33
	v_fmac_f32_e32 v158, v142, v34
	v_fmac_f32_e32 v159, v143, v35
	global_store_dwordx4 v1, v[144:147], s[40:41] offset:0 nt
	global_store_dwordx4 v1, v[148:151], s[40:41] offset:1024 nt
	global_store_dwordx4 v1, v[152:155], s[40:41] offset:2048 nt
	global_store_dwordx4 v1, v[156:159], s[40:41] offset:3072 nt
	v_mul_f32_e32 v160, v160, v15
	v_mul_f32_e32 v161, v161, v15
	v_mul_f32_e32 v162, v162, v15
	v_mul_f32_e32 v163, v163, v15
	v_mul_f32_e32 v164, v164, v15
	v_mul_f32_e32 v165, v165, v15
	v_mul_f32_e32 v166, v166, v15
	v_mul_f32_e32 v167, v167, v15
	v_mul_f32_e32 v168, v168, v15
	v_mul_f32_e32 v169, v169, v15
	v_mul_f32_e32 v170, v170, v15
	v_mul_f32_e32 v171, v171, v15
	v_mul_f32_e32 v172, v172, v15
	v_mul_f32_e32 v173, v173, v15
	v_mul_f32_e32 v174, v174, v15
	v_mul_f32_e32 v175, v175, v15
	v_fmac_f32_e32 v176, v160, v20
	v_fmac_f32_e32 v177, v161, v21
	v_fmac_f32_e32 v178, v162, v22
	v_fmac_f32_e32 v179, v163, v23
	v_fmac_f32_e32 v180, v164, v24
	v_fmac_f32_e32 v181, v165, v25
	v_fmac_f32_e32 v182, v166, v26
	v_fmac_f32_e32 v183, v167, v27
	v_fmac_f32_e32 v184, v168, v28
	v_fmac_f32_e32 v185, v169, v29
	v_fmac_f32_e32 v186, v170, v30
	v_fmac_f32_e32 v187, v171, v31
	v_fmac_f32_e32 v188, v172, v32
	v_fmac_f32_e32 v189, v173, v33
	v_fmac_f32_e32 v190, v174, v34
	v_fmac_f32_e32 v191, v175, v35
	global_store_dwordx4 v1, v[176:179], s[48:49] offset:0 nt
	global_store_dwordx4 v1, v[180:183], s[48:49] offset:1024 nt
	global_store_dwordx4 v1, v[184:187], s[48:49] offset:2048 nt
	global_store_dwordx4 v1, v[188:191], s[48:49] offset:3072 nt
	v_mul_f32_e32 v10, v144, v144
	v_fmac_f32_e32 v10, v145, v145
	v_fmac_f32_e32 v10, v146, v146
	v_fmac_f32_e32 v10, v147, v147
	v_fmac_f32_e32 v10, v148, v148
	v_fmac_f32_e32 v10, v149, v149
	v_fmac_f32_e32 v10, v150, v150
	v_fmac_f32_e32 v10, v151, v151
	v_fmac_f32_e32 v10, v152, v152
	v_fmac_f32_e32 v10, v153, v153
	v_fmac_f32_e32 v10, v154, v154
	v_fmac_f32_e32 v10, v155, v155
	v_fmac_f32_e32 v10, v156, v156
	v_fmac_f32_e32 v10, v157, v157
	v_fmac_f32_e32 v10, v158, v158
	v_fmac_f32_e32 v10, v159, v159
	v_mul_f32_e32 v11, v176, v176
	v_fmac_f32_e32 v11, v177, v177
	v_fmac_f32_e32 v11, v178, v178
	v_fmac_f32_e32 v11, v179, v179
	v_fmac_f32_e32 v11, v180, v180
	v_fmac_f32_e32 v11, v181, v181
	v_fmac_f32_e32 v11, v182, v182
	v_fmac_f32_e32 v11, v183, v183
	v_fmac_f32_e32 v11, v184, v184
	v_fmac_f32_e32 v11, v185, v185
	v_fmac_f32_e32 v11, v186, v186
	v_fmac_f32_e32 v11, v187, v187
	v_fmac_f32_e32 v11, v188, v188
	v_fmac_f32_e32 v11, v189, v189
	v_fmac_f32_e32 v11, v190, v190
	v_fmac_f32_e32 v11, v191, v191
	ds_bpermute_b32 v12, v4, v10
	ds_bpermute_b32 v13, v4, v11
	s_waitcnt lgkmcnt(0)
	v_add_f32_e32 v10, v10, v12
	v_add_f32_e32 v11, v11, v13
	ds_bpermute_b32 v12, v5, v10
	ds_bpermute_b32 v13, v5, v11
	s_waitcnt lgkmcnt(0)
	v_add_f32_e32 v10, v10, v12
	v_add_f32_e32 v11, v11, v13
	ds_bpermute_b32 v12, v6, v10
	ds_bpermute_b32 v13, v6, v11
	s_waitcnt lgkmcnt(0)
	v_add_f32_e32 v10, v10, v12
	v_add_f32_e32 v11, v11, v13
	ds_bpermute_b32 v12, v7, v10
	ds_bpermute_b32 v13, v7, v11
	s_waitcnt lgkmcnt(0)
	v_add_f32_e32 v10, v10, v12
	v_add_f32_e32 v11, v11, v13
	ds_bpermute_b32 v12, v8, v10
	ds_bpermute_b32 v13, v8, v11
	s_waitcnt lgkmcnt(0)
	v_add_f32_e32 v10, v10, v12
	v_add_f32_e32 v11, v11, v13
	ds_bpermute_b32 v12, v9, v10
	ds_bpermute_b32 v13, v9, v11
	s_waitcnt lgkmcnt(0)
	v_add_f32_e32 v10, v10, v12
	v_add_f32_e32 v11, v11, v13
	v_fma_f32 v14, v10, s17, v3
	v_fma_f32 v15, v11, s17, v3
	v_rsq_f32_e32 v14, v14
	v_rsq_f32_e32 v15, v15
	s_nop 0
	v_mul_f32_e32 v128, v144, v14
	v_mul_f32_e32 v129, v145, v14
	v_mul_f32_e32 v130, v146, v14
	v_mul_f32_e32 v131, v147, v14
	v_mul_f32_e32 v132, v148, v14
	v_mul_f32_e32 v133, v149, v14
	v_mul_f32_e32 v134, v150, v14
	v_mul_f32_e32 v135, v151, v14
	v_mul_f32_e32 v136, v152, v14
	v_mul_f32_e32 v137, v153, v14
	v_mul_f32_e32 v138, v154, v14
	v_mul_f32_e32 v139, v155, v14
	v_mul_f32_e32 v140, v156, v14
	v_mul_f32_e32 v141, v157, v14
	v_mul_f32_e32 v142, v158, v14
	v_mul_f32_e32 v143, v159, v14
	v_mul_f32_e32 v128, v128, v36
	v_mul_f32_e32 v129, v129, v37
	v_mul_f32_e32 v130, v130, v38
	v_mul_f32_e32 v131, v131, v39
	v_mul_f32_e32 v132, v132, v40
	v_mul_f32_e32 v133, v133, v41
	v_mul_f32_e32 v134, v134, v42
	v_mul_f32_e32 v135, v135, v43
	v_mul_f32_e32 v136, v136, v44
	v_mul_f32_e32 v137, v137, v45
	v_mul_f32_e32 v138, v138, v46
	v_mul_f32_e32 v139, v139, v47
	v_mul_f32_e32 v140, v140, v48
	v_mul_f32_e32 v141, v141, v49
	v_mul_f32_e32 v142, v142, v50
	v_mul_f32_e32 v143, v143, v51
	v_cvt_pk_bf16_f32 v128, v128, v129
	v_cvt_pk_bf16_f32 v129, v130, v131
	v_cvt_pk_bf16_f32 v132, v132, v133
	v_cvt_pk_bf16_f32 v133, v134, v135
	v_cvt_pk_bf16_f32 v136, v136, v137
	v_cvt_pk_bf16_f32 v137, v138, v139
	v_cvt_pk_bf16_f32 v140, v140, v141
	v_cvt_pk_bf16_f32 v141, v142, v143
	global_store_dwordx2 v2, v[128:129], s[42:43] offset:0
	global_store_dwordx2 v2, v[132:133], s[42:43] offset:512
	global_store_dwordx2 v2, v[136:137], s[42:43] offset:1024
	global_store_dwordx2 v2, v[140:141], s[42:43] offset:1536
	v_mul_f32_e32 v160, v176, v15
	v_mul_f32_e32 v161, v177, v15
	v_mul_f32_e32 v162, v178, v15
	v_mul_f32_e32 v163, v179, v15
	v_mul_f32_e32 v164, v180, v15
	v_mul_f32_e32 v165, v181, v15
	v_mul_f32_e32 v166, v182, v15
	v_mul_f32_e32 v167, v183, v15
	v_mul_f32_e32 v168, v184, v15
	v_mul_f32_e32 v169, v185, v15
	v_mul_f32_e32 v170, v186, v15
	v_mul_f32_e32 v171, v187, v15
	v_mul_f32_e32 v172, v188, v15
	v_mul_f32_e32 v173, v189, v15
	v_mul_f32_e32 v174, v190, v15
	v_mul_f32_e32 v175, v191, v15
	v_mul_f32_e32 v160, v160, v36
	v_mul_f32_e32 v161, v161, v37
	v_mul_f32_e32 v162, v162, v38
	v_mul_f32_e32 v163, v163, v39
	v_mul_f32_e32 v164, v164, v40
	v_mul_f32_e32 v165, v165, v41
	v_mul_f32_e32 v166, v166, v42
	v_mul_f32_e32 v167, v167, v43
	v_mul_f32_e32 v168, v168, v44
	v_mul_f32_e32 v169, v169, v45
	v_mul_f32_e32 v170, v170, v46
	v_mul_f32_e32 v171, v171, v47
	v_mul_f32_e32 v172, v172, v48
	v_mul_f32_e32 v173, v173, v49
	v_mul_f32_e32 v174, v174, v50
	v_mul_f32_e32 v175, v175, v51
	v_cvt_pk_bf16_f32 v160, v160, v161
	v_cvt_pk_bf16_f32 v161, v162, v163
	v_cvt_pk_bf16_f32 v164, v164, v165
	v_cvt_pk_bf16_f32 v165, v166, v167
	v_cvt_pk_bf16_f32 v168, v168, v169
	v_cvt_pk_bf16_f32 v169, v170, v171
	v_cvt_pk_bf16_f32 v172, v172, v173
	v_cvt_pk_bf16_f32 v173, v174, v175
	global_store_dwordx2 v2, v[160:161], s[50:51] offset:0
	global_store_dwordx2 v2, v[164:165], s[50:51] offset:512
	global_store_dwordx2 v2, v[168:169], s[50:51] offset:1024
	global_store_dwordx2 v2, v[172:173], s[50:51] offset:1536
	v_add_f32_e32 v208, v208, v212
	v_add_f32_e32 v209, v209, v213
	v_add_f32_e32 v210, v210, v214
	v_add_f32_e32 v211, v211, v215
	v_readfirstlane_b32 s18, v0
	s_lshr_b32 s18, s18, 6
	s_lshl_b32 s19, s18, 2
	s_and_b32 s52, s18, 4
	s_lshl_b32 s52, s52, 2
	v_mov_b32_e32 v16, s19
	v_mov_b32_e32 v17, s52
	v_mul_f32_e32 v10, v208, v208
	v_fmac_f32_e32 v10, v209, v209
	v_fmac_f32_e32 v10, v210, v210
	v_fmac_f32_e32 v10, v211, v211
	ds_bpermute_b32 v11, v4, v10
	s_waitcnt lgkmcnt(0)
	v_add_f32_e32 v10, v10, v11
	ds_bpermute_b32 v11, v5, v10
	s_waitcnt lgkmcnt(0)
	v_add_f32_e32 v10, v10, v11
	ds_bpermute_b32 v11, v6, v10
	s_waitcnt lgkmcnt(0)
	v_add_f32_e32 v10, v10, v11
	ds_bpermute_b32 v11, v7, v10
	s_waitcnt lgkmcnt(0)
	v_add_f32_e32 v10, v10, v11
	ds_bpermute_b32 v11, v8, v10
	s_waitcnt lgkmcnt(0)
	v_add_f32_e32 v10, v10, v11
	ds_bpermute_b32 v11, v9, v10
	s_waitcnt lgkmcnt(0)
	v_add_f32_e32 v10, v10, v11
	ds_write_b32 v16, v10 offset:0
	s_waitcnt lgkmcnt(0)
	s_barrier
	ds_read_b128 v[12:15], v17 offset:0
	s_waitcnt lgkmcnt(0)
	v_add_f32_e32 v12, v12, v13
	v_add_f32_e32 v14, v14, v15
	v_add_f32_e32 v10, v12, v14
	v_fma_f32 v11, v10, s17, v3
	v_rsq_f32_e32 v11, v11
	s_nop 0
	v_mul_f32_e32 v208, v208, v11
	v_mul_f32_e32 v209, v209, v11
	v_mul_f32_e32 v210, v210, v11
	v_mul_f32_e32 v211, v211, v11
	v_fmac_f32_e32 v240, v208, v244
	v_fmac_f32_e32 v241, v209, v245
	v_fmac_f32_e32 v242, v210, v246
	v_fmac_f32_e32 v243, v211, v247
	s_lshl_b32 s18, s54, 12
	s_add_u32 s18, s18, s55
	s_add_u32 s56, s4, s18
	s_addc_u32 s57, s5, 0
	s_add_u32 s56, s56, 0x4000000
	s_addc_u32 s57, s57, 0
	global_store_dwordx4 v1, v[240:243], s[56:57]
	v_mul_f32_e32 v10, v240, v240
	v_fmac_f32_e32 v10, v241, v241
	v_fmac_f32_e32 v10, v242, v242
	v_fmac_f32_e32 v10, v243, v243
	ds_bpermute_b32 v11, v4, v10
	s_waitcnt lgkmcnt(0)
	v_add_f32_e32 v10, v10, v11
	ds_bpermute_b32 v11, v5, v10
	s_waitcnt lgkmcnt(0)
	v_add_f32_e32 v10, v10, v11
	ds_bpermute_b32 v11, v6, v10
	s_waitcnt lgkmcnt(0)
	v_add_f32_e32 v10, v10, v11
	ds_bpermute_b32 v11, v7, v10
	s_waitcnt lgkmcnt(0)
	v_add_f32_e32 v10, v10, v11
	ds_bpermute_b32 v11, v8, v10
	s_waitcnt lgkmcnt(0)
	v_add_f32_e32 v10, v10, v11
	ds_bpermute_b32 v11, v9, v10
	s_waitcnt lgkmcnt(0)
	v_add_f32_e32 v10, v10, v11
	ds_write_b32 v16, v10 offset:64
	s_waitcnt lgkmcnt(0)
	s_barrier
	ds_read_b128 v[12:15], v17 offset:64
	s_waitcnt lgkmcnt(0)
	v_add_f32_e32 v12, v12, v13
	v_add_f32_e32 v14, v14, v15
	v_add_f32_e32 v10, v12, v14
	v_fma_f32 v11, v10, s17, v3
	v_rsq_f32_e32 v11, v11
	s_nop 0
	v_mul_f32_e32 v208, v240, v11
	v_mul_f32_e32 v209, v241, v11
	v_mul_f32_e32 v210, v242, v11
	v_mul_f32_e32 v211, v243, v11
	v_mul_f32_e32 v208, v208, v248
	v_mul_f32_e32 v209, v209, v249
	v_mul_f32_e32 v210, v210, v250
	v_mul_f32_e32 v211, v211, v251
	v_cvt_pk_bf16_f32 v208, v208, v209
	v_cvt_pk_bf16_f32 v209, v210, v211
	s_lshl_b32 s18, s54, 11
	s_lshr_b32 s19, s55, 1
	s_add_u32 s18, s18, s19
	s_add_u32 s56, s6, s18
	s_addc_u32 s57, s7, 0
	s_add_u32 s56, s56, 0x5100000
	s_addc_u32 s57, s57, 0
	global_store_dwordx2 v2, v[208:209], s[56:57]

_Z10fwd_kernelILi14ELi15EEv4Args:
	s_load_dword s3, s[0:1], 0xe8
	s_load_dwordx4 s[4:7], s[0:1], 0xd0
	s_load_dwordx2 s[8:9], s[0:1], 0xb8
	s_waitcnt lgkmcnt(0)
	s_cmp_lg_u32 s3, 0x100
	s_cbranch_scc1 .Lrows14_orig
	s_add_u32 s8, s8, 0x1000
	s_addc_u32 s9, s9, 0
	v_readfirstlane_b32 s16, v0
	s_lshr_b32 s16, s16, 6
	s_lshl_b32 s18, s2, 3
	s_add_u32 s16, s16, s18
	s_mov_b32 s17, 0x3a800000
	v_mov_b32_e32 v3, 0x358637bd
	v_and_b32_e32 v10, 63, v0
	v_lshlrev_b32_e32 v1, 4, v10
	v_lshlrev_b32_e32 v2, 3, v10
	v_xor_b32_e32 v4, 1, v10
	v_xor_b32_e32 v5, 2, v10
	v_xor_b32_e32 v6, 4, v10
	v_xor_b32_e32 v7, 8, v10
	v_xor_b32_e32 v8, 16, v10
	v_xor_b32_e32 v9, 32, v10
	v_lshlrev_b32_e32 v4, 2, v4
	v_lshlrev_b32_e32 v5, 2, v5
	v_lshlrev_b32_e32 v6, 2, v6
	v_lshlrev_b32_e32 v7, 2, v7
	v_lshlrev_b32_e32 v8, 2, v8
	v_lshlrev_b32_e32 v9, 2, v9
	global_load_dwordx4 v[20:23], v1, s[8:9] offset:0
	global_load_dwordx4 v[24:27], v1, s[8:9] offset:1024
	global_load_dwordx4 v[28:31], v1, s[8:9] offset:2048
	global_load_dwordx4 v[32:35], v1, s[8:9] offset:3072
	s_lshr_b32 s54, s16, 2
	s_and_b32 s55, s16, 3
	s_lshl_b32 s55, s55, 10
	s_lshl_b32 s18, s54, 12
	s_add_u32 s18, s18, s55
	s_add_u32 s56, s6, s18
	s_addc_u32 s57, s7, 0
	s_add_u32 s56, s56, 0x100000
	s_addc_u32 s57, s57, 0
	global_load_dwordx4 v[208:211], v1, s[56:57]
	s_add_u32 s56, s56, 0x200000
	s_addc_u32 s57, s57, 0
	global_load_dwordx4 v[212:215], v1, s[56:57]
	s_add_u32 s56, s56, 0x200000
	s_addc_u32 s57, s57, 0
	global_load_dwordx4 v[216:219], v1, s[56:57]
	s_add_u32 s56, s56, 0x200000
	s_addc_u32 s57, s57, 0
	global_load_dwordx4 v[220:223], v1, s[56:57]
	s_add_u32 s56, s56, 0x200000
	s_addc_u32 s57, s57, 0
	global_load_dwordx4 v[224:227], v1, s[56:57]
	s_add_u32 s56, s56, 0x200000
	s_addc_u32 s57, s57, 0
	global_load_dwordx4 v[228:231], v1, s[56:57]
	s_add_u32 s56, s56, 0x200000
	s_addc_u32 s57, s57, 0
	global_load_dwordx4 v[232:235], v1, s[56:57]
	s_add_u32 s56, s56, 0x200000
	s_addc_u32 s57, s57, 0
	global_load_dwordx4 v[236:239], v1, s[56:57]
	s_add_u32 s56, s4, s18
	s_addc_u32 s57, s5, 0
	s_add_u32 s56, s56, 0x4000000
	s_addc_u32 s57, s57, 0
	global_load_dwordx4 v[240:243], v1, s[56:57]
	s_add_u32 s56, s8, s55
	s_addc_u32 s57, s9, 0
	global_load_dwordx4 v[244:247], v1, s[56:57]
	s_add_u32 s53, s16, 0x0
	s_lshl_b32 s18, s53, 12
	s_lshl_b32 s19, s53, 11
	s_add_u32 s20, s4, s18
	s_addc_u32 s21, s5, 0
	s_add_u32 s22, s6, s19
	s_addc_u32 s23, s7, 0
	s_add_u32 s22, s22, 0x5200000
	s_addc_u32 s23, s23, 0
	s_add_u32 s24, s4, s18
	s_addc_u32 s25, s5, 0
	global_load_dwordx2 v[66:67], v2, s[22:23] offset:0 nt
	global_load_dwordx2 v[70:71], v2, s[22:23] offset:512 nt
	global_load_dwordx2 v[74:75], v2, s[22:23] offset:1024 nt
	global_load_dwordx2 v[78:79], v2, s[22:23] offset:1536 nt
	global_load_dwordx4 v[80:83], v1, s[20:21] offset:0 nt
	global_load_dwordx4 v[84:87], v1, s[20:21] offset:1024 nt
	global_load_dwordx4 v[88:91], v1, s[20:21] offset:2048 nt
	global_load_dwordx4 v[92:95], v1, s[20:21] offset:3072 nt
	s_add_u32 s53, s16, 0x800
	s_lshl_b32 s18, s53, 12
	s_lshl_b32 s19, s53, 11
	s_add_u32 s28, s4, s18
	s_addc_u32 s29, s5, 0
	s_add_u32 s30, s6, s19
	s_addc_u32 s31, s7, 0
	s_add_u32 s30, s30, 0x5200000
	s_addc_u32 s31, s31, 0
	s_add_u32 s32, s4, s18
	s_addc_u32 s33, s5, 0
	global_load_dwordx2 v[98:99], v2, s[30:31] offset:0 nt
	global_load_dwordx2 v[102:103], v2, s[30:31] offset:512 nt
	global_load_dwordx2 v[106:107], v2, s[30:31] offset:1024 nt
	global_load_dwordx2 v[110:111], v2, s[30:31] offset:1536 nt
	global_load_dwordx4 v[112:115], v1, s[28:29] offset:0 nt
	global_load_dwordx4 v[116:119], v1, s[28:29] offset:1024 nt
	global_load_dwordx4 v[120:123], v1, s[28:29] offset:2048 nt
	global_load_dwordx4 v[124:127], v1, s[28:29] offset:3072 nt
	s_add_u32 s53, s16, 0x1000
	s_lshl_b32 s18, s53, 12
	s_lshl_b32 s19, s53, 11
	s_add_u32 s36, s4, s18
	s_addc_u32 s37, s5, 0
	s_add_u32 s38, s6, s19
	s_addc_u32 s39, s7, 0
	s_add_u32 s38, s38, 0x5200000
	s_addc_u32 s39, s39, 0
	s_add_u32 s40, s4, s18
	s_addc_u32 s41, s5, 0
	global_load_dwordx2 v[130:131], v2, s[38:39] offset:0 nt
	global_load_dwordx2 v[134:135], v2, s[38:39] offset:512 nt
	global_load_dwordx2 v[138:139], v2, s[38:39] offset:1024 nt
	global_load_dwordx2 v[142:143], v2, s[38:39] offset:1536 nt
	global_load_dwordx4 v[144:147], v1, s[36:37] offset:0 nt
	global_load_dwordx4 v[148:151], v1, s[36:37] offset:1024 nt
	global_load_dwordx4 v[152:155], v1, s[36:37] offset:2048 nt
	global_load_dwordx4 v[156:159], v1, s[36:37] offset:3072 nt
	s_add_u32 s53, s16, 0x1800
	s_lshl_b32 s18, s53, 12
	s_lshl_b32 s19, s53, 11
	s_add_u32 s44, s4, s18
	s_addc_u32 s45, s5, 0
	s_add_u32 s46, s6, s19
	s_addc_u32 s47, s7, 0
	s_add_u32 s46, s46, 0x5200000
	s_addc_u32 s47, s47, 0
	s_add_u32 s48, s4, s18
	s_addc_u32 s49, s5, 0
	global_load_dwordx2 v[162:163], v2, s[46:47] offset:0 nt
	global_load_dwordx2 v[166:167], v2, s[46:47] offset:512 nt
	global_load_dwordx2 v[170:171], v2, s[46:47] offset:1024 nt
	global_load_dwordx2 v[174:175], v2, s[46:47] offset:1536 nt
	global_load_dwordx4 v[176:179], v1, s[44:45] offset:0 nt
	global_load_dwordx4 v[180:183], v1, s[44:45] offset:1024 nt
	global_load_dwordx4 v[184:187], v1, s[44:45] offset:2048 nt
	global_load_dwordx4 v[188:191], v1, s[44:45] offset:3072 nt
	s_waitcnt vmcnt(16)
	v_lshlrev_b32_e32 v64, 16, v66
	v_and_b32_e32 v65, 0xffff0000, v66
	v_lshlrev_b32_e32 v66, 16, v67
	v_and_b32_e32 v67, 0xffff0000, v67
	v_lshlrev_b32_e32 v68, 16, v70
	v_and_b32_e32 v69, 0xffff0000, v70
	v_lshlrev_b32_e32 v70, 16, v71
	v_and_b32_e32 v71, 0xffff0000, v71
	v_lshlrev_b32_e32 v72, 16, v74
	v_and_b32_e32 v73, 0xffff0000, v74
	v_lshlrev_b32_e32 v74, 16, v75
	v_and_b32_e32 v75, 0xffff0000, v75
	v_lshlrev_b32_e32 v76, 16, v78
	v_and_b32_e32 v77, 0xffff0000, v78
	v_lshlrev_b32_e32 v78, 16, v79
	v_and_b32_e32 v79, 0xffff0000, v79
	v_lshlrev_b32_e32 v96, 16, v98
	v_and_b32_e32 v97, 0xffff0000, v98
	v_lshlrev_b32_e32 v98, 16, v99
	v_and_b32_e32 v99, 0xffff0000, v99
	v_lshlrev_b32_e32 v100, 16, v102
	v_and_b32_e32 v101, 0xffff0000, v102
	v_lshlrev_b32_e32 v102, 16, v103
	v_and_b32_e32 v103, 0xffff0000, v103
	v_lshlrev_b32_e32 v104, 16, v106
	v_and_b32_e32 v105, 0xffff0000, v106
	v_lshlrev_b32_e32 v106, 16, v107
	v_and_b32_e32 v107, 0xffff0000, v107
	v_lshlrev_b32_e32 v108, 16, v110
	v_and_b32_e32 v109, 0xffff0000, v110
	v_lshlrev_b32_e32 v110, 16, v111
	v_and_b32_e32 v111, 0xffff0000, v111
	v_mul_f32_e32 v10, v64, v64
	v_fmac_f32_e32 v10, v65, v65
	v_fmac_f32_e32 v10, v66, v66
	v_fmac_f32_e32 v10, v67, v67
	v_fmac_f32_e32 v10, v68, v68
	v_fmac_f32_e32 v10, v69, v69
	v_fmac_f32_e32 v10, v70, v70
	v_fmac_f32_e32 v10, v71, v71
	v_fmac_f32_e32 v10, v72, v72
	v_fmac_f32_e32 v10, v73, v73
	v_fmac_f32_e32 v10, v74, v74
	v_fmac_f32_e32 v10, v75, v75
	v_fmac_f32_e32 v10, v76, v76
	v_fmac_f32_e32 v10, v77, v77
	v_fmac_f32_e32 v10, v78, v78
	v_fmac_f32_e32 v10, v79, v79
	v_mul_f32_e32 v11, v96, v96
	v_fmac_f32_e32 v11, v97, v97
	v_fmac_f32_e32 v11, v98, v98
	v_fmac_f32_e32 v11, v99, v99
	v_fmac_f32_e32 v11, v100, v100
	v_fmac_f32_e32 v11, v101, v101
	v_fmac_f32_e32 v11, v102, v102
	v_fmac_f32_e32 v11, v103, v103
	v_fmac_f32_e32 v11, v104, v104
	v_fmac_f32_e32 v11, v105, v105
	v_fmac_f32_e32 v11, v106, v106
	v_fmac_f32_e32 v11, v107, v107
	v_fmac_f32_e32 v11, v108, v108
	v_fmac_f32_e32 v11, v109, v109
	v_fmac_f32_e32 v11, v110, v110
	v_fmac_f32_e32 v11, v111, v111
	ds_bpermute_b32 v12, v4, v10
	ds_bpermute_b32 v13, v4, v11
	s_waitcnt lgkmcnt(0)
	v_add_f32_e32 v10, v10, v12
	v_add_f32_e32 v11, v11, v13
	ds_bpermute_b32 v12, v5, v10
	ds_bpermute_b32 v13, v5, v11
	s_waitcnt lgkmcnt(0)
	v_add_f32_e32 v10, v10, v12
	v_add_f32_e32 v11, v11, v13
	ds_bpermute_b32 v12, v6, v10
	ds_bpermute_b32 v13, v6, v11
	s_waitcnt lgkmcnt(0)
	v_add_f32_e32 v10, v10, v12
	v_add_f32_e32 v11, v11, v13
	ds_bpermute_b32 v12, v7, v10
	ds_bpermute_b32 v13, v7, v11
	s_waitcnt lgkmcnt(0)
	v_add_f32_e32 v10, v10, v12
	v_add_f32_e32 v11, v11, v13
	ds_bpermute_b32 v12, v8, v10
	ds_bpermute_b32 v13, v8, v11
	s_waitcnt lgkmcnt(0)
	v_add_f32_e32 v10, v10, v12
	v_add_f32_e32 v11, v11, v13
	ds_bpermute_b32 v12, v9, v10
	ds_bpermute_b32 v13, v9, v11
	s_waitcnt lgkmcnt(0)
	v_add_f32_e32 v10, v10, v12
	v_add_f32_e32 v11, v11, v13
	v_fma_f32 v14, v10, s17, v3
	v_fma_f32 v15, v11, s17, v3
	v_rsq_f32_e32 v14, v14
	v_rsq_f32_e32 v15, v15
	s_nop 0
	v_mul_f32_e32 v64, v64, v14
	v_mul_f32_e32 v65, v65, v14
	v_mul_f32_e32 v66, v66, v14
	v_mul_f32_e32 v67, v67, v14
	v_mul_f32_e32 v68, v68, v14
	v_mul_f32_e32 v69, v69, v14
	v_mul_f32_e32 v70, v70, v14
	v_mul_f32_e32 v71, v71, v14
	v_mul_f32_e32 v72, v72, v14
	v_mul_f32_e32 v73, v73, v14
	v_mul_f32_e32 v74, v74, v14
	v_mul_f32_e32 v75, v75, v14
	v_mul_f32_e32 v76, v76, v14
	v_mul_f32_e32 v77, v77, v14
	v_mul_f32_e32 v78, v78, v14
	v_mul_f32_e32 v79, v79, v14
	v_fmac_f32_e32 v80, v64, v20
	v_fmac_f32_e32 v81, v65, v21
	v_fmac_f32_e32 v82, v66, v22
	v_fmac_f32_e32 v83, v67, v23
	v_fmac_f32_e32 v84, v68, v24
	v_fmac_f32_e32 v85, v69, v25
	v_fmac_f32_e32 v86, v70, v26
	v_fmac_f32_e32 v87, v71, v27
	v_fmac_f32_e32 v88, v72, v28
	v_fmac_f32_e32 v89, v73, v29
	v_fmac_f32_e32 v90, v74, v30
	v_fmac_f32_e32 v91, v75, v31
	v_fmac_f32_e32 v92, v76, v32
	v_fmac_f32_e32 v93, v77, v33
	v_fmac_f32_e32 v94, v78, v34
	v_fmac_f32_e32 v95, v79, v35
	global_store_dwordx4 v1, v[80:83], s[24:25] offset:0 nt
	global_store_dwordx4 v1, v[84:87], s[24:25] offset:1024 nt
	global_store_dwordx4 v1, v[88:91], s[24:25] offset:2048 nt
	global_store_dwordx4 v1, v[92:95], s[24:25] offset:3072 nt
	v_mul_f32_e32 v96, v96, v15
	v_mul_f32_e32 v97, v97, v15
	v_mul_f32_e32 v98, v98, v15
	v_mul_f32_e32 v99, v99, v15
	v_mul_f32_e32 v100, v100, v15
	v_mul_f32_e32 v101, v101, v15
	v_mul_f32_e32 v102, v102, v15
	v_mul_f32_e32 v103, v103, v15
	v_mul_f32_e32 v104, v104, v15
	v_mul_f32_e32 v105, v105, v15
	v_mul_f32_e32 v106, v106, v15
	v_mul_f32_e32 v107, v107, v15
	v_mul_f32_e32 v108, v108, v15
	v_mul_f32_e32 v109, v109, v15
	v_mul_f32_e32 v110, v110, v15
	v_mul_f32_e32 v111, v111, v15
	v_fmac_f32_e32 v112, v96, v20
	v_fmac_f32_e32 v113, v97, v21
	v_fmac_f32_e32 v114, v98, v22
	v_fmac_f32_e32 v115, v99, v23
	v_fmac_f32_e32 v116, v100, v24
	v_fmac_f32_e32 v117, v101, v25
	v_fmac_f32_e32 v118, v102, v26
	v_fmac_f32_e32 v119, v103, v27
	v_fmac_f32_e32 v120, v104, v28
	v_fmac_f32_e32 v121, v105, v29
	v_fmac_f32_e32 v122, v106, v30
	v_fmac_f32_e32 v123, v107, v31
	v_fmac_f32_e32 v124, v108, v32
	v_fmac_f32_e32 v125, v109, v33
	v_fmac_f32_e32 v126, v110, v34
	v_fmac_f32_e32 v127, v111, v35
	global_store_dwordx4 v1, v[112:115], s[32:33] offset:0 nt
	global_store_dwordx4 v1, v[116:119], s[32:33] offset:1024 nt
	global_store_dwordx4 v1, v[120:123], s[32:33] offset:2048 nt
	global_store_dwordx4 v1, v[124:127], s[32:33] offset:3072 nt
	s_add_u32 s53, s16, 0x2000
	s_lshl_b32 s18, s53, 12
	s_lshl_b32 s19, s53, 11
	s_add_u32 s20, s4, s18
	s_addc_u32 s21, s5, 0
	s_add_u32 s22, s6, s19
	s_addc_u32 s23, s7, 0
	s_add_u32 s22, s22, 0x5200000
	s_addc_u32 s23, s23, 0
	s_add_u32 s24, s4, s18
	s_addc_u32 s25, s5, 0
	global_load_dwordx2 v[66:67], v2, s[22:23] offset:0 nt
	global_load_dwordx2 v[70:71], v2, s[22:23] offset:512 nt
	global_load_dwordx2 v[74:75], v2, s[22:23] offset:1024 nt
	global_load_dwordx2 v[78:79], v2, s[22:23] offset:1536 nt
	global_load_dwordx4 v[80:83], v1, s[20:21] offset:0 nt
	global_load_dwordx4 v[84:87], v1, s[20:21] offset:1024 nt
	global_load_dwordx4 v[88:91], v1, s[20:21] offset:2048 nt
	global_load_dwordx4 v[92:95], v1, s[20:21] offset:3072 nt
	s_add_u32 s53, s16, 0x2800
	s_lshl_b32 s18, s53, 12
	s_lshl_b32 s19, s53, 11
	s_add_u32 s28, s4, s18
	s_addc_u32 s29, s5, 0
	s_add_u32 s30, s6, s19
	s_addc_u32 s31, s7, 0
	s_add_u32 s30, s30, 0x5200000
	s_addc_u32 s31, s31, 0
	s_add_u32 s32, s4, s18
	s_addc_u32 s33, s5, 0
	global_load_dwordx2 v[98:99], v2, s[30:31] offset:0 nt
	global_load_dwordx2 v[102:103], v2, s[30:31] offset:512 nt
	global_load_dwordx2 v[106:107], v2, s[30:31] offset:1024 nt
	global_load_dwordx2 v[110:111], v2, s[30:31] offset:1536 nt
	global_load_dwordx4 v[112:115], v1, s[28:29] offset:0 nt
	global_load_dwordx4 v[116:119], v1, s[28:29] offset:1024 nt
	global_load_dwordx4 v[120:123], v1, s[28:29] offset:2048 nt
	global_load_dwordx4 v[124:127], v1, s[28:29] offset:3072 nt
	s_waitcnt vmcnt(24)
	v_lshlrev_b32_e32 v128, 16, v130
	v_and_b32_e32 v129, 0xffff0000, v130
	v_lshlrev_b32_e32 v130, 16, v131
	v_and_b32_e32 v131, 0xffff0000, v131
	v_lshlrev_b32_e32 v132, 16, v134
	v_and_b32_e32 v133, 0xffff0000, v134
	v_lshlrev_b32_e32 v134, 16, v135
	v_and_b32_e32 v135, 0xffff0000, v135
	v_lshlrev_b32_e32 v136, 16, v138
	v_and_b32_e32 v137, 0xffff0000, v138
	v_lshlrev_b32_e32 v138, 16, v139
	v_and_b32_e32 v139, 0xffff0000, v139
	v_lshlrev_b32_e32 v140, 16, v142
	v_and_b32_e32 v141, 0xffff0000, v142
	v_lshlrev_b32_e32 v142, 16, v143
	v_and_b32_e32 v143, 0xffff0000, v143
	v_lshlrev_b32_e32 v160, 16, v162
	v_and_b32_e32 v161, 0xffff0000, v162
	v_lshlrev_b32_e32 v162, 16, v163
	v_and_b32_e32 v163, 0xffff0000, v163
	v_lshlrev_b32_e32 v164, 16, v166
	v_and_b32_e32 v165, 0xffff0000, v166
	v_lshlrev_b32_e32 v166, 16, v167
	v_and_b32_e32 v167, 0xffff0000, v167
	v_lshlrev_b32_e32 v168, 16, v170
	v_and_b32_e32 v169, 0xffff0000, v170
	v_lshlrev_b32_e32 v170, 16, v171
	v_and_b32_e32 v171, 0xffff0000, v171
	v_lshlrev_b32_e32 v172, 16, v174
	v_and_b32_e32 v173, 0xffff0000, v174
	v_lshlrev_b32_e32 v174, 16, v175
	v_and_b32_e32 v175, 0xffff0000, v175
	v_mul_f32_e32 v10, v128, v128
	v_fmac_f32_e32 v10, v129, v129
	v_fmac_f32_e32 v10, v130, v130
	v_fmac_f32_e32 v10, v131, v131
	v_fmac_f32_e32 v10, v132, v132
	v_fmac_f32_e32 v10, v133, v133
	v_fmac_f32_e32 v10, v134, v134
	v_fmac_f32_e32 v10, v135, v135
	v_fmac_f32_e32 v10, v136, v136
	v_fmac_f32_e32 v10, v137, v137
	v_fmac_f32_e32 v10, v138, v138
	v_fmac_f32_e32 v10, v139, v139
	v_fmac_f32_e32 v10, v140, v140
	v_fmac_f32_e32 v10, v141, v141
	v_fmac_f32_e32 v10, v142, v142
	v_fmac_f32_e32 v10, v143, v143
	v_mul_f32_e32 v11, v160, v160
	v_fmac_f32_e32 v11, v161, v161
	v_fmac_f32_e32 v11, v162, v162
	v_fmac_f32_e32 v11, v163, v163
	v_fmac_f32_e32 v11, v164, v164
	v_fmac_f32_e32 v11, v165, v165
	v_fmac_f32_e32 v11, v166, v166
	v_fmac_f32_e32 v11, v167, v167
	v_fmac_f32_e32 v11, v168, v168
	v_fmac_f32_e32 v11, v169, v169
	v_fmac_f32_e32 v11, v170, v170
	v_fmac_f32_e32 v11, v171, v171
	v_fmac_f32_e32 v11, v172, v172
	v_fmac_f32_e32 v11, v173, v173
	v_fmac_f32_e32 v11, v174, v174
	v_fmac_f32_e32 v11, v175, v175
	ds_bpermute_b32 v12, v4, v10
	ds_bpermute_b32 v13, v4, v11
	s_waitcnt lgkmcnt(0)
	v_add_f32_e32 v10, v10, v12
	v_add_f32_e32 v11, v11, v13
	ds_bpermute_b32 v12, v5, v10
	ds_bpermute_b32 v13, v5, v11
	s_waitcnt lgkmcnt(0)
	v_add_f32_e32 v10, v10, v12
	v_add_f32_e32 v11, v11, v13
	ds_bpermute_b32 v12, v6, v10
	ds_bpermute_b32 v13, v6, v11
	s_waitcnt lgkmcnt(0)
	v_add_f32_e32 v10, v10, v12
	v_add_f32_e32 v11, v11, v13
	ds_bpermute_b32 v12, v7, v10
	ds_bpermute_b32 v13, v7, v11
	s_waitcnt lgkmcnt(0)
	v_add_f32_e32 v10, v10, v12
	v_add_f32_e32 v11, v11, v13
	ds_bpermute_b32 v12, v8, v10
	ds_bpermute_b32 v13, v8, v11
	s_waitcnt lgkmcnt(0)
	v_add_f32_e32 v10, v10, v12
	v_add_f32_e32 v11, v11, v13
	ds_bpermute_b32 v12, v9, v10
	ds_bpermute_b32 v13, v9, v11
	s_waitcnt lgkmcnt(0)
	v_add_f32_e32 v10, v10, v12
	v_add_f32_e32 v11, v11, v13
	v_fma_f32 v14, v10, s17, v3
	v_fma_f32 v15, v11, s17, v3
	v_rsq_f32_e32 v14, v14
	v_rsq_f32_e32 v15, v15
	s_nop 0
	v_mul_f32_e32 v128, v128, v14
	v_mul_f32_e32 v129, v129, v14
	v_mul_f32_e32 v130, v130, v14
	v_mul_f32_e32 v131, v131, v14
	v_mul_f32_e32 v132, v132, v14
	v_mul_f32_e32 v133, v133, v14
	v_mul_f32_e32 v134, v134, v14
	v_mul_f32_e32 v135, v135, v14
	v_mul_f32_e32 v136, v136, v14
	v_mul_f32_e32 v137, v137, v14
	v_mul_f32_e32 v138, v138, v14
	v_mul_f32_e32 v139, v139, v14
	v_mul_f32_e32 v140, v140, v14
	v_mul_f32_e32 v141, v141, v14
	v_mul_f32_e32 v142, v142, v14
	v_mul_f32_e32 v143, v143, v14
	v_fmac_f32_e32 v144, v128, v20
	v_fmac_f32_e32 v145, v129, v21
	v_fmac_f32_e32 v146, v130, v22
	v_fmac_f32_e32 v147, v131, v23
	v_fmac_f32_e32 v148, v132, v24
	v_fmac_f32_e32 v149, v133, v25
	v_fmac_f32_e32 v150, v134, v26
	v_fmac_f32_e32 v151, v135, v27
	v_fmac_f32_e32 v152, v136, v28
	v_fmac_f32_e32 v153, v137, v29
	v_fmac_f32_e32 v154, v138, v30
	v_fmac_f32_e32 v155, v139, v31
	v_fmac_f32_e32 v156, v140, v32
	v_fmac_f32_e32 v157, v141, v33
	v_fmac_f32_e32 v158, v142, v34
	v_fmac_f32_e32 v159, v143, v35
	global_store_dwordx4 v1, v[144:147], s[40:41] offset:0 nt
	global_store_dwordx4 v1, v[148:151], s[40:41] offset:1024 nt
	global_store_dwordx4 v1, v[152:155], s[40:41] offset:2048 nt
	global_store_dwordx4 v1, v[156:159], s[40:41] offset:3072 nt
	v_mul_f32_e32 v160, v160, v15
	v_mul_f32_e32 v161, v161, v15
	v_mul_f32_e32 v162, v162, v15
	v_mul_f32_e32 v163, v163, v15
	v_mul_f32_e32 v164, v164, v15
	v_mul_f32_e32 v165, v165, v15
	v_mul_f32_e32 v166, v166, v15
	v_mul_f32_e32 v167, v167, v15
	v_mul_f32_e32 v168, v168, v15
	v_mul_f32_e32 v169, v169, v15
	v_mul_f32_e32 v170, v170, v15
	v_mul_f32_e32 v171, v171, v15
	v_mul_f32_e32 v172, v172, v15
	v_mul_f32_e32 v173, v173, v15
	v_mul_f32_e32 v174, v174, v15
	v_mul_f32_e32 v175, v175, v15
	v_fmac_f32_e32 v176, v160, v20
	v_fmac_f32_e32 v177, v161, v21
	v_fmac_f32_e32 v178, v162, v22
	v_fmac_f32_e32 v179, v163, v23
	v_fmac_f32_e32 v180, v164, v24
	v_fmac_f32_e32 v181, v165, v25
	v_fmac_f32_e32 v182, v166, v26
	v_fmac_f32_e32 v183, v167, v27
	v_fmac_f32_e32 v184, v168, v28
	v_fmac_f32_e32 v185, v169, v29
	v_fmac_f32_e32 v186, v170, v30
	v_fmac_f32_e32 v187, v171, v31
	v_fmac_f32_e32 v188, v172, v32
	v_fmac_f32_e32 v189, v173, v33
	v_fmac_f32_e32 v190, v174, v34
	v_fmac_f32_e32 v191, v175, v35
	global_store_dwordx4 v1, v[176:179], s[48:49] offset:0 nt
	global_store_dwordx4 v1, v[180:183], s[48:49] offset:1024 nt
	global_store_dwordx4 v1, v[184:187], s[48:49] offset:2048 nt
	global_store_dwordx4 v1, v[188:191], s[48:49] offset:3072 nt
	s_add_u32 s53, s16, 0x3000
	s_lshl_b32 s18, s53, 12
	s_lshl_b32 s19, s53, 11
	s_add_u32 s36, s4, s18
	s_addc_u32 s37, s5, 0
	s_add_u32 s38, s6, s19
	s_addc_u32 s39, s7, 0
	s_add_u32 s38, s38, 0x5200000
	s_addc_u32 s39, s39, 0
	s_add_u32 s40, s4, s18
	s_addc_u32 s41, s5, 0
	global_load_dwordx2 v[130:131], v2, s[38:39] offset:0 nt
	global_load_dwordx2 v[134:135], v2, s[38:39] offset:512 nt
	global_load_dwordx2 v[138:139], v2, s[38:39] offset:1024 nt
	global_load_dwordx2 v[142:143], v2, s[38:39] offset:1536 nt
	global_load_dwordx4 v[144:147], v1, s[36:37] offset:0 nt
	global_load_dwordx4 v[148:151], v1, s[36:37] offset:1024 nt
	global_load_dwordx4 v[152:155], v1, s[36:37] offset:2048 nt
	global_load_dwordx4 v[156:159], v1, s[36:37] offset:3072 nt
	s_add_u32 s53, s16, 0x3800
	s_lshl_b32 s18, s53, 12
	s_lshl_b32 s19, s53, 11
	s_add_u32 s44, s4, s18
	s_addc_u32 s45, s5, 0
	s_add_u32 s46, s6, s19
	s_addc_u32 s47, s7, 0
	s_add_u32 s46, s46, 0x5200000
	s_addc_u32 s47, s47, 0
	s_add_u32 s48, s4, s18
	s_addc_u32 s49, s5, 0
	global_load_dwordx2 v[162:163], v2, s[46:47] offset:0 nt
	global_load_dwordx2 v[166:167], v2, s[46:47] offset:512 nt
	global_load_dwordx2 v[170:171], v2, s[46:47] offset:1024 nt
	global_load_dwordx2 v[174:175], v2, s[46:47] offset:1536 nt
	global_load_dwordx4 v[176:179], v1, s[44:45] offset:0 nt
	global_load_dwordx4 v[180:183], v1, s[44:45] offset:1024 nt
	global_load_dwordx4 v[184:187], v1, s[44:45] offset:2048 nt
	global_load_dwordx4 v[188:191], v1, s[44:45] offset:3072 nt
	s_waitcnt vmcnt(24)
	v_lshlrev_b32_e32 v64, 16, v66
	v_and_b32_e32 v65, 0xffff0000, v66
	v_lshlrev_b32_e32 v66, 16, v67
	v_and_b32_e32 v67, 0xffff0000, v67
	v_lshlrev_b32_e32 v68, 16, v70
	v_and_b32_e32 v69, 0xffff0000, v70
	v_lshlrev_b32_e32 v70, 16, v71
	v_and_b32_e32 v71, 0xffff0000, v71
	v_lshlrev_b32_e32 v72, 16, v74
	v_and_b32_e32 v73, 0xffff0000, v74
	v_lshlrev_b32_e32 v74, 16, v75
	v_and_b32_e32 v75, 0xffff0000, v75
	v_lshlrev_b32_e32 v76, 16, v78
	v_and_b32_e32 v77, 0xffff0000, v78
	v_lshlrev_b32_e32 v78, 16, v79
	v_and_b32_e32 v79, 0xffff0000, v79
	v_lshlrev_b32_e32 v96, 16, v98
	v_and_b32_e32 v97, 0xffff0000, v98
	v_lshlrev_b32_e32 v98, 16, v99
	v_and_b32_e32 v99, 0xffff0000, v99
	v_lshlrev_b32_e32 v100, 16, v102
	v_and_b32_e32 v101, 0xffff0000, v102
	v_lshlrev_b32_e32 v102, 16, v103
	v_and_b32_e32 v103, 0xffff0000, v103
	v_lshlrev_b32_e32 v104, 16, v106
	v_and_b32_e32 v105, 0xffff0000, v106
	v_lshlrev_b32_e32 v106, 16, v107
	v_and_b32_e32 v107, 0xffff0000, v107
	v_lshlrev_b32_e32 v108, 16, v110
	v_and_b32_e32 v109, 0xffff0000, v110
	v_lshlrev_b32_e32 v110, 16, v111
	v_and_b32_e32 v111, 0xffff0000, v111
	v_mul_f32_e32 v10, v64, v64
	v_fmac_f32_e32 v10, v65, v65
	v_fmac_f32_e32 v10, v66, v66
	v_fmac_f32_e32 v10, v67, v67
	v_fmac_f32_e32 v10, v68, v68
	v_fmac_f32_e32 v10, v69, v69
	v_fmac_f32_e32 v10, v70, v70
	v_fmac_f32_e32 v10, v71, v71
	v_fmac_f32_e32 v10, v72, v72
	v_fmac_f32_e32 v10, v73, v73
	v_fmac_f32_e32 v10, v74, v74
	v_fmac_f32_e32 v10, v75, v75
	v_fmac_f32_e32 v10, v76, v76
	v_fmac_f32_e32 v10, v77, v77
	v_fmac_f32_e32 v10, v78, v78
	v_fmac_f32_e32 v10, v79, v79
	v_mul_f32_e32 v11, v96, v96
	v_fmac_f32_e32 v11, v97, v97
	v_fmac_f32_e32 v11, v98, v98
	v_fmac_f32_e32 v11, v99, v99
	v_fmac_f32_e32 v11, v100, v100
	v_fmac_f32_e32 v11, v101, v101
	v_fmac_f32_e32 v11, v102, v102
	v_fmac_f32_e32 v11, v103, v103
	v_fmac_f32_e32 v11, v104, v104
	v_fmac_f32_e32 v11, v105, v105
	v_fmac_f32_e32 v11, v106, v106
	v_fmac_f32_e32 v11, v107, v107
	v_fmac_f32_e32 v11, v108, v108
	v_fmac_f32_e32 v11, v109, v109
	v_fmac_f32_e32 v11, v110, v110
	v_fmac_f32_e32 v11, v111, v111
	ds_bpermute_b32 v12, v4, v10
	ds_bpermute_b32 v13, v4, v11
	s_waitcnt lgkmcnt(0)
	v_add_f32_e32 v10, v10, v12
	v_add_f32_e32 v11, v11, v13
	ds_bpermute_b32 v12, v5, v10
	ds_bpermute_b32 v13, v5, v11
	s_waitcnt lgkmcnt(0)
	v_add_f32_e32 v10, v10, v12
	v_add_f32_e32 v11, v11, v13
	ds_bpermute_b32 v12, v6, v10
	ds_bpermute_b32 v13, v6, v11
	s_waitcnt lgkmcnt(0)
	v_add_f32_e32 v10, v10, v12
	v_add_f32_e32 v11, v11, v13
	ds_bpermute_b32 v12, v7, v10
	ds_bpermute_b32 v13, v7, v11
	s_waitcnt lgkmcnt(0)
	v_add_f32_e32 v10, v10, v12
	v_add_f32_e32 v11, v11, v13
	ds_bpermute_b32 v12, v8, v10
	ds_bpermute_b32 v13, v8, v11
	s_waitcnt lgkmcnt(0)
	v_add_f32_e32 v10, v10, v12
	v_add_f32_e32 v11, v11, v13
	ds_bpermute_b32 v12, v9, v10
	ds_bpermute_b32 v13, v9, v11
	s_waitcnt lgkmcnt(0)
	v_add_f32_e32 v10, v10, v12
	v_add_f32_e32 v11, v11, v13
	v_fma_f32 v14, v10, s17, v3
	v_fma_f32 v15, v11, s17, v3
	v_rsq_f32_e32 v14, v14
	v_rsq_f32_e32 v15, v15
	s_nop 0
	v_mul_f32_e32 v64, v64, v14
	v_mul_f32_e32 v65, v65, v14
	v_mul_f32_e32 v66, v66, v14
	v_mul_f32_e32 v67, v67, v14
	v_mul_f32_e32 v68, v68, v14
	v_mul_f32_e32 v69, v69, v14
	v_mul_f32_e32 v70, v70, v14
	v_mul_f32_e32 v71, v71, v14
	v_mul_f32_e32 v72, v72, v14
	v_mul_f32_e32 v73, v73, v14
	v_mul_f32_e32 v74, v74, v14
	v_mul_f32_e32 v75, v75, v14
	v_mul_f32_e32 v76, v76, v14
	v_mul_f32_e32 v77, v77, v14
	v_mul_f32_e32 v78, v78, v14
	v_mul_f32_e32 v79, v79, v14
	v_fmac_f32_e32 v80, v64, v20
	v_fmac_f32_e32 v81, v65, v21
	v_fmac_f32_e32 v82, v66, v22
	v_fmac_f32_e32 v83, v67, v23
	v_fmac_f32_e32 v84, v68, v24
	v_fmac_f32_e32 v85, v69, v25
	v_fmac_f32_e32 v86, v70, v26
	v_fmac_f32_e32 v87, v71, v27
	v_fmac_f32_e32 v88, v72, v28
	v_fmac_f32_e32 v89, v73, v29
	v_fmac_f32_e32 v90, v74, v30
	v_fmac_f32_e32 v91, v75, v31
	v_fmac_f32_e32 v92, v76, v32
	v_fmac_f32_e32 v93, v77, v33
	v_fmac_f32_e32 v94, v78, v34
	v_fmac_f32_e32 v95, v79, v35
	global_store_dwordx4 v1, v[80:83], s[24:25] offset:0 nt
	global_store_dwordx4 v1, v[84:87], s[24:25] offset:1024 nt
	global_store_dwordx4 v1, v[88:91], s[24:25] offset:2048 nt
	global_store_dwordx4 v1, v[92:95], s[24:25] offset:3072 nt
	v_mul_f32_e32 v96, v96, v15
	v_mul_f32_e32 v97, v97, v15
	v_mul_f32_e32 v98, v98, v15
	v_mul_f32_e32 v99, v99, v15
	v_mul_f32_e32 v100, v100, v15
	v_mul_f32_e32 v101, v101, v15
	v_mul_f32_e32 v102, v102, v15
	v_mul_f32_e32 v103, v103, v15
	v_mul_f32_e32 v104, v104, v15
	v_mul_f32_e32 v105, v105, v15
	v_mul_f32_e32 v106, v106, v15
	v_mul_f32_e32 v107, v107, v15
	v_mul_f32_e32 v108, v108, v15
	v_mul_f32_e32 v109, v109, v15
	v_mul_f32_e32 v110, v110, v15
	v_mul_f32_e32 v111, v111, v15
	v_fmac_f32_e32 v112, v96, v20
	v_fmac_f32_e32 v113, v97, v21
	v_fmac_f32_e32 v114, v98, v22
	v_fmac_f32_e32 v115, v99, v23
	v_fmac_f32_e32 v116, v100, v24
	v_fmac_f32_e32 v117, v101, v25
	v_fmac_f32_e32 v118, v102, v26
	v_fmac_f32_e32 v119, v103, v27
	v_fmac_f32_e32 v120, v104, v28
	v_fmac_f32_e32 v121, v105, v29
	v_fmac_f32_e32 v122, v106, v30
	v_fmac_f32_e32 v123, v107, v31
	v_fmac_f32_e32 v124, v108, v32
	v_fmac_f32_e32 v125, v109, v33
	v_fmac_f32_e32 v126, v110, v34
	v_fmac_f32_e32 v127, v111, v35
	global_store_dwordx4 v1, v[112:115], s[32:33] offset:0 nt
	global_store_dwordx4 v1, v[116:119], s[32:33] offset:1024 nt
	global_store_dwordx4 v1, v[120:123], s[32:33] offset:2048 nt
	global_store_dwordx4 v1, v[124:127], s[32:33] offset:3072 nt
	s_waitcnt vmcnt(8)
	v_lshlrev_b32_e32 v128, 16, v130
	v_and_b32_e32 v129, 0xffff0000, v130
	v_lshlrev_b32_e32 v130, 16, v131
	v_and_b32_e32 v131, 0xffff0000, v131
	v_lshlrev_b32_e32 v132, 16, v134
	v_and_b32_e32 v133, 0xffff0000, v134
	v_lshlrev_b32_e32 v134, 16, v135
	v_and_b32_e32 v135, 0xffff0000, v135
	v_lshlrev_b32_e32 v136, 16, v138
	v_and_b32_e32 v137, 0xffff0000, v138
	v_lshlrev_b32_e32 v138, 16, v139
	v_and_b32_e32 v139, 0xffff0000, v139
	v_lshlrev_b32_e32 v140, 16, v142
	v_and_b32_e32 v141, 0xffff0000, v142
	v_lshlrev_b32_e32 v142, 16, v143
	v_and_b32_e32 v143, 0xffff0000, v143
	v_lshlrev_b32_e32 v160, 16, v162
	v_and_b32_e32 v161, 0xffff0000, v162
	v_lshlrev_b32_e32 v162, 16, v163
	v_and_b32_e32 v163, 0xffff0000, v163
	v_lshlrev_b32_e32 v164, 16, v166
	v_and_b32_e32 v165, 0xffff0000, v166
	v_lshlrev_b32_e32 v166, 16, v167
	v_and_b32_e32 v167, 0xffff0000, v167
	v_lshlrev_b32_e32 v168, 16, v170
	v_and_b32_e32 v169, 0xffff0000, v170
	v_lshlrev_b32_e32 v170, 16, v171
	v_and_b32_e32 v171, 0xffff0000, v171
	v_lshlrev_b32_e32 v172, 16, v174
	v_and_b32_e32 v173, 0xffff0000, v174
	v_lshlrev_b32_e32 v174, 16, v175
	v_and_b32_e32 v175, 0xffff0000, v175
	v_mul_f32_e32 v10, v128, v128
	v_fmac_f32_e32 v10, v129, v129
	v_fmac_f32_e32 v10, v130, v130
	v_fmac_f32_e32 v10, v131, v131
	v_fmac_f32_e32 v10, v132, v132
	v_fmac_f32_e32 v10, v133, v133
	v_fmac_f32_e32 v10, v134, v134
	v_fmac_f32_e32 v10, v135, v135
	v_fmac_f32_e32 v10, v136, v136
	v_fmac_f32_e32 v10, v137, v137
	v_fmac_f32_e32 v10, v138, v138
	v_fmac_f32_e32 v10, v139, v139
	v_fmac_f32_e32 v10, v140, v140
	v_fmac_f32_e32 v10, v141, v141
	v_fmac_f32_e32 v10, v142, v142
	v_fmac_f32_e32 v10, v143, v143
	v_mul_f32_e32 v11, v160, v160
	v_fmac_f32_e32 v11, v161, v161
	v_fmac_f32_e32 v11, v162, v162
	v_fmac_f32_e32 v11, v163, v163
	v_fmac_f32_e32 v11, v164, v164
	v_fmac_f32_e32 v11, v165, v165
	v_fmac_f32_e32 v11, v166, v166
	v_fmac_f32_e32 v11, v167, v167
	v_fmac_f32_e32 v11, v168, v168
	v_fmac_f32_e32 v11, v169, v169
	v_fmac_f32_e32 v11, v170, v170
	v_fmac_f32_e32 v11, v171, v171
	v_fmac_f32_e32 v11, v172, v172
	v_fmac_f32_e32 v11, v173, v173
	v_fmac_f32_e32 v11, v174, v174
	v_fmac_f32_e32 v11, v175, v175
	ds_bpermute_b32 v12, v4, v10
	ds_bpermute_b32 v13, v4, v11
	s_waitcnt lgkmcnt(0)
	v_add_f32_e32 v10, v10, v12
	v_add_f32_e32 v11, v11, v13
	ds_bpermute_b32 v12, v5, v10
	ds_bpermute_b32 v13, v5, v11
	s_waitcnt lgkmcnt(0)
	v_add_f32_e32 v10, v10, v12
	v_add_f32_e32 v11, v11, v13
	ds_bpermute_b32 v12, v6, v10
	ds_bpermute_b32 v13, v6, v11
	s_waitcnt lgkmcnt(0)
	v_add_f32_e32 v10, v10, v12
	v_add_f32_e32 v11, v11, v13
	ds_bpermute_b32 v12, v7, v10
	ds_bpermute_b32 v13, v7, v11
	s_waitcnt lgkmcnt(0)
	v_add_f32_e32 v10, v10, v12
	v_add_f32_e32 v11, v11, v13
	ds_bpermute_b32 v12, v8, v10
	ds_bpermute_b32 v13, v8, v11
	s_waitcnt lgkmcnt(0)
	v_add_f32_e32 v10, v10, v12
	v_add_f32_e32 v11, v11, v13
	ds_bpermute_b32 v12, v9, v10
	ds_bpermute_b32 v13, v9, v11
	s_waitcnt lgkmcnt(0)
	v_add_f32_e32 v10, v10, v12
	v_add_f32_e32 v11, v11, v13
	v_fma_f32 v14, v10, s17, v3
	v_fma_f32 v15, v11, s17, v3
	v_rsq_f32_e32 v14, v14
	v_rsq_f32_e32 v15, v15
	s_nop 0
	v_mul_f32_e32 v128, v128, v14
	v_mul_f32_e32 v129, v129, v14
	v_mul_f32_e32 v130, v130, v14
	v_mul_f32_e32 v131, v131, v14
	v_mul_f32_e32 v132, v132, v14
	v_mul_f32_e32 v133, v133, v14
	v_mul_f32_e32 v134, v134, v14
	v_mul_f32_e32 v135, v135, v14
	v_mul_f32_e32 v136, v136, v14
	v_mul_f32_e32 v137, v137, v14
	v_mul_f32_e32 v138, v138, v14
	v_mul_f32_e32 v139, v139, v14
	v_mul_f32_e32 v140, v140, v14
	v_mul_f32_e32 v141, v141, v14
	v_mul_f32_e32 v142, v142, v14
	v_mul_f32_e32 v143, v143, v14
	v_fmac_f32_e32 v144, v128, v20
	v_fmac_f32_e32 v145, v129, v21
	v_fmac_f32_e32 v146, v130, v22
	v_fmac_f32_e32 v147, v131, v23
	v_fmac_f32_e32 v148, v132, v24
	v_fmac_f32_e32 v149, v133, v25
	v_fmac_f32_e32 v150, v134, v26
	v_fmac_f32_e32 v151, v135, v27
	v_fmac_f32_e32 v152, v136, v28
	v_fmac_f32_e32 v153, v137, v29
	v_fmac_f32_e32 v154, v138, v30
	v_fmac_f32_e32 v155, v139, v31
	v_fmac_f32_e32 v156, v140, v32
	v_fmac_f32_e32 v157, v141, v33
	v_fmac_f32_e32 v158, v142, v34
	v_fmac_f32_e32 v159, v143, v35
	global_store_dwordx4 v1, v[144:147], s[40:41] offset:0 nt
	global_store_dwordx4 v1, v[148:151], s[40:41] offset:1024 nt
	global_store_dwordx4 v1, v[152:155], s[40:41] offset:2048 nt
	global_store_dwordx4 v1, v[156:159], s[40:41] offset:3072 nt
	v_mul_f32_e32 v160, v160, v15
	v_mul_f32_e32 v161, v161, v15
	v_mul_f32_e32 v162, v162, v15
	v_mul_f32_e32 v163, v163, v15
	v_mul_f32_e32 v164, v164, v15
	v_mul_f32_e32 v165, v165, v15
	v_mul_f32_e32 v166, v166, v15
	v_mul_f32_e32 v167, v167, v15
	v_mul_f32_e32 v168, v168, v15
	v_mul_f32_e32 v169, v169, v15
	v_mul_f32_e32 v170, v170, v15
	v_mul_f32_e32 v171, v171, v15
	v_mul_f32_e32 v172, v172, v15
	v_mul_f32_e32 v173, v173, v15
	v_mul_f32_e32 v174, v174, v15
	v_mul_f32_e32 v175, v175, v15
	v_fmac_f32_e32 v176, v160, v20
	v_fmac_f32_e32 v177, v161, v21
	v_fmac_f32_e32 v178, v162, v22
	v_fmac_f32_e32 v179, v163, v23
	v_fmac_f32_e32 v180, v164, v24
	v_fmac_f32_e32 v181, v165, v25
	v_fmac_f32_e32 v182, v166, v26
	v_fmac_f32_e32 v183, v167, v27
	v_fmac_f32_e32 v184, v168, v28
	v_fmac_f32_e32 v185, v169, v29
	v_fmac_f32_e32 v186, v170, v30
	v_fmac_f32_e32 v187, v171, v31
	v_fmac_f32_e32 v188, v172, v32
	v_fmac_f32_e32 v189, v173, v33
	v_fmac_f32_e32 v190, v174, v34
	v_fmac_f32_e32 v191, v175, v35
	global_store_dwordx4 v1, v[176:179], s[48:49] offset:0 nt
	global_store_dwordx4 v1, v[180:183], s[48:49] offset:1024 nt
	global_store_dwordx4 v1, v[184:187], s[48:49] offset:2048 nt
	global_store_dwordx4 v1, v[188:191], s[48:49] offset:3072 nt
	v_add_f32_e32 v208, v208, v212
	v_add_f32_e32 v209, v209, v213
	v_add_f32_e32 v210, v210, v214
	v_add_f32_e32 v211, v211, v215
	v_add_f32_e32 v216, v216, v220
	v_add_f32_e32 v217, v217, v221
	v_add_f32_e32 v218, v218, v222
	v_add_f32_e32 v219, v219, v223
	v_add_f32_e32 v224, v224, v228
	v_add_f32_e32 v225, v225, v229
	v_add_f32_e32 v226, v226, v230
	v_add_f32_e32 v227, v227, v231
	v_add_f32_e32 v232, v232, v236
	v_add_f32_e32 v233, v233, v237
	v_add_f32_e32 v234, v234, v238
	v_add_f32_e32 v235, v235, v239
	v_add_f32_e32 v208, v208, v216
	v_add_f32_e32 v209, v209, v217
	v_add_f32_e32 v210, v210, v218
	v_add_f32_e32 v211, v211, v219
	v_add_f32_e32 v224, v224, v232
	v_add_f32_e32 v225, v225, v233
	v_add_f32_e32 v226, v226, v234
	v_add_f32_e32 v227, v227, v235
	v_add_f32_e32 v208, v208, v224
	v_add_f32_e32 v209, v209, v225
	v_add_f32_e32 v210, v210, v226
	v_add_f32_e32 v211, v211, v227
	v_readfirstlane_b32 s18, v0
	s_lshr_b32 s18, s18, 6
	s_lshl_b32 s19, s18, 2
	s_and_b32 s52, s18, 4
	s_lshl_b32 s52, s52, 2
	v_mov_b32_e32 v16, s19
	v_mov_b32_e32 v17, s52
	v_mul_f32_e32 v10, v208, v208
	v_fmac_f32_e32 v10, v209, v209
	v_fmac_f32_e32 v10, v210, v210
	v_fmac_f32_e32 v10, v211, v211
	ds_bpermute_b32 v11, v4, v10
	s_waitcnt lgkmcnt(0)
	v_add_f32_e32 v10, v10, v11
	ds_bpermute_b32 v11, v5, v10
	s_waitcnt lgkmcnt(0)
	v_add_f32_e32 v10, v10, v11
	ds_bpermute_b32 v11, v6, v10
	s_waitcnt lgkmcnt(0)
	v_add_f32_e32 v10, v10, v11
	ds_bpermute_b32 v11, v7, v10
	s_waitcnt lgkmcnt(0)
	v_add_f32_e32 v10, v10, v11
	ds_bpermute_b32 v11, v8, v10
	s_waitcnt lgkmcnt(0)
	v_add_f32_e32 v10, v10, v11
	ds_bpermute_b32 v11, v9, v10
	s_waitcnt lgkmcnt(0)
	v_add_f32_e32 v10, v10, v11
	ds_write_b32 v16, v10 offset:0
	s_waitcnt lgkmcnt(0)
	s_barrier
	ds_read_b128 v[12:15], v17 offset:0
	s_waitcnt lgkmcnt(0)
	v_add_f32_e32 v12, v12, v13
	v_add_f32_e32 v14, v14, v15
	v_add_f32_e32 v10, v12, v14
	v_fma_f32 v11, v10, s17, v3
	v_rsq_f32_e32 v11, v11
	s_nop 0
	v_mul_f32_e32 v208, v208, v11
	v_mul_f32_e32 v209, v209, v11
	v_mul_f32_e32 v210, v210, v11
	v_mul_f32_e32 v211, v211, v11
	v_fmac_f32_e32 v240, v208, v244
	v_fmac_f32_e32 v241, v209, v245
	v_fmac_f32_e32 v242, v210, v246
	v_fmac_f32_e32 v243, v211, v247
	s_lshl_b32 s18, s54, 12
	s_add_u32 s18, s18, s55
	s_add_u32 s56, s4, s18
	s_addc_u32 s57, s5, 0
	s_add_u32 s56, s56, 0x4000000
	s_addc_u32 s57, s57, 0
	global_store_dwordx4 v1, v[240:243], s[56:57]
